# all remaining wave-sum ds_swizzle exchange steps (norm phases, prep qk norm) via DPP / permlane16_swap, bit-identical
# baseline (speedup 1.0000x reference)
; template <int K> __device__ __forceinline__ float swz_xor(float v) { return __uint_as_float((unsigned)__builtin_amdgcn_ds_swizzle((int)__float_as_uint(v), (K << 10) | 0x1f)); }
; __device__ __forceinline__ float xor32_sum(float v) { const auto rr = __builtin_amdgcn_permlane32_swap(__float_as_uint(v), __float_as_uint(v), false, false); return __uint_as_float(rr[0]) + __uint_as_float(rr[1]); }
; __device__ __forceinline__ float wave_sum(float v) {
;     v += swz_xor<1>(v); v += swz_xor<2>(v); v += swz_xor<4>(v); v += swz_xor<8>(v); v += swz_xor<16>(v);
;     return xor32_sum(v);
; __device__ __forceinline__ void final_norm_phase(const Ctx& F, const float* X, const float* gw, float* out) {
;     for (int row = F.gw; row < SEQ; row += F.ngw) {
;         const f32x4* xr = (const f32x4*)(X + (size_t)row * D) + F.lane;
;         f32x4 v[4]; float ss = 0.f;
; #pragma unroll
;         for (int j = 0; j < 4; ++j) { v[j] = xr[64 * j]; ss += (v[j].x * v[j].x + v[j].y * v[j].y) + (v[j].z * v[j].z + v[j].w * v[j].w); }
;         const float rs = 1.0f / sqrtf(wave_sum(ss) * (1.f / D) + EPSN);
; #pragma unroll
;         for (int j = 0; j < 4; ++j) { const int col = 4 * F.lane + 256 * j; *(f32x4*)(out + (size_t)row * D + col) = v[j] * rs * *(const f32x4*)(gw + col); }
;     }
.LBB0_15:
	s_nop 0
	v_lshl_add_u64 v[4:5], s[44:45], 0, v[0:1]
	v_add_co_u32_e32 v12, vcc, 0xcb48000, v4
	v_add_co_u32_e64 v16, s[4:5], s89, v4
	s_nop 0
	v_addc_co_u32_e32 v13, vcc, 0, v5, vcc
	v_addc_co_u32_e64 v17, s[4:5], 0, v5, s[4:5]
	global_load_dwordx4 v[4:7], v[12:13], off offset:1024
	global_load_dwordx4 v[8:11], v[12:13], off offset:2048
	s_nop 0
	global_load_dwordx4 v[12:15], v[12:13], off offset:3072
	s_nop 0
	global_load_dwordx4 v[16:19], v[16:17], off
	s_nop 0
	global_load_dwordx4 v[20:23], v[2:3], off
	v_lshl_add_u64 v[24:25], s[46:47], 0, v[0:1]
	s_add_i32 s42, s42, s58
	s_add_u32 s44, s44, s0
	s_addc_u32 s45, s45, s1
	s_add_u32 s46, s46, s0
	s_addc_u32 s47, s47, s1
	s_cmpk_gt_i32 s42, 0x3fff
	s_waitcnt vmcnt(0)
	v_mul_f32_e32 v28, v5, v5
	v_mul_f32_e32 v29, v7, v7
	s_waitcnt vmcnt(3)
	v_mul_f32_e32 v30, v9, v9
	s_waitcnt vmcnt(1)
	v_mul_f32_e32 v26, v17, v17
	v_mul_f32_e32 v27, v19, v19
	v_mul_f32_e32 v31, v11, v11
	v_mul_f32_e32 v32, v13, v13
	v_mul_f32_e32 v33, v15, v15
	v_fmac_f32_e32 v26, v16, v16
	v_fmac_f32_e32 v27, v18, v18
	v_fmac_f32_e32 v28, v4, v4
	v_fmac_f32_e32 v29, v6, v6
	v_fmac_f32_e32 v30, v8, v8
	v_fmac_f32_e32 v31, v10, v10
	v_fmac_f32_e32 v32, v12, v12
	v_fmac_f32_e32 v33, v14, v14
	v_add_f32_e32 v26, v26, v27
	v_add_f32_e32 v27, v28, v29
	v_add_f32_e32 v28, v30, v31
	v_add_f32_e32 v29, v32, v33
	v_add_f32_e32 v27, v27, v28
	v_add_f32_e32 v27, v27, v29
	v_add_f32_e32 v26, v27, v26
	s_nop 1
	v_mov_b32_dpp v27, v26 quad_perm:[1,0,3,2] row_mask:0xf bank_mask:0xf
	s_waitcnt lgkmcnt(0)
	v_add_f32_e32 v26, v26, v27
	s_nop 1
	v_mov_b32_dpp v27, v26 quad_perm:[2,3,0,1] row_mask:0xf bank_mask:0xf
	s_waitcnt lgkmcnt(0)
	v_add_f32_e32 v26, v26, v27
	s_nop 1
	v_mov_b32_dpp v27, v26 row_half_mirror row_mask:0xf bank_mask:0xf
	s_waitcnt lgkmcnt(0)
	v_add_f32_e32 v26, v26, v27
	s_nop 1
	v_mov_b32_dpp v27, v26 row_ror:8 row_mask:0xf bank_mask:0xf
	s_waitcnt lgkmcnt(0)
	v_add_f32_e32 v26, v26, v27
	v_mov_b32_e32 v27, v26
	s_nop 1
	v_permlane16_swap_b32_e32 v26, v27
	s_waitcnt lgkmcnt(0)
	v_add_f32_e32 v26, v26, v27
	v_mov_b32_e32 v27, v26
	s_nop 1
	v_permlane32_swap_b32_e32 v26, v27
	v_add_f32_e32 v26, v26, v27
	v_fmamk_f32 v26, v26, 0x3a800000, v193
	v_mul_f32_e32 v27, 0x4f800000, v26
	v_cmp_gt_f32_e32 vcc, s41, v26
	s_nop 1
	v_cndmask_b32_e32 v26, v26, v27, vcc
	v_sqrt_f32_e32 v27, v26
	s_nop 0
	v_add_u32_e32 v28, -1, v27
	v_add_u32_e32 v29, 1, v27
	v_fma_f32 v30, -v28, v27, v26
	v_fma_f32 v31, -v29, v27, v26
	v_cmp_ge_f32_e64 s[4:5], 0, v30
	s_nop 1
	v_cndmask_b32_e64 v27, v27, v28, s[4:5]
	v_cmp_lt_f32_e64 s[4:5], 0, v31
	s_nop 1
	v_cndmask_b32_e64 v27, v27, v29, s[4:5]
	v_mul_f32_e32 v28, 0x37800000, v27
	v_cndmask_b32_e32 v27, v27, v28, vcc
	v_cmp_class_f32_e32 vcc, v26, v202
	s_nop 1
	v_cndmask_b32_e32 v26, v27, v26, vcc
	v_div_scale_f32 v27, s[2:3], v26, v26, 1.0
	v_rcp_f32_e32 v29, v27
	v_div_scale_f32 v28, vcc, 1.0, v26, 1.0
	v_fma_f32 v30, -v27, v29, 1.0
	v_fmac_f32_e32 v29, v30, v29
	v_mul_f32_e32 v30, v28, v29
	v_fma_f32 v31, -v27, v30, v28
	v_fmac_f32_e32 v30, v31, v29
	v_fma_f32 v27, -v27, v30, v28
	v_div_fmas_f32 v27, v27, v29, v30
	v_div_fixup_f32 v26, v27, v26, 1.0
	v_pk_mul_f32 v[4:5], v[4:5], v[26:27] op_sel_hi:[1,0]
	v_pk_mul_f32 v[6:7], v[6:7], v[26:27] op_sel_hi:[1,0]
	s_waitcnt vmcnt(0)
	v_pk_mul_f32 v[4:5], v[20:21], v[4:5]
	v_pk_mul_f32 v[6:7], v[22:23], v[6:7]
	global_store_dwordx4 v[24:25], v[4:7], off
	global_load_dwordx4 v[4:7], v[2:3], off offset:1024
	v_pk_mul_f32 v[10:11], v[10:11], v[26:27] op_sel_hi:[1,0]
	v_pk_mul_f32 v[8:9], v[8:9], v[26:27] op_sel_hi:[1,0]
	s_waitcnt vmcnt(0)
	v_pk_mul_f32 v[6:7], v[6:7], v[10:11]
	v_pk_mul_f32 v[4:5], v[4:5], v[8:9]
	global_store_dwordx4 v[24:25], v[4:7], off offset:1024
	global_load_dwordx4 v[4:7], v[2:3], off offset:2048
	v_pk_mul_f32 v[8:9], v[14:15], v[26:27] op_sel_hi:[1,0]
	v_pk_mul_f32 v[10:11], v[12:13], v[26:27] op_sel_hi:[1,0]
	s_waitcnt vmcnt(0)
	v_pk_mul_f32 v[6:7], v[6:7], v[8:9]
	v_pk_mul_f32 v[4:5], v[4:5], v[10:11]
	global_store_dwordx4 v[24:25], v[4:7], off offset:2048
	global_load_dwordx4 v[4:7], v[2:3], off offset:3072
	v_pk_mul_f32 v[8:9], v[18:19], v[26:27] op_sel_hi:[1,0]
	v_pk_mul_f32 v[10:11], v[16:17], v[26:27] op_sel_hi:[1,0]
	s_waitcnt vmcnt(0)
	v_pk_mul_f32 v[6:7], v[6:7], v[8:9]
	v_pk_mul_f32 v[4:5], v[4:5], v[10:11]
	global_store_dwordx4 v[24:25], v[4:7], off offset:3072
	s_cbranch_scc0 .LBB0_15

; __device__ __forceinline__ void norm_phase(const Ctx& F, float* X, const float* gw, const float* modl, int ish, int isc, bf16_t* XN, const float* part, int nsplit) {
;     for (int row = SEQ + F.gw; row < NTOK; row += F.ngw) {
;         const float* mv = modl + NMODV;
;         f32x4* xr = (f32x4*)(X + (size_t)row * D) + F.lane;
;         f32x4 v[4];
; #pragma unroll
;         for (int j = 0; j < 4; ++j) v[j] = xr[64 * j];
;         const f32x4* pr = (const f32x4*)(part + (size_t)(row - SEQ) * D) + F.lane;
;         int s = 0;
;         for (; s + 4 <= nsplit; s += 4) {
;             f32x4 t[4][4];
; #pragma unroll
;             for (int u = 0; u < 4; ++u)
; #pragma unroll
;                 for (int j = 0; j < 4; ++j) t[u][j] = pr[(size_t)(s + u) * (256 * D / 4) + 64 * j];
; #pragma unroll
;             for (int u = 0; u < 4; ++u)
; #pragma unroll
;                 for (int j = 0; j < 4; ++j) v[j] += t[u][j];
;         }
;         for (; s < nsplit; ++s)
; #pragma unroll
;             for (int j = 0; j < 4; ++j) v[j] += pr[(size_t)s * (256 * D / 4) + 64 * j];
.LBB0_82:
	v_lshl_add_u64 v[46:47], s[14:15], 0, v[42:43]
	v_add_co_u32_e32 v44, vcc, 0xcb48000, v46
	v_lshl_add_u64 v[118:119], s[14:15], 0, v[38:39]
	s_nop 0
	v_addc_co_u32_e32 v45, vcc, 0, v47, vcc
	v_add_co_u32_e32 v46, vcc, 0xcb49000, v46
	global_load_dwordx4 v[2:5], v[44:45], off offset:1024
	global_load_dwordx4 v[6:9], v[44:45], off offset:2048
	global_load_dwordx4 v[10:13], v[44:45], off offset:3072
	v_addc_co_u32_e32 v47, vcc, 0, v47, vcc
	v_add_co_u32_e32 v60, vcc, 0x2355a000, v118
	global_load_dwordx4 v[48:51], v[46:47], off
	s_nop 0
	v_addc_co_u32_e32 v61, vcc, 0, v119, vcc
	v_add_co_u32_e32 v64, vcc, 0x2355b000, v118
	global_load_dwordx4 v[52:55], v[60:61], off offset:1024
	global_load_dwordx4 v[56:59], v[60:61], off offset:2048
	s_nop 0
	global_load_dwordx4 v[60:63], v[60:61], off offset:3072
	v_addc_co_u32_e32 v65, vcc, 0, v119, vcc
	v_add_co_u32_e32 v78, vcc, 0x2365a000, v118
	global_load_dwordx4 v[64:67], v[64:65], off
	s_nop 0
	v_addc_co_u32_e32 v79, vcc, 0, v119, vcc
	s_waitcnt vmcnt(0)
	v_add_co_u32_e32 v82, vcc, 0x2365b000, v118
	global_load_dwordx4 v[70:73], v[78:79], off offset:1024
	global_load_dwordx4 v[74:77], v[78:79], off offset:2048
	s_nop 0
	global_load_dwordx4 v[78:81], v[78:79], off offset:3072
	v_addc_co_u32_e32 v83, vcc, 0, v119, vcc
	v_add_co_u32_e32 v94, vcc, 0x2375a000, v118
	global_load_dwordx4 v[82:85], v[82:83], off
	s_nop 0
	v_addc_co_u32_e32 v95, vcc, 0, v119, vcc
	v_add_co_u32_e32 v98, vcc, 0x2375b000, v118
	global_load_dwordx4 v[86:89], v[94:95], off offset:1024
	global_load_dwordx4 v[90:93], v[94:95], off offset:2048
	s_nop 0
	global_load_dwordx4 v[94:97], v[94:95], off offset:3072
	v_addc_co_u32_e32 v99, vcc, 0, v119, vcc
	v_add_co_u32_e32 v110, vcc, 0x2385a000, v118
	global_load_dwordx4 v[98:101], v[98:99], off
	s_nop 0
	v_addc_co_u32_e32 v111, vcc, 0, v119, vcc
	global_load_dwordx4 v[102:105], v[110:111], off offset:1024
	global_load_dwordx4 v[106:109], v[110:111], off offset:2048
	s_nop 0
	global_load_dwordx4 v[110:113], v[110:111], off offset:3072
	v_add_co_u32_e32 v114, vcc, 0x2385b000, v118
	s_mov_b32 s2, 0x2395a000
	s_nop 0
	v_addc_co_u32_e32 v115, vcc, 0, v119, vcc
	global_load_dwordx4 v[114:117], v[114:115], off
	s_add_i32 s42, s42, s58
	v_lshl_add_u64 v[38:39], v[38:39], 0, s[0:1]
	v_lshl_add_u64 v[42:43], v[42:43], 0, s[0:1]
	s_cmpk_gt_i32 s42, 0x40ff
	s_waitcnt vmcnt(15)
	v_pk_add_f32 v[4:5], v[4:5], v[54:55]
	v_pk_add_f32 v[2:3], v[2:3], v[52:53]
	s_waitcnt vmcnt(13)
	v_pk_add_f32 v[10:11], v[10:11], v[60:61]
	v_pk_add_f32 v[8:9], v[8:9], v[58:59]
	v_pk_add_f32 v[6:7], v[6:7], v[56:57]
	v_pk_add_f32 v[12:13], v[12:13], v[62:63]
	s_waitcnt vmcnt(12)
	v_pk_add_f32 v[48:49], v[48:49], v[64:65]
	v_pk_add_f32 v[50:51], v[50:51], v[66:67]
	s_waitcnt vmcnt(11)
	v_pk_add_f32 v[4:5], v[4:5], v[72:73]
	v_pk_add_f32 v[2:3], v[2:3], v[70:71]
	s_waitcnt vmcnt(9)
	v_pk_add_f32 v[10:11], v[10:11], v[78:79]
	v_pk_add_f32 v[8:9], v[8:9], v[76:77]
	v_pk_add_f32 v[6:7], v[6:7], v[74:75]
	v_pk_add_f32 v[12:13], v[12:13], v[80:81]
	s_waitcnt vmcnt(8)
	v_pk_add_f32 v[48:49], v[48:49], v[82:83]
	v_pk_add_f32 v[50:51], v[50:51], v[84:85]
	s_waitcnt vmcnt(7)
	v_pk_add_f32 v[4:5], v[4:5], v[88:89]
	v_pk_add_f32 v[2:3], v[2:3], v[86:87]
	s_waitcnt vmcnt(5)
	v_pk_add_f32 v[10:11], v[10:11], v[94:95]
	v_pk_add_f32 v[8:9], v[8:9], v[92:93]
	v_pk_add_f32 v[6:7], v[6:7], v[90:91]
	v_pk_add_f32 v[12:13], v[12:13], v[96:97]
	s_waitcnt vmcnt(4)
	v_pk_add_f32 v[48:49], v[48:49], v[98:99]
	v_pk_add_f32 v[50:51], v[50:51], v[100:101]
	s_waitcnt vmcnt(3)
	v_pk_add_f32 v[104:105], v[4:5], v[104:105]
	s_waitcnt vmcnt(1)
	v_pk_add_f32 v[110:111], v[10:11], v[110:111]
	v_add_co_u32_e32 v10, vcc, s2, v118
	s_mov_b32 s2, 0x23a5a000
	s_nop 0
	v_addc_co_u32_e32 v11, vcc, 0, v119, vcc
	s_waitcnt vmcnt(0)
	v_pk_add_f32 v[114:115], v[48:49], v[114:115]
	v_add_co_u32_e32 v48, vcc, s5, v118
	v_pk_add_f32 v[102:103], v[2:3], v[102:103]
	s_nop 0
	v_addc_co_u32_e32 v49, vcc, 0, v119, vcc
	v_add_co_u32_e32 v60, vcc, s2, v118
	s_mov_b32 s2, 0x23b5a000
	s_nop 0
	v_addc_co_u32_e32 v61, vcc, 0, v119, vcc
	v_add_co_u32_e32 v64, vcc, s20, v118
	v_pk_add_f32 v[108:109], v[8:9], v[108:109]
	s_nop 0
	v_addc_co_u32_e32 v65, vcc, 0, v119, vcc
	v_add_co_u32_e32 v78, vcc, s2, v118
	s_mov_b32 s2, 0x23c5a000
	s_nop 0
	v_addc_co_u32_e32 v79, vcc, 0, v119, vcc
	v_add_co_u32_e32 v82, vcc, s57, v118
	v_pk_add_f32 v[106:107], v[6:7], v[106:107]
	s_nop 0
	v_addc_co_u32_e32 v83, vcc, 0, v119, vcc
	v_add_co_u32_e32 v94, vcc, s2, v118
	v_pk_add_f32 v[112:113], v[12:13], v[112:113]
	v_pk_add_f32 v[116:117], v[50:51], v[116:117]
	global_load_dwordx4 v[2:5], v[10:11], off offset:1024
	global_load_dwordx4 v[6:9], v[10:11], off offset:2048
	s_nop 0
	global_load_dwordx4 v[10:13], v[10:11], off offset:3072
	v_addc_co_u32_e32 v95, vcc, 0, v119, vcc
	global_load_dwordx4 v[48:51], v[48:49], off
	s_nop 0
	global_load_dwordx4 v[52:55], v[60:61], off offset:1024
	global_load_dwordx4 v[56:59], v[60:61], off offset:2048
	s_nop 0
	global_load_dwordx4 v[60:63], v[60:61], off offset:3072
	v_add_co_u32_e32 v98, vcc, s91, v118
	global_load_dwordx4 v[64:67], v[64:65], off
	s_nop 0
	global_load_dwordx4 v[70:73], v[78:79], off offset:1024
	global_load_dwordx4 v[74:77], v[78:79], off offset:2048
	s_nop 0
	global_load_dwordx4 v[78:81], v[78:79], off offset:3072
	v_addc_co_u32_e32 v99, vcc, 0, v119, vcc
	global_load_dwordx4 v[82:85], v[82:83], off
	s_nop 0
	global_load_dwordx4 v[86:89], v[94:95], off offset:1024
	global_load_dwordx4 v[90:93], v[94:95], off offset:2048
	s_nop 0
	global_load_dwordx4 v[94:97], v[94:95], off offset:3072
	s_waitcnt vmcnt(14)
; __device__ __forceinline__ unsigned pk2(float lo, float hi) { const f32x2_t v = {lo, hi}; const bf16x2_t b = __builtin_convertvector(v, bf16x2_t); return __builtin_bit_cast(unsigned, b); }
; template <int K> __device__ __forceinline__ float swz_xor(float v) { return __uint_as_float((unsigned)__builtin_amdgcn_ds_swizzle((int)__float_as_uint(v), (K << 10) | 0x1f)); }
; __device__ __forceinline__ float xor32_sum(float v) { const auto rr = __builtin_amdgcn_permlane32_swap(__float_as_uint(v), __float_as_uint(v), false, false); return __uint_as_float(rr[0]) + __uint_as_float(rr[1]); }
; __device__ __forceinline__ float wave_sum(float v) {
;     v += swz_xor<1>(v); v += swz_xor<2>(v); v += swz_xor<4>(v); v += swz_xor<8>(v); v += swz_xor<16>(v);
;     return xor32_sum(v);
; __device__ __forceinline__ void norm_phase(const Ctx& F, float* X, const float* gw, const float* modl, int ish, int isc, bf16_t* XN, const float* part, int nsplit) {
;     ...
;                 for (int j = 0; j < 4; ++j) v[j] += t[u][j];
;         }
;         for (; s < nsplit; ++s)
; #pragma unroll
;             for (int j = 0; j < 4; ++j) v[j] += pr[(size_t)s * (256 * D / 4) + 64 * j];
;         if (nsplit > 0) {
; #pragma unroll
;             for (int j = 0; j < 4; ++j) xr[64 * j] = v[j];
;         }
;         float ss = 0.f;
; #pragma unroll
;         for (int j = 0; j < 4; ++j) ss += (v[j].x * v[j].x + v[j].y * v[j].y) + (v[j].z * v[j].z + v[j].w * v[j].w);
;         const float rs = __builtin_amdgcn_rsqf(wave_sum(ss) * (1.f / D) + EPSN);
; #pragma unroll
;         for (int j = 0; j < 4; ++j) {
;             const int col = 4 * F.lane + 256 * j;
;             const f32x4 g4 = *(const f32x4*)(gw + col), sh = *(const f32x4*)(mv + ish * 1024 + col), sc = *(const f32x4*)(mv + isc * 1024 + col);
;             const f32x4 o = (v[j] * rs) * (g4 * (sc + 1.0f)) + sh;
;             u32x2 w; w.x = pk2(o.x, o.y); w.y = pk2(o.z, o.w);
;             *(u32x2*)(XN + (size_t)row * D + col) = w;
;         }
	v_pk_add_f32 v[4:5], v[104:105], v[4:5]
	global_load_dwordx4 v[98:101], v[98:99], off
	v_pk_add_f32 v[2:3], v[102:103], v[2:3]
	s_waitcnt vmcnt(14)
	v_pk_add_f32 v[8:9], v[108:109], v[8:9]
	v_pk_add_f32 v[6:7], v[106:107], v[6:7]
	s_waitcnt vmcnt(13)
	v_pk_add_f32 v[12:13], v[112:113], v[12:13]
	v_pk_add_f32 v[10:11], v[110:111], v[10:11]
	s_waitcnt vmcnt(12)
	v_pk_add_f32 v[50:51], v[116:117], v[50:51]
	v_pk_add_f32 v[48:49], v[114:115], v[48:49]
	s_waitcnt vmcnt(11)
	v_pk_add_f32 v[4:5], v[4:5], v[54:55]
	v_pk_add_f32 v[2:3], v[2:3], v[52:53]
	s_waitcnt vmcnt(10)
	v_pk_add_f32 v[8:9], v[8:9], v[58:59]
	v_pk_add_f32 v[6:7], v[6:7], v[56:57]
	s_waitcnt vmcnt(9)
	v_pk_add_f32 v[12:13], v[12:13], v[62:63]
	v_pk_add_f32 v[10:11], v[10:11], v[60:61]
	s_waitcnt vmcnt(8)
	v_pk_add_f32 v[50:51], v[50:51], v[66:67]
	v_pk_add_f32 v[48:49], v[48:49], v[64:65]
	s_waitcnt vmcnt(7)
	v_pk_add_f32 v[4:5], v[4:5], v[72:73]
	v_pk_add_f32 v[2:3], v[2:3], v[70:71]
	s_waitcnt vmcnt(6)
	v_pk_add_f32 v[8:9], v[8:9], v[76:77]
	v_pk_add_f32 v[6:7], v[6:7], v[74:75]
	s_waitcnt vmcnt(5)
	v_pk_add_f32 v[52:53], v[12:13], v[80:81]
	v_pk_add_f32 v[54:55], v[10:11], v[78:79]
	s_waitcnt vmcnt(4)
	v_pk_add_f32 v[56:57], v[50:51], v[84:85]
	v_pk_add_f32 v[58:59], v[48:49], v[82:83]
	s_waitcnt vmcnt(3)
	v_pk_add_f32 v[50:51], v[4:5], v[88:89]
	v_pk_add_f32 v[48:49], v[2:3], v[86:87]
	s_waitcnt vmcnt(2)
	v_pk_add_f32 v[12:13], v[8:9], v[92:93]
	v_pk_add_f32 v[10:11], v[6:7], v[90:91]
	s_waitcnt vmcnt(1)
	v_pk_add_f32 v[8:9], v[52:53], v[96:97]
	v_pk_add_f32 v[6:7], v[54:55], v[94:95]
	v_mul_f32_e32 v15, v49, v49
	v_mul_f32_e32 v17, v51, v51
	v_fmac_f32_e32 v15, v48, v48
	v_fmac_f32_e32 v17, v50, v50
	v_add_f32_e32 v15, v15, v17
	v_mul_f32_e32 v17, v11, v11
	v_mul_f32_e32 v19, v13, v13
	v_fmac_f32_e32 v17, v10, v10
	v_fmac_f32_e32 v19, v12, v12
	v_add_f32_e32 v17, v17, v19
	v_add_f32_e32 v15, v15, v17
	v_mul_f32_e32 v17, v7, v7
	v_mul_f32_e32 v19, v9, v9
	v_fmac_f32_e32 v17, v6, v6
	v_fmac_f32_e32 v19, v8, v8
	v_add_f32_e32 v17, v17, v19
	v_add_f32_e32 v15, v15, v17
	s_waitcnt vmcnt(0)
	v_pk_add_f32 v[4:5], v[56:57], v[100:101]
	v_pk_add_f32 v[2:3], v[58:59], v[98:99]
	global_store_dwordx4 v[44:45], v[48:51], off offset:1024
	global_store_dwordx4 v[44:45], v[10:13], off offset:2048
	global_store_dwordx4 v[44:45], v[6:9], off offset:3072
	global_store_dwordx4 v[46:47], v[2:5], off
	global_load_dwordx4 v[52:55], v[20:21], off
	global_load_dwordx4 v[56:59], v[22:23], off
	global_load_dwordx4 v[60:63], v[24:25], off
	v_mul_f32_e32 v17, v3, v3
	v_mul_f32_e32 v19, v5, v5
	v_fmac_f32_e32 v17, v2, v2
	v_fmac_f32_e32 v19, v4, v4
	v_add_f32_e32 v17, v17, v19
	v_add_f32_e32 v15, v15, v17
	s_nop 1
	v_mov_b32_dpp v17, v15 quad_perm:[1,0,3,2] row_mask:0xf bank_mask:0xf
	s_waitcnt lgkmcnt(0)
	v_add_f32_e32 v15, v15, v17
	s_nop 1
	v_mov_b32_dpp v17, v15 quad_perm:[2,3,0,1] row_mask:0xf bank_mask:0xf
	s_waitcnt lgkmcnt(0)
	v_add_f32_e32 v15, v15, v17
	s_nop 1
	v_mov_b32_dpp v17, v15 row_half_mirror row_mask:0xf bank_mask:0xf
	s_waitcnt lgkmcnt(0)
	v_add_f32_e32 v15, v15, v17
	s_nop 1
	v_mov_b32_dpp v17, v15 row_ror:8 row_mask:0xf bank_mask:0xf
	s_waitcnt lgkmcnt(0)
	v_add_f32_e32 v15, v15, v17
	v_mov_b32_e32 v17, v15
	s_nop 1
	v_permlane16_swap_b32_e32 v15, v17
	s_waitcnt lgkmcnt(0)
	v_add_f32_e32 v15, v15, v17
	v_mov_b32_e32 v17, v15
	s_nop 1
	v_permlane32_swap_b32_e32 v15, v17
	v_add_f32_e32 v15, v15, v17
	v_fmamk_f32 v15, v15, 0x3a800000, v193
	v_rsq_f32_e32 v44, v15
	s_waitcnt vmcnt(0)
	v_pk_add_f32 v[60:61], v[60:61], 1.0 op_sel_hi:[1,0]
	v_pk_mul_f32 v[46:47], v[48:49], v[44:45] op_sel_hi:[1,0]
	v_pk_mul_f32 v[48:49], v[50:51], v[44:45] op_sel_hi:[1,0]
	v_pk_add_f32 v[50:51], v[62:63], 1.0 op_sel_hi:[1,0]
	v_pk_mul_f32 v[52:53], v[52:53], v[60:61]
	v_pk_mul_f32 v[50:51], v[54:55], v[50:51]
	v_pk_fma_f32 v[46:47], v[52:53], v[46:47], v[56:57]
	v_pk_fma_f32 v[48:49], v[50:51], v[48:49], v[58:59]
	v_cvt_pk_bf16_f32 v46, v46, v47
	v_cvt_pk_bf16_f32 v47, v48, v49
	v_lshl_add_u64 v[48:49], s[14:15], 0, v[40:41]
	v_add_co_u32_e32 v48, vcc, s74, v48
	v_pk_mul_f32 v[10:11], v[10:11], v[44:45] op_sel_hi:[1,0]
	s_nop 0
	v_addc_co_u32_e32 v49, vcc, 0, v49, vcc
	global_store_dwordx2 v[48:49], v[46:47], off offset:1024
	global_load_dwordx4 v[50:53], v[20:21], off offset:1024
	global_load_dwordx4 v[54:57], v[26:27], off
	global_load_dwordx4 v[58:61], v[28:29], off
	v_pk_mul_f32 v[12:13], v[12:13], v[44:45] op_sel_hi:[1,0]
	v_pk_mul_f32 v[6:7], v[6:7], v[44:45] op_sel_hi:[1,0]
	v_pk_mul_f32 v[8:9], v[8:9], v[44:45] op_sel_hi:[1,0]
	v_pk_mul_f32 v[2:3], v[2:3], v[44:45] op_sel_hi:[1,0]
	v_pk_mul_f32 v[4:5], v[4:5], v[44:45] op_sel_hi:[1,0]
	v_lshl_add_u64 v[40:41], v[40:41], 0, s[54:55]
	s_waitcnt vmcnt(0)
	v_pk_add_f32 v[46:47], v[60:61], 1.0 op_sel_hi:[1,0]
	v_pk_add_f32 v[58:59], v[58:59], 1.0 op_sel_hi:[1,0]
	v_pk_mul_f32 v[46:47], v[52:53], v[46:47]
	v_pk_mul_f32 v[50:51], v[50:51], v[58:59]
	v_pk_fma_f32 v[12:13], v[12:13], v[46:47], v[56:57]
	v_pk_fma_f32 v[10:11], v[10:11], v[50:51], v[54:55]
	s_nop 0
	v_cvt_pk_bf16_f32 v10, v10, v11
	v_cvt_pk_bf16_f32 v11, v12, v13
	global_store_dwordx2 v[48:49], v[10:11], off offset:1536
	global_load_dwordx4 v[10:13], v[20:21], off offset:2048
	s_nop 0
	global_load_dwordx4 v[50:53], v[30:31], off
	global_load_dwordx4 v[54:57], v[32:33], off
	s_waitcnt vmcnt(0)
	v_pk_add_f32 v[46:47], v[56:57], 1.0 op_sel_hi:[1,0]
	v_pk_add_f32 v[54:55], v[54:55], 1.0 op_sel_hi:[1,0]
	v_pk_mul_f32 v[12:13], v[12:13], v[46:47]
	v_pk_mul_f32 v[10:11], v[10:11], v[54:55]
	v_pk_fma_f32 v[8:9], v[8:9], v[12:13], v[52:53]
	v_pk_fma_f32 v[6:7], v[6:7], v[10:11], v[50:51]
	s_nop 0
	v_cvt_pk_bf16_f32 v6, v6, v7
	v_cvt_pk_bf16_f32 v7, v8, v9
	global_store_dwordx2 v[48:49], v[6:7], off offset:2048
	global_load_dwordx4 v[6:9], v[20:21], off offset:3072
	s_nop 0
	global_load_dwordx4 v[10:13], v[34:35], off
	global_load_dwordx4 v[50:53], v[36:37], off
	s_waitcnt vmcnt(0)
	v_pk_add_f32 v[44:45], v[52:53], 1.0 op_sel_hi:[1,0]
	v_pk_add_f32 v[46:47], v[50:51], 1.0 op_sel_hi:[1,0]
	v_pk_mul_f32 v[8:9], v[8:9], v[44:45]
	v_pk_mul_f32 v[6:7], v[6:7], v[46:47]
	v_pk_fma_f32 v[4:5], v[4:5], v[8:9], v[12:13]
	v_pk_fma_f32 v[2:3], v[2:3], v[6:7], v[10:11]
	s_nop 0
	v_cvt_pk_bf16_f32 v2, v2, v3
	v_cvt_pk_bf16_f32 v3, v4, v5
	global_store_dwordx2 v[48:49], v[2:3], off offset:2560
	s_cbranch_scc0 .LBB0_82

; __device__ __forceinline__ void norm_phase(const Ctx& F, float* X, const float* gw, const float* modl, int ish, int isc, bf16_t* XN, const float* part, int nsplit) {
;     ...
;     for (int row0 = 4 * F.gw; row0 < SEQ; row0 += 4 * F.ngw) {
;         const float* mv = modl;
;         f32x4 v[4][4];
; #pragma unroll
;         for (int r = 0; r < 4; ++r) { const f32x4* xr = (const f32x4*)(X + (size_t)(row0 + r) * D) + F.lane;
; #pragma unroll
;             for (int j = 0; j < 4; ++j) v[r][j] = xr[64 * j]; }
;         float rs[4];
; #pragma unroll
;         for (int r = 0; r < 4; ++r) { float ss = 0.f;
; #pragma unroll
;             for (int j = 0; j < 4; ++j) ss += (v[r][j].x * v[r][j].x + v[r][j].y * v[r][j].y) + (v[r][j].z * v[r][j].z + v[r][j].w * v[r][j].w);
;             rs[r] = __builtin_amdgcn_rsqf(wave_sum(ss) * (1.f / D) + EPSN); }
.LBB0_85:
	v_lshl_add_u64 v[76:77], s[14:15], 0, v[68:69]
	v_add_co_u32_e64 v72, s[4:5], s74, v76
	v_lshl_add_u64 v[14:15], s[14:15], 0, v[70:71]
	s_nop 0
	v_addc_co_u32_e64 v73, s[4:5], 0, v77, s[4:5]
	v_add_co_u32_e64 v74, s[4:5], s56, v76
	v_add_co_u32_e32 v2, vcc, 0xcb48000, v14
	s_nop 0
	v_addc_co_u32_e64 v75, s[4:5], 0, v77, s[4:5]
	s_mov_b64 s[4:5], vcc
	v_add_co_u32_e32 v6, vcc, 0xcb49000, v14
	v_addc_co_u32_e64 v3, s[4:5], 0, v15, s[4:5]
	s_mov_b64 s[4:5], vcc
	global_load_dwordx4 v[78:81], v[50:51], off
	global_load_dwordx4 v[34:37], v[52:53], off
	global_load_dwordx4 v[82:85], v[54:55], off
	v_add_co_u32_e32 v10, vcc, 0xcb4a000, v14
	v_addc_co_u32_e64 v7, s[4:5], 0, v15, s[4:5]
	global_load_dwordx4 v[86:89], v[2:3], off offset:1024
	global_load_dwordx4 v[38:41], v[2:3], off offset:2048
	global_load_dwordx4 v[18:21], v[2:3], off offset:3072
	s_mov_b64 s[4:5], vcc
	global_load_dwordx4 v[2:5], v[6:7], off
	global_load_dwordx4 v[90:93], v[6:7], off offset:1024
	global_load_dwordx4 v[42:45], v[6:7], off offset:2048
	global_load_dwordx4 v[22:25], v[6:7], off offset:3072
	v_add_co_u32_e32 v16, vcc, 0xcb4b000, v14
	v_addc_co_u32_e64 v11, s[4:5], 0, v15, s[4:5]
	s_mov_b64 s[4:5], vcc
	global_load_dwordx4 v[6:9], v[10:11], off
	global_load_dwordx4 v[94:97], v[10:11], off offset:1024
	global_load_dwordx4 v[98:101], v[10:11], off offset:2048
	global_load_dwordx4 v[30:33], v[10:11], off offset:3072
	v_add_co_u32_e32 v14, vcc, 0xcb4c000, v14
	v_addc_co_u32_e64 v17, s[4:5], 0, v15, s[4:5]
	global_load_dwordx4 v[10:13], v[16:17], off
	global_load_dwordx4 v[102:105], v[16:17], off offset:1024
	global_load_dwordx4 v[46:49], v[16:17], off offset:2048
	global_load_dwordx4 v[26:29], v[16:17], off offset:3072
	v_addc_co_u32_e32 v15, vcc, 0, v15, vcc
	global_load_dwordx4 v[14:17], v[14:15], off
	s_add_i32 s42, s42, s88
	v_lshl_add_u64 v[68:69], v[68:69], 0, s[26:27]
	v_lshl_add_u64 v[70:71], v[70:71], 0, s[64:65]
	s_cmpk_gt_i32 s42, 0x3fff
	s_waitcnt vmcnt(0)
	v_pk_add_f32 v[84:85], v[84:85], 1.0 op_sel_hi:[1,0]
	v_pk_add_f32 v[82:83], v[82:83], 1.0 op_sel_hi:[1,0]
	v_pk_mul_f32 v[84:85], v[80:81], v[84:85]
	v_pk_mul_f32 v[106:107], v[78:79], v[82:83]
	s_waitcnt vmcnt(15)
	v_mul_f32_e32 v0, v87, v87
	v_mul_f32_e32 v78, v89, v89
	s_waitcnt vmcnt(14)
	v_mul_f32_e32 v79, v39, v39
	v_mul_f32_e32 v80, v41, v41
	s_waitcnt vmcnt(13)
	v_mul_f32_e32 v81, v19, v19
	v_mul_f32_e32 v82, v21, v21
	v_fmac_f32_e32 v0, v86, v86
	v_fmac_f32_e32 v78, v88, v88
	v_fmac_f32_e32 v79, v38, v38
	v_fmac_f32_e32 v80, v40, v40
	v_fmac_f32_e32 v81, v18, v18
	v_fmac_f32_e32 v82, v20, v20
	s_waitcnt vmcnt(12)
	v_mul_f32_e32 v83, v3, v3
	v_mul_f32_e32 v108, v5, v5
	s_waitcnt vmcnt(11)
	v_mul_f32_e32 v109, v91, v91
	v_mul_f32_e32 v110, v93, v93
	s_waitcnt vmcnt(10)
	v_mul_f32_e32 v111, v43, v43
	v_mul_f32_e32 v112, v45, v45
	s_waitcnt vmcnt(9)
	v_mul_f32_e32 v113, v23, v23
	v_mul_f32_e32 v114, v25, v25
	v_add_f32_e32 v0, v0, v78
	v_add_f32_e32 v78, v79, v80
	v_add_f32_e32 v79, v81, v82
	v_fmac_f32_e32 v83, v2, v2
	v_fmac_f32_e32 v108, v4, v4
	v_fmac_f32_e32 v109, v90, v90
	v_fmac_f32_e32 v110, v92, v92
	v_fmac_f32_e32 v111, v42, v42
	v_fmac_f32_e32 v112, v44, v44
	v_fmac_f32_e32 v113, v22, v22
	v_fmac_f32_e32 v114, v24, v24
	s_waitcnt vmcnt(8)
	v_mul_f32_e32 v80, v7, v7
	v_mul_f32_e32 v81, v9, v9
	s_waitcnt vmcnt(7)
	v_mul_f32_e32 v82, v95, v95
	v_mul_f32_e32 v115, v97, v97
	s_waitcnt vmcnt(6)
	v_mul_f32_e32 v116, v99, v99
	v_mul_f32_e32 v117, v101, v101
	s_waitcnt vmcnt(5)
	v_mul_f32_e32 v118, v31, v31
	v_mul_f32_e32 v119, v33, v33
	v_add_f32_e32 v0, v0, v78
	v_add_f32_e32 v78, v83, v108
	v_add_f32_e32 v83, v109, v110
	v_add_f32_e32 v108, v111, v112
	v_add_f32_e32 v109, v113, v114
	v_fmac_f32_e32 v80, v6, v6
	v_fmac_f32_e32 v81, v8, v8
	v_fmac_f32_e32 v82, v94, v94
	v_fmac_f32_e32 v115, v96, v96
	v_fmac_f32_e32 v116, v98, v98
	v_fmac_f32_e32 v117, v100, v100
	s_waitcnt vmcnt(3)
	v_mul_f32_e32 v112, v103, v103
	v_mul_f32_e32 v113, v105, v105
	s_waitcnt vmcnt(2)
	v_mul_f32_e32 v114, v47, v47
	v_mul_f32_e32 v120, v49, v49
	v_fmac_f32_e32 v118, v30, v30
	v_fmac_f32_e32 v119, v32, v32
	v_mul_f32_e32 v110, v11, v11
	v_mul_f32_e32 v111, v13, v13
	s_waitcnt vmcnt(1)
	v_mul_f32_e32 v121, v27, v27
	v_mul_f32_e32 v122, v29, v29
	v_add_f32_e32 v0, v0, v79
	v_add_f32_e32 v79, v83, v108
	v_add_f32_e32 v80, v80, v81
	v_add_f32_e32 v81, v82, v115
	v_add_f32_e32 v82, v116, v117
	v_fmac_f32_e32 v112, v102, v102
	v_fmac_f32_e32 v113, v104, v104
	v_fmac_f32_e32 v114, v46, v46
	v_fmac_f32_e32 v120, v48, v48
	v_add_f32_e32 v83, v118, v119
	v_fmac_f32_e32 v110, v10, v10
	v_fmac_f32_e32 v111, v12, v12
	v_fmac_f32_e32 v121, v26, v26
	v_fmac_f32_e32 v122, v28, v28
	s_waitcnt vmcnt(0)
	v_mul_f32_e32 v108, v15, v15
	v_mul_f32_e32 v115, v17, v17
	v_add_f32_e32 v0, v0, v78
	v_add_f32_e32 v78, v79, v109
	v_add_f32_e32 v79, v81, v82
	v_add_f32_e32 v82, v112, v113
	v_add_f32_e32 v109, v114, v120
	v_add_f32_e32 v81, v110, v111
	v_add_f32_e32 v110, v121, v122
	v_fmac_f32_e32 v108, v14, v14
	v_fmac_f32_e32 v115, v16, v16
	s_nop 1
	v_mov_b32_dpp v111, v0 quad_perm:[1,0,3,2] row_mask:0xf bank_mask:0xf
	v_add_f32_e32 v78, v78, v80
	v_add_f32_e32 v79, v79, v83
	v_add_f32_e32 v80, v82, v109
	v_add_f32_e32 v82, v108, v115
	s_nop 1
	v_mov_b32_dpp v83, v78 quad_perm:[1,0,3,2] row_mask:0xf bank_mask:0xf
	v_add_f32_e32 v79, v79, v81
	v_add_f32_e32 v80, v80, v110
	s_nop 1
	v_mov_b32_dpp v81, v79 quad_perm:[1,0,3,2] row_mask:0xf bank_mask:0xf
	v_add_f32_e32 v80, v80, v82
	s_nop 1
	v_mov_b32_dpp v82, v80 quad_perm:[1,0,3,2] row_mask:0xf bank_mask:0xf
	s_waitcnt lgkmcnt(3)
; __device__ __forceinline__ unsigned pk2(float lo, float hi) { const f32x2_t v = {lo, hi}; const bf16x2_t b = __builtin_convertvector(v, bf16x2_t); return __builtin_bit_cast(unsigned, b); }
; __device__ __forceinline__ void norm_phase(const Ctx& F, float* X, const float* gw, const float* modl, int ish, int isc, bf16_t* XN, const float* part, int nsplit) {
;     ...
;         for (int r = 0; r < 4; ++r) { float ss = 0.f;
; #pragma unroll
;             for (int j = 0; j < 4; ++j) ss += (v[r][j].x * v[r][j].x + v[r][j].y * v[r][j].y) + (v[r][j].z * v[r][j].z + v[r][j].w * v[r][j].w);
;             rs[r] = __builtin_amdgcn_rsqf(wave_sum(ss) * (1.f / D) + EPSN); }
; #pragma unroll
;         for (int j = 0; j < 4; ++j) {
;             const int col = 4 * F.lane + 256 * j;
;             const f32x4 g4 = *(const f32x4*)(gw + col), sh = *(const f32x4*)(mv + ish * 1024 + col), sc = *(const f32x4*)(mv + isc * 1024 + col);
;             const f32x4 gs = g4 * (sc + 1.0f);
; #pragma unroll
;             for (int r = 0; r < 4; ++r) {
;                 const f32x4 o = (v[r][j] * rs[r]) * gs + sh;
;                 u32x2 w; w.x = pk2(o.x, o.y); w.y = pk2(o.z, o.w);
;                 *(u32x2*)(XN + (size_t)(row0 + r) * D + col) = w;
	v_add_f32_e32 v0, v0, v111
	s_nop 1
	v_mov_b32_dpp v108, v0 quad_perm:[2,3,0,1] row_mask:0xf bank_mask:0xf
	s_waitcnt lgkmcnt(3)
	v_add_f32_e32 v78, v78, v83
	s_nop 1
	v_mov_b32_dpp v83, v78 quad_perm:[2,3,0,1] row_mask:0xf bank_mask:0xf
	s_waitcnt lgkmcnt(3)
	v_add_f32_e32 v79, v79, v81
	s_nop 1
	v_mov_b32_dpp v81, v79 quad_perm:[2,3,0,1] row_mask:0xf bank_mask:0xf
	s_waitcnt lgkmcnt(3)
	v_add_f32_e32 v80, v80, v82
	s_nop 1
	v_mov_b32_dpp v82, v80 quad_perm:[2,3,0,1] row_mask:0xf bank_mask:0xf
	s_waitcnt lgkmcnt(3)
	v_add_f32_e32 v0, v0, v108
	s_nop 1
	v_mov_b32_dpp v108, v0 row_half_mirror row_mask:0xf bank_mask:0xf
	s_waitcnt lgkmcnt(3)
	v_add_f32_e32 v78, v78, v83
	s_nop 1
	v_mov_b32_dpp v83, v78 row_half_mirror row_mask:0xf bank_mask:0xf
	s_waitcnt lgkmcnt(3)
	v_add_f32_e32 v79, v79, v81
	s_nop 1
	v_mov_b32_dpp v81, v79 row_half_mirror row_mask:0xf bank_mask:0xf
	s_waitcnt lgkmcnt(3)
	v_add_f32_e32 v80, v80, v82
	s_nop 1
	v_mov_b32_dpp v82, v80 row_half_mirror row_mask:0xf bank_mask:0xf
	s_waitcnt lgkmcnt(3)
	v_add_f32_e32 v0, v0, v108
	s_nop 1
	v_mov_b32_dpp v108, v0 row_ror:8 row_mask:0xf bank_mask:0xf
	s_waitcnt lgkmcnt(3)
	v_add_f32_e32 v78, v78, v83
	s_nop 1
	v_mov_b32_dpp v83, v78 row_ror:8 row_mask:0xf bank_mask:0xf
	s_waitcnt lgkmcnt(3)
	v_add_f32_e32 v79, v79, v81
	s_nop 1
	v_mov_b32_dpp v81, v79 row_ror:8 row_mask:0xf bank_mask:0xf
	s_waitcnt lgkmcnt(3)
	v_add_f32_e32 v80, v80, v82
	s_nop 1
	v_mov_b32_dpp v82, v80 row_ror:8 row_mask:0xf bank_mask:0xf
	s_waitcnt lgkmcnt(3)
	v_add_f32_e32 v0, v0, v108
	v_mov_b32_e32 v108, v0
	s_nop 1
	v_permlane16_swap_b32_e32 v0, v108
	s_waitcnt lgkmcnt(3)
	v_add_f32_e32 v78, v78, v83
	v_mov_b32_e32 v83, v78
	s_nop 1
	v_permlane16_swap_b32_e32 v78, v83
	s_waitcnt lgkmcnt(3)
	v_add_f32_e32 v79, v79, v81
	v_mov_b32_e32 v81, v79
	s_nop 1
	v_permlane16_swap_b32_e32 v79, v81
	s_waitcnt lgkmcnt(3)
	v_add_f32_e32 v80, v80, v82
	v_mov_b32_e32 v82, v80
	s_nop 1
	v_permlane16_swap_b32_e32 v80, v82
	s_waitcnt lgkmcnt(3)
	v_add_f32_e32 v0, v0, v108
	v_mov_b32_e32 v108, v0
	s_waitcnt lgkmcnt(2)
	v_add_f32_e32 v78, v78, v83
	v_permlane32_swap_b32_e32 v0, v108
	v_mov_b32_e32 v83, v78
	s_waitcnt lgkmcnt(1)
	v_add_f32_e32 v79, v79, v81
	v_add_f32_e32 v0, v0, v108
	v_permlane32_swap_b32_e32 v78, v83
	v_mov_b32_e32 v81, v79
	s_waitcnt lgkmcnt(0)
	v_add_f32_e32 v80, v80, v82
	v_fmamk_f32 v0, v0, 0x3a800000, v193
	v_add_f32_e32 v78, v78, v83
	v_permlane32_swap_b32_e32 v79, v81
	v_mov_b32_e32 v82, v80
	v_rsq_f32_e32 v0, v0
	v_fmamk_f32 v78, v78, 0x3a800000, v193
	v_add_f32_e32 v79, v79, v81
	v_permlane32_swap_b32_e32 v80, v82
	v_rsq_f32_e32 v78, v78
	v_fmamk_f32 v79, v79, 0x3a800000, v193
	v_add_f32_e32 v81, v80, v82
	v_rsq_f32_e32 v80, v79
	v_fmamk_f32 v79, v81, 0x3a800000, v193
	v_rsq_f32_e32 v82, v79
	v_pk_mul_f32 v[86:87], v[86:87], v[0:1] op_sel_hi:[1,0]
	v_pk_mul_f32 v[88:89], v[88:89], v[0:1] op_sel_hi:[1,0]
	v_pk_fma_f32 v[86:87], v[86:87], v[106:107], v[34:35]
	v_pk_fma_f32 v[88:89], v[88:89], v[84:85], v[36:37]
	v_pk_mul_f32 v[90:91], v[90:91], v[78:79] op_sel_hi:[1,0]
	v_pk_mul_f32 v[92:93], v[92:93], v[78:79] op_sel_hi:[1,0]
	v_cvt_pk_bf16_f32 v86, v86, v87
	v_cvt_pk_bf16_f32 v87, v88, v89
	v_pk_fma_f32 v[88:89], v[92:93], v[84:85], v[36:37]
	v_pk_fma_f32 v[90:91], v[90:91], v[106:107], v[34:35]
	v_pk_mul_f32 v[92:93], v[94:95], v[80:81] op_sel_hi:[1,0]
	v_pk_mul_f32 v[94:95], v[96:97], v[80:81] op_sel_hi:[1,0]
	global_store_dwordx2 v[72:73], v[86:87], off offset:1024
	v_cvt_pk_bf16_f32 v86, v90, v91
	v_cvt_pk_bf16_f32 v87, v88, v89
	v_pk_fma_f32 v[88:89], v[94:95], v[84:85], v[36:37]
	v_pk_fma_f32 v[90:91], v[92:93], v[106:107], v[34:35]
	v_pk_mul_f32 v[92:93], v[102:103], v[82:83] op_sel_hi:[1,0]
	v_pk_mul_f32 v[94:95], v[104:105], v[82:83] op_sel_hi:[1,0]
	v_pk_fma_f32 v[34:35], v[106:107], v[92:93], v[34:35]
	v_pk_fma_f32 v[36:37], v[84:85], v[94:95], v[36:37]
	global_store_dwordx2 v[72:73], v[86:87], off offset:3072
	v_cvt_pk_bf16_f32 v86, v90, v91
	v_cvt_pk_bf16_f32 v87, v88, v89
	v_cvt_pk_bf16_f32 v34, v34, v35
	v_cvt_pk_bf16_f32 v35, v36, v37
	global_store_dwordx2 v[74:75], v[86:87], off offset:1024
	global_store_dwordx2 v[74:75], v[34:35], off offset:3072
	global_load_dwordx4 v[34:37], v[58:59], off
	s_nop 0
	global_load_dwordx4 v[84:87], v[50:51], off offset:1024
	global_load_dwordx4 v[88:91], v[56:57], off
	v_pk_mul_f32 v[38:39], v[38:39], v[0:1] op_sel_hi:[1,0]
	v_pk_mul_f32 v[40:41], v[40:41], v[0:1] op_sel_hi:[1,0]
	v_pk_mul_f32 v[42:43], v[42:43], v[78:79] op_sel_hi:[1,0]
	v_pk_mul_f32 v[44:45], v[44:45], v[78:79] op_sel_hi:[1,0]
	v_pk_mul_f32 v[92:93], v[98:99], v[80:81] op_sel_hi:[1,0]
	v_pk_mul_f32 v[94:95], v[100:101], v[80:81] op_sel_hi:[1,0]
	v_pk_mul_f32 v[46:47], v[46:47], v[82:83] op_sel_hi:[1,0]
	v_pk_mul_f32 v[48:49], v[48:49], v[82:83] op_sel_hi:[1,0]
	v_pk_mul_f32 v[18:19], v[18:19], v[0:1] op_sel_hi:[1,0]
	v_pk_mul_f32 v[20:21], v[20:21], v[0:1] op_sel_hi:[1,0]
	v_pk_mul_f32 v[22:23], v[22:23], v[78:79] op_sel_hi:[1,0]
	v_pk_mul_f32 v[24:25], v[24:25], v[78:79] op_sel_hi:[1,0]
	v_pk_mul_f32 v[30:31], v[30:31], v[80:81] op_sel_hi:[1,0]
	v_pk_mul_f32 v[32:33], v[32:33], v[80:81] op_sel_hi:[1,0]
	v_pk_mul_f32 v[26:27], v[26:27], v[82:83] op_sel_hi:[1,0]
	v_pk_mul_f32 v[28:29], v[28:29], v[82:83] op_sel_hi:[1,0]
	v_pk_mul_f32 v[2:3], v[2:3], v[0:1] op_sel_hi:[1,0]
	v_pk_mul_f32 v[4:5], v[4:5], v[0:1] op_sel_hi:[1,0]
	v_pk_mul_f32 v[6:7], v[6:7], v[78:79] op_sel_hi:[1,0]
	v_pk_mul_f32 v[8:9], v[8:9], v[78:79] op_sel_hi:[1,0]
	v_pk_mul_f32 v[10:11], v[10:11], v[80:81] op_sel_hi:[1,0]
	v_pk_mul_f32 v[12:13], v[12:13], v[80:81] op_sel_hi:[1,0]
	v_pk_mul_f32 v[14:15], v[14:15], v[82:83] op_sel_hi:[1,0]
	v_pk_mul_f32 v[16:17], v[16:17], v[82:83] op_sel_hi:[1,0]
	s_waitcnt vmcnt(2)
; __device__ __forceinline__ unsigned pk2(float lo, float hi) { const f32x2_t v = {lo, hi}; const bf16x2_t b = __builtin_convertvector(v, bf16x2_t); return __builtin_bit_cast(unsigned, b); }
; __device__ __forceinline__ void norm_phase(const Ctx& F, float* X, const float* gw, const float* modl, int ish, int isc, bf16_t* XN, const float* part, int nsplit) {
;     ...
; #pragma unroll
;         for (int j = 0; j < 4; ++j) {
;             const int col = 4 * F.lane + 256 * j;
;             const f32x4 g4 = *(const f32x4*)(gw + col), sh = *(const f32x4*)(mv + ish * 1024 + col), sc = *(const f32x4*)(mv + isc * 1024 + col);
;             const f32x4 gs = g4 * (sc + 1.0f);
; #pragma unroll
;             for (int r = 0; r < 4; ++r) {
;                 const f32x4 o = (v[r][j] * rs[r]) * gs + sh;
;                 u32x2 w; w.x = pk2(o.x, o.y); w.y = pk2(o.z, o.w);
;                 *(u32x2*)(XN + (size_t)(row0 + r) * D + col) = w;
;             }
;         }
	v_pk_add_f32 v[36:37], v[36:37], 1.0 op_sel_hi:[1,0]
	v_pk_add_f32 v[34:35], v[34:35], 1.0 op_sel_hi:[1,0]
	s_waitcnt vmcnt(1)
	v_pk_mul_f32 v[36:37], v[86:87], v[36:37]
	v_pk_mul_f32 v[34:35], v[84:85], v[34:35]
	s_waitcnt vmcnt(0)
	v_pk_fma_f32 v[40:41], v[40:41], v[36:37], v[90:91]
	v_pk_fma_f32 v[38:39], v[38:39], v[34:35], v[88:89]
	v_pk_fma_f32 v[44:45], v[44:45], v[36:37], v[90:91]
	v_pk_fma_f32 v[42:43], v[42:43], v[34:35], v[88:89]
	v_pk_fma_f32 v[84:85], v[94:95], v[36:37], v[90:91]
	v_pk_fma_f32 v[86:87], v[92:93], v[34:35], v[88:89]
	v_pk_fma_f32 v[36:37], v[48:49], v[36:37], v[90:91]
	v_pk_fma_f32 v[34:35], v[46:47], v[34:35], v[88:89]
	v_cvt_pk_bf16_f32 v38, v38, v39
	v_cvt_pk_bf16_f32 v39, v40, v41
	v_cvt_pk_bf16_f32 v40, v42, v43
	v_cvt_pk_bf16_f32 v41, v44, v45
	v_cvt_pk_bf16_f32 v42, v86, v87
	v_cvt_pk_bf16_f32 v43, v84, v85
	v_cvt_pk_bf16_f32 v34, v34, v35
	v_cvt_pk_bf16_f32 v35, v36, v37
	global_store_dwordx2 v[72:73], v[38:39], off offset:1536
	global_store_dwordx2 v[72:73], v[40:41], off offset:3584
	global_store_dwordx2 v[74:75], v[42:43], off offset:1536
	global_store_dwordx2 v[74:75], v[34:35], off offset:3584
	global_load_dwordx4 v[34:37], v[62:63], off
	s_nop 0
	global_load_dwordx4 v[38:41], v[50:51], off offset:2048
	global_load_dwordx4 v[42:45], v[60:61], off
	v_add_co_u32_e32 v46, vcc, s29, v76
	s_waitcnt vmcnt(2)
	v_pk_add_f32 v[36:37], v[36:37], 1.0 op_sel_hi:[1,0]
	v_pk_add_f32 v[34:35], v[34:35], 1.0 op_sel_hi:[1,0]
	s_waitcnt vmcnt(1)
	v_pk_mul_f32 v[36:37], v[40:41], v[36:37]
	v_pk_mul_f32 v[34:35], v[38:39], v[34:35]
	s_waitcnt vmcnt(0)
	v_pk_fma_f32 v[20:21], v[20:21], v[36:37], v[44:45]
	v_pk_fma_f32 v[18:19], v[18:19], v[34:35], v[42:43]
	v_pk_fma_f32 v[24:25], v[24:25], v[36:37], v[44:45]
	v_pk_fma_f32 v[22:23], v[22:23], v[34:35], v[42:43]
	v_pk_fma_f32 v[32:33], v[32:33], v[36:37], v[44:45]
	v_pk_fma_f32 v[30:31], v[30:31], v[34:35], v[42:43]
	v_pk_fma_f32 v[28:29], v[28:29], v[36:37], v[44:45]
	v_pk_fma_f32 v[26:27], v[26:27], v[34:35], v[42:43]
	v_cvt_pk_bf16_f32 v18, v18, v19
	v_cvt_pk_bf16_f32 v19, v20, v21
	v_addc_co_u32_e32 v47, vcc, 0, v77, vcc
	v_cvt_pk_bf16_f32 v20, v22, v23
	v_cvt_pk_bf16_f32 v21, v24, v25
	v_cvt_pk_bf16_f32 v22, v30, v31
	v_cvt_pk_bf16_f32 v23, v32, v33
	v_cvt_pk_bf16_f32 v24, v26, v27
	v_cvt_pk_bf16_f32 v25, v28, v29
	global_store_dwordx2 v[72:73], v[18:19], off offset:2048
	global_store_dwordx2 v[46:47], v[20:21], off offset:-4096
	global_store_dwordx2 v[74:75], v[22:23], off offset:2048
	global_store_dwordx2 v[46:47], v[24:25], off
	global_load_dwordx4 v[18:21], v[66:67], off
	s_nop 0
	global_load_dwordx4 v[22:25], v[50:51], off offset:3072
	global_load_dwordx4 v[26:29], v[64:65], off
	s_waitcnt vmcnt(2)
	v_pk_add_f32 v[20:21], v[20:21], 1.0 op_sel_hi:[1,0]
	v_pk_add_f32 v[18:19], v[18:19], 1.0 op_sel_hi:[1,0]
	s_waitcnt vmcnt(1)
	v_pk_mul_f32 v[20:21], v[24:25], v[20:21]
	v_pk_mul_f32 v[18:19], v[22:23], v[18:19]
	s_waitcnt vmcnt(0)
	v_pk_fma_f32 v[4:5], v[4:5], v[20:21], v[28:29]
	v_pk_fma_f32 v[2:3], v[2:3], v[18:19], v[26:27]
	v_pk_fma_f32 v[8:9], v[8:9], v[20:21], v[28:29]
	v_pk_fma_f32 v[6:7], v[6:7], v[18:19], v[26:27]
	v_pk_fma_f32 v[12:13], v[12:13], v[20:21], v[28:29]
	v_pk_fma_f32 v[10:11], v[10:11], v[18:19], v[26:27]
	v_pk_fma_f32 v[16:17], v[16:17], v[20:21], v[28:29]
	v_pk_fma_f32 v[14:15], v[14:15], v[18:19], v[26:27]
	v_cvt_pk_bf16_f32 v2, v2, v3
	v_cvt_pk_bf16_f32 v3, v4, v5
	v_cvt_pk_bf16_f32 v4, v6, v7
	v_cvt_pk_bf16_f32 v5, v8, v9
	v_cvt_pk_bf16_f32 v6, v10, v11
	v_cvt_pk_bf16_f32 v7, v12, v13
	v_cvt_pk_bf16_f32 v8, v14, v15
	v_cvt_pk_bf16_f32 v9, v16, v17
	global_store_dwordx2 v[72:73], v[2:3], off offset:2560
	global_store_dwordx2 v[74:75], v[4:5], off offset:512
	global_store_dwordx2 v[74:75], v[6:7], off offset:2560
	global_store_dwordx2 v[46:47], v[8:9], off offset:512
	s_cbranch_scc0 .LBB0_85

; __device__ __forceinline__ float bf2f(unsigned v) { return __uint_as_float(v << 16); }
; __device__ __forceinline__ unsigned f2bf(float f) { return pk2(f, 0.f) & 0xffffu; }
; template <int K> __device__ __forceinline__ float swz_xor(float v) { return __uint_as_float((unsigned)__builtin_amdgcn_ds_swizzle((int)__float_as_uint(v), (K << 10) | 0x1f)); }
; __device__ __forceinline__ void prep_qk(bf16_t* PB, int tok0, int col, const float* gain, bool rope, float outscale, int lane) {
;     ...
;     for (int pass = 0; pass < 16; ++pass) {
;         const int tok = tok0 + pass * 4 + tq;
;         bf16_t* p = PB + (size_t)tok * INW + col + i;
;         float x0 = bf2f(p[0]), x1 = bf2f(p[16]), x2 = bf2f(p[32]), x3 = bf2f(p[48]);
;         float ss = (x0 * x0 + x1 * x1) + (x2 * x2 + x3 * x3);
;         ss += swz_xor<1>(ss); ss += swz_xor<2>(ss); ss += swz_xor<4>(ss); ss += swz_xor<8>(ss);
;         const float r = 1.0f / sqrtf(ss * (1.f / 64.f) + EPSN);
;         x0 = x0 * r * g0; x1 = x1 * r * g1; x2 = x2 * r * g2; x3 = x3 * r * g3;
;         if (rope) {
;             const float ar = (float)(tok >> 6) * inv, ac = (float)(tok & 63) * inv;
;             const float sr = __sinf(ar), cr = __cosf(ar), sc = __sinf(ac), cc = __cosf(ac);
;             const float a0 = x0, b0 = x1; x0 = a0 * cr - b0 * sr; x1 = b0 * cr + a0 * sr;
;             const float a1 = x2, b1 = x3; x2 = a1 * cc - b1 * sc; x3 = b1 * cc + a1 * sc;
;         }
;         p[0] = (bf16_t)f2bf(x0 * outscale); p[16] = (bf16_t)f2bf(x1 * outscale); p[32] = (bf16_t)f2bf(x2 * outscale); p[48] = (bf16_t)f2bf(x3 * outscale);
;     }
.LBB0_478:
	v_add_u32_e32 v17, s2, v0
	v_mad_i64_i32 v[8:9], s[4:5], v17, s21, v[6:7]
	global_load_ushort v10, v[8:9], off offset:64
	global_load_ushort v11, v[8:9], off
	global_load_ushort v12, v[8:9], off offset:96
	global_load_ushort v13, v[8:9], off offset:32
	s_waitcnt vmcnt(0)
	v_lshlrev_b32_e32 v10, 16, v10
	s_waitcnt vmcnt(1)
	v_lshlrev_b32_e32 v12, 16, v12
	s_waitcnt vmcnt(0)
	v_lshlrev_b32_e32 v13, 16, v13
	v_lshlrev_b32_e32 v11, 16, v11
	v_pk_mul_f32 v[18:19], v[12:13], v[12:13]
	s_nop 0
	v_pk_fma_f32 v[18:19], v[10:11], v[10:11], v[18:19]
	s_nop 0
	v_add_f32_e32 v18, v19, v18
	s_nop 1
	v_mov_b32_dpp v19, v18 quad_perm:[1,0,3,2] row_mask:0xf bank_mask:0xf
	s_waitcnt lgkmcnt(0)
	v_add_f32_e32 v18, v18, v19
	s_nop 1
	v_mov_b32_dpp v19, v18 quad_perm:[2,3,0,1] row_mask:0xf bank_mask:0xf
	s_waitcnt lgkmcnt(0)
	v_add_f32_e32 v18, v18, v19
	s_nop 1
	v_mov_b32_dpp v19, v18 row_half_mirror row_mask:0xf bank_mask:0xf
	s_waitcnt lgkmcnt(0)
	v_add_f32_e32 v18, v18, v19
	s_nop 1
	v_mov_b32_dpp v19, v18 row_ror:8 row_mask:0xf bank_mask:0xf
	s_waitcnt lgkmcnt(0)
	v_add_f32_e32 v18, v18, v19
	v_fmamk_f32 v18, v18, 0x3c800000, v193
	v_cmp_gt_f32_e32 vcc, s41, v18
	v_mul_f32_e32 v19, 0x4f800000, v18
	s_nop 0
	v_cndmask_b32_e32 v18, v18, v19, vcc
	v_sqrt_f32_e32 v19, v18
	s_nop 0
	v_add_u32_e32 v20, -1, v19
	v_fma_f32 v21, -v20, v19, v18
	v_cmp_ge_f32_e64 s[4:5], 0, v21
	v_add_u32_e32 v21, 1, v19
	s_nop 0
	v_cndmask_b32_e64 v20, v19, v20, s[4:5]
	v_fma_f32 v19, -v21, v19, v18
	v_cmp_lt_f32_e64 s[4:5], 0, v19
	s_nop 1
	v_cndmask_b32_e64 v19, v20, v21, s[4:5]
	v_mul_f32_e32 v20, 0x37800000, v19
	v_cndmask_b32_e32 v19, v19, v20, vcc
	v_cmp_class_f32_e32 vcc, v18, v202
	s_nop 1
	v_cndmask_b32_e32 v18, v19, v18, vcc
	v_div_scale_f32 v19, s[4:5], v18, v18, 1.0
	v_rcp_f32_e32 v20, v19
	s_nop 0
	v_fma_f32 v21, -v19, v20, 1.0
	v_fmac_f32_e32 v20, v21, v20
	v_div_scale_f32 v21, vcc, 1.0, v18, 1.0
	v_mul_f32_e32 v22, v21, v20
	v_fma_f32 v23, -v19, v22, v21
	v_fmac_f32_e32 v22, v23, v20
	v_fma_f32 v19, -v19, v22, v21
	v_div_fmas_f32 v19, v19, v20, v22
	v_div_fixup_f32 v18, v19, v18, 1.0
	v_pk_mul_f32 v[10:11], v[18:19], v[10:11] op_sel_hi:[0,1]
	v_pk_mul_f32 v[18:19], v[18:19], v[12:13] op_sel_hi:[0,1]
	v_pk_mul_f32 v[12:13], v[2:3], v[10:11]
	v_pk_mul_f32 v[10:11], v[4:5], v[18:19]
	v_cndmask_b32_e64 v18, 0, 1, s[44:45]
	v_cmp_ne_u32_e64 s[4:5], 1, v18
	s_andn2_b64 vcc, exec, s[44:45]
	s_cbranch_vccnz .LBB0_480
	v_ashrrev_i32_e32 v18, 6, v17
	v_cvt_f32_i32_e32 v18, v18
	v_and_b32_e32 v19, 63, v17
	v_cvt_f32_ubyte0_e32 v19, v19
	v_mul_f32_e32 v20, v16, v19
	v_mul_f32_e32 v18, v16, v18
	v_mul_f32_e32 v18, 0.15915494, v18
	v_mul_f32_e32 v20, 0.15915494, v20
	v_sin_f32_e32 v19, v18
	v_cos_f32_e32 v21, v18
	v_sin_f32_e32 v18, v20
	v_cos_f32_e32 v20, v20
	v_pk_mul_f32 v[22:23], v[18:19], v[10:11]
	s_nop 0
	v_pk_fma_f32 v[22:23], v[20:21], v[12:13], v[22:23] neg_lo:[0,0,1] neg_hi:[0,0,1]
	v_pk_mul_f32 v[12:13], v[18:19], v[12:13]
	s_nop 0
	v_pk_fma_f32 v[10:11], v[20:21], v[10:11], v[12:13]
	v_mov_b64_e32 v[12:13], v[22:23]
.LBB0_480:
	v_cvt_pk_bf16_f32 v11, v11, s0
	v_cvt_pk_bf16_f32 v13, v13, s0
	global_store_short v[8:9], v11, off offset:32
	v_cvt_pk_bf16_f32 v11, v12, s0
	v_cvt_pk_bf16_f32 v10, v10, s0
	v_add_u32_e32 v18, 4, v17
	global_store_short v[8:9], v13, off
	global_store_short v[8:9], v11, off offset:64
	global_store_short v[8:9], v10, off offset:96
	v_mad_i64_i32 v[8:9], s[6:7], v18, s21, v[6:7]
	global_load_ushort v10, v[8:9], off offset:64
	global_load_ushort v11, v[8:9], off
	global_load_ushort v12, v[8:9], off offset:96
	global_load_ushort v13, v[8:9], off offset:32
	s_waitcnt vmcnt(3)
	v_lshlrev_b32_e32 v10, 16, v10
	s_waitcnt vmcnt(1)
	v_lshlrev_b32_e32 v12, 16, v12
	s_waitcnt vmcnt(0)
	v_lshlrev_b32_e32 v13, 16, v13
	v_lshlrev_b32_e32 v11, 16, v11
	v_pk_mul_f32 v[20:21], v[12:13], v[12:13]
	s_nop 0
	v_pk_fma_f32 v[20:21], v[10:11], v[10:11], v[20:21]
	s_nop 0
	v_add_f32_e32 v19, v21, v20
	s_nop 1
	v_mov_b32_dpp v20, v19 quad_perm:[1,0,3,2] row_mask:0xf bank_mask:0xf
	s_waitcnt lgkmcnt(0)
	v_add_f32_e32 v19, v19, v20
	s_nop 1
	v_mov_b32_dpp v20, v19 quad_perm:[2,3,0,1] row_mask:0xf bank_mask:0xf
	s_waitcnt lgkmcnt(0)
	v_add_f32_e32 v19, v19, v20
	s_nop 1
	v_mov_b32_dpp v20, v19 row_half_mirror row_mask:0xf bank_mask:0xf
	s_waitcnt lgkmcnt(0)
	v_add_f32_e32 v19, v19, v20
	s_nop 1
	v_mov_b32_dpp v20, v19 row_ror:8 row_mask:0xf bank_mask:0xf
	s_waitcnt lgkmcnt(0)
	v_add_f32_e32 v19, v19, v20
	v_fmamk_f32 v19, v19, 0x3c800000, v193
	v_cmp_gt_f32_e32 vcc, s41, v19
	v_mul_f32_e32 v20, 0x4f800000, v19
	s_nop 0
	v_cndmask_b32_e32 v19, v19, v20, vcc
	v_sqrt_f32_e32 v20, v19
	s_nop 0
	v_add_u32_e32 v21, -1, v20
	v_fma_f32 v22, -v21, v20, v19
	v_cmp_ge_f32_e64 s[6:7], 0, v22
	v_add_u32_e32 v22, 1, v20
	s_nop 0
	v_cndmask_b32_e64 v21, v20, v21, s[6:7]
	v_fma_f32 v20, -v22, v20, v19
	v_cmp_lt_f32_e64 s[6:7], 0, v20
	s_nop 1
	v_cndmask_b32_e64 v20, v21, v22, s[6:7]
	v_mul_f32_e32 v21, 0x37800000, v20
	v_cndmask_b32_e32 v20, v20, v21, vcc
	v_cmp_class_f32_e32 vcc, v19, v202
	s_nop 1
	v_cndmask_b32_e32 v19, v20, v19, vcc
	v_div_scale_f32 v20, s[6:7], v19, v19, 1.0
	v_rcp_f32_e32 v21, v20
	s_nop 0
	v_fma_f32 v22, -v20, v21, 1.0
	v_fmac_f32_e32 v21, v22, v21
	v_div_scale_f32 v22, vcc, 1.0, v19, 1.0
	v_mul_f32_e32 v23, v22, v21
	v_fma_f32 v24, -v20, v23, v22
	v_fmac_f32_e32 v23, v24, v21
	v_fma_f32 v20, -v20, v23, v22
	v_div_fmas_f32 v20, v20, v21, v23
	v_div_fixup_f32 v20, v20, v19, 1.0
	v_pk_mul_f32 v[10:11], v[20:21], v[10:11] op_sel_hi:[0,1]
	v_pk_mul_f32 v[20:21], v[20:21], v[12:13] op_sel_hi:[0,1]
	v_pk_mul_f32 v[12:13], v[2:3], v[10:11]
	v_pk_mul_f32 v[10:11], v[4:5], v[20:21]
	s_and_b64 vcc, exec, s[4:5]
	s_cbranch_vccnz .LBB0_482
	v_ashrrev_i32_e32 v19, 6, v18
	v_cvt_f32_i32_e32 v19, v19
	v_and_b32_e32 v18, 63, v18
	v_cvt_f32_ubyte0_e32 v18, v18
	v_mul_f32_e32 v18, v16, v18
	v_mul_f32_e32 v19, v16, v19
	v_mul_f32_e32 v20, 0.15915494, v19
	v_sin_f32_e32 v19, v20
	v_cos_f32_e32 v21, v20
	v_mul_f32_e32 v20, 0.15915494, v18
	v_sin_f32_e32 v18, v20
	v_cos_f32_e32 v20, v20
	v_pk_mul_f32 v[22:23], v[18:19], v[10:11]
	s_nop 0
	v_pk_fma_f32 v[22:23], v[20:21], v[12:13], v[22:23] neg_lo:[0,0,1] neg_hi:[0,0,1]
	v_pk_mul_f32 v[12:13], v[18:19], v[12:13]
	s_nop 0
	v_pk_fma_f32 v[10:11], v[20:21], v[10:11], v[12:13]
	v_mov_b64_e32 v[12:13], v[22:23]
; __device__ __forceinline__ float bf2f(unsigned v) { return __uint_as_float(v << 16); }
; __device__ __forceinline__ unsigned f2bf(float f) { return pk2(f, 0.f) & 0xffffu; }
; template <int K> __device__ __forceinline__ float swz_xor(float v) { return __uint_as_float((unsigned)__builtin_amdgcn_ds_swizzle((int)__float_as_uint(v), (K << 10) | 0x1f)); }
; __device__ __forceinline__ void prep_qk(bf16_t* PB, int tok0, int col, const float* gain, bool rope, float outscale, int lane) {
;     ...
;     for (int pass = 0; pass < 16; ++pass) {
;         const int tok = tok0 + pass * 4 + tq;
;         bf16_t* p = PB + (size_t)tok * INW + col + i;
;         float x0 = bf2f(p[0]), x1 = bf2f(p[16]), x2 = bf2f(p[32]), x3 = bf2f(p[48]);
;         float ss = (x0 * x0 + x1 * x1) + (x2 * x2 + x3 * x3);
;         ss += swz_xor<1>(ss); ss += swz_xor<2>(ss); ss += swz_xor<4>(ss); ss += swz_xor<8>(ss);
;         const float r = 1.0f / sqrtf(ss * (1.f / 64.f) + EPSN);
;         x0 = x0 * r * g0; x1 = x1 * r * g1; x2 = x2 * r * g2; x3 = x3 * r * g3;
;         if (rope) {
;             const float ar = (float)(tok >> 6) * inv, ac = (float)(tok & 63) * inv;
;             const float sr = __sinf(ar), cr = __cosf(ar), sc = __sinf(ac), cc = __cosf(ac);
;             const float a0 = x0, b0 = x1; x0 = a0 * cr - b0 * sr; x1 = b0 * cr + a0 * sr;
;             const float a1 = x2, b1 = x3; x2 = a1 * cc - b1 * sc; x3 = b1 * cc + a1 * sc;
;         }
;         p[0] = (bf16_t)f2bf(x0 * outscale); p[16] = (bf16_t)f2bf(x1 * outscale); p[32] = (bf16_t)f2bf(x2 * outscale); p[48] = (bf16_t)f2bf(x3 * outscale);
;     }
.LBB0_482:
	v_cvt_pk_bf16_f32 v11, v11, s0
	v_cvt_pk_bf16_f32 v13, v13, s0
	global_store_short v[8:9], v11, off offset:32
	v_cvt_pk_bf16_f32 v11, v12, s0
	v_cvt_pk_bf16_f32 v10, v10, s0
	v_add_u32_e32 v18, 8, v17
	global_store_short v[8:9], v13, off
	global_store_short v[8:9], v11, off offset:64
	global_store_short v[8:9], v10, off offset:96
	v_mad_i64_i32 v[8:9], s[6:7], v18, s21, v[6:7]
	global_load_ushort v10, v[8:9], off offset:64
	global_load_ushort v11, v[8:9], off
	global_load_ushort v12, v[8:9], off offset:96
	global_load_ushort v13, v[8:9], off offset:32
	s_waitcnt vmcnt(3)
	v_lshlrev_b32_e32 v10, 16, v10
	s_waitcnt vmcnt(1)
	v_lshlrev_b32_e32 v12, 16, v12
	s_waitcnt vmcnt(0)
	v_lshlrev_b32_e32 v13, 16, v13
	v_lshlrev_b32_e32 v11, 16, v11
	v_pk_mul_f32 v[20:21], v[12:13], v[12:13]
	s_nop 0
	v_pk_fma_f32 v[20:21], v[10:11], v[10:11], v[20:21]
	s_nop 0
	v_add_f32_e32 v19, v21, v20
	s_nop 1
	v_mov_b32_dpp v20, v19 quad_perm:[1,0,3,2] row_mask:0xf bank_mask:0xf
	s_waitcnt lgkmcnt(0)
	v_add_f32_e32 v19, v19, v20
	s_nop 1
	v_mov_b32_dpp v20, v19 quad_perm:[2,3,0,1] row_mask:0xf bank_mask:0xf
	s_waitcnt lgkmcnt(0)
	v_add_f32_e32 v19, v19, v20
	s_nop 1
	v_mov_b32_dpp v20, v19 row_half_mirror row_mask:0xf bank_mask:0xf
	s_waitcnt lgkmcnt(0)
	v_add_f32_e32 v19, v19, v20
	s_nop 1
	v_mov_b32_dpp v20, v19 row_ror:8 row_mask:0xf bank_mask:0xf
	s_waitcnt lgkmcnt(0)
	v_add_f32_e32 v19, v19, v20
	v_fmamk_f32 v19, v19, 0x3c800000, v193
	v_cmp_gt_f32_e32 vcc, s41, v19
	v_mul_f32_e32 v20, 0x4f800000, v19
	s_nop 0
	v_cndmask_b32_e32 v19, v19, v20, vcc
	v_sqrt_f32_e32 v20, v19
	s_nop 0
	v_add_u32_e32 v21, -1, v20
	v_fma_f32 v22, -v21, v20, v19
	v_cmp_ge_f32_e64 s[6:7], 0, v22
	v_add_u32_e32 v22, 1, v20
	s_nop 0
	v_cndmask_b32_e64 v21, v20, v21, s[6:7]
	v_fma_f32 v20, -v22, v20, v19
	v_cmp_lt_f32_e64 s[6:7], 0, v20
	s_nop 1
	v_cndmask_b32_e64 v20, v21, v22, s[6:7]
	v_mul_f32_e32 v21, 0x37800000, v20
	v_cndmask_b32_e32 v20, v20, v21, vcc
	v_cmp_class_f32_e32 vcc, v19, v202
	s_nop 1
	v_cndmask_b32_e32 v19, v20, v19, vcc
	v_div_scale_f32 v20, s[6:7], v19, v19, 1.0
	v_rcp_f32_e32 v21, v20
	s_nop 0
	v_fma_f32 v22, -v20, v21, 1.0
	v_fmac_f32_e32 v21, v22, v21
	v_div_scale_f32 v22, vcc, 1.0, v19, 1.0
	v_mul_f32_e32 v23, v22, v21
	v_fma_f32 v24, -v20, v23, v22
	v_fmac_f32_e32 v23, v24, v21
	v_fma_f32 v20, -v20, v23, v22
	v_div_fmas_f32 v20, v20, v21, v23
	v_div_fixup_f32 v20, v20, v19, 1.0
	v_pk_mul_f32 v[10:11], v[20:21], v[10:11] op_sel_hi:[0,1]
	v_pk_mul_f32 v[20:21], v[20:21], v[12:13] op_sel_hi:[0,1]
	v_pk_mul_f32 v[12:13], v[2:3], v[10:11]
	v_pk_mul_f32 v[10:11], v[4:5], v[20:21]
	s_and_b64 vcc, exec, s[4:5]
	s_cbranch_vccnz .LBB0_484
	v_ashrrev_i32_e32 v19, 6, v18
	v_cvt_f32_i32_e32 v19, v19
	v_and_b32_e32 v18, 63, v18
	v_cvt_f32_ubyte0_e32 v18, v18
	v_mul_f32_e32 v18, v16, v18
	v_mul_f32_e32 v19, v16, v19
	v_mul_f32_e32 v20, 0.15915494, v19
	v_sin_f32_e32 v19, v20
	v_cos_f32_e32 v21, v20
	v_mul_f32_e32 v20, 0.15915494, v18
	v_sin_f32_e32 v18, v20
	v_cos_f32_e32 v20, v20
	v_pk_mul_f32 v[22:23], v[18:19], v[10:11]
	s_nop 0
	v_pk_fma_f32 v[22:23], v[20:21], v[12:13], v[22:23] neg_lo:[0,0,1] neg_hi:[0,0,1]
	v_pk_mul_f32 v[12:13], v[18:19], v[12:13]
	s_nop 0
	v_pk_fma_f32 v[10:11], v[20:21], v[10:11], v[12:13]
	v_mov_b64_e32 v[12:13], v[22:23]
.LBB0_484:
	v_cvt_pk_bf16_f32 v11, v11, s0
	v_cvt_pk_bf16_f32 v13, v13, s0
	global_store_short v[8:9], v11, off offset:32
	v_cvt_pk_bf16_f32 v11, v12, s0
	v_cvt_pk_bf16_f32 v10, v10, s0
	v_add_u32_e32 v17, 12, v17
	global_store_short v[8:9], v13, off
	global_store_short v[8:9], v11, off offset:64
	global_store_short v[8:9], v10, off offset:96
	v_mad_i64_i32 v[8:9], s[6:7], v17, s21, v[6:7]
	global_load_ushort v10, v[8:9], off offset:64
	global_load_ushort v11, v[8:9], off
	global_load_ushort v12, v[8:9], off offset:96
	global_load_ushort v13, v[8:9], off offset:32
	s_waitcnt vmcnt(3)
	v_lshlrev_b32_e32 v10, 16, v10
	s_waitcnt vmcnt(1)
	v_lshlrev_b32_e32 v12, 16, v12
	s_waitcnt vmcnt(0)
	v_lshlrev_b32_e32 v13, 16, v13
	v_lshlrev_b32_e32 v11, 16, v11
	v_pk_mul_f32 v[18:19], v[12:13], v[12:13]
	s_nop 0
	v_pk_fma_f32 v[18:19], v[10:11], v[10:11], v[18:19]
	s_nop 0
	v_add_f32_e32 v18, v19, v18
	s_nop 1
	v_mov_b32_dpp v19, v18 quad_perm:[1,0,3,2] row_mask:0xf bank_mask:0xf
	s_waitcnt lgkmcnt(0)
	v_add_f32_e32 v18, v18, v19
	s_nop 1
	v_mov_b32_dpp v19, v18 quad_perm:[2,3,0,1] row_mask:0xf bank_mask:0xf
	s_waitcnt lgkmcnt(0)
	v_add_f32_e32 v18, v18, v19
	s_nop 1
	v_mov_b32_dpp v19, v18 row_half_mirror row_mask:0xf bank_mask:0xf
	s_waitcnt lgkmcnt(0)
	v_add_f32_e32 v18, v18, v19
	s_nop 1
	v_mov_b32_dpp v19, v18 row_ror:8 row_mask:0xf bank_mask:0xf
	s_waitcnt lgkmcnt(0)
	v_add_f32_e32 v18, v18, v19
	v_fmamk_f32 v18, v18, 0x3c800000, v193
	v_cmp_gt_f32_e32 vcc, s41, v18
	v_mul_f32_e32 v19, 0x4f800000, v18
	s_nop 0
	v_cndmask_b32_e32 v18, v18, v19, vcc
	v_sqrt_f32_e32 v19, v18
	s_nop 0
	v_add_u32_e32 v20, -1, v19
	v_fma_f32 v21, -v20, v19, v18
	v_cmp_ge_f32_e64 s[6:7], 0, v21
	v_add_u32_e32 v21, 1, v19
	s_nop 0
	v_cndmask_b32_e64 v20, v19, v20, s[6:7]
	v_fma_f32 v19, -v21, v19, v18
	v_cmp_lt_f32_e64 s[6:7], 0, v19
	s_nop 1
	v_cndmask_b32_e64 v19, v20, v21, s[6:7]
	v_mul_f32_e32 v20, 0x37800000, v19
	v_cndmask_b32_e32 v19, v19, v20, vcc
	v_cmp_class_f32_e32 vcc, v18, v202
	s_nop 1
	v_cndmask_b32_e32 v18, v19, v18, vcc
	v_div_scale_f32 v19, s[6:7], v18, v18, 1.0
	v_rcp_f32_e32 v20, v19
	s_nop 0
	v_fma_f32 v21, -v19, v20, 1.0
	v_fmac_f32_e32 v20, v21, v20
	v_div_scale_f32 v21, vcc, 1.0, v18, 1.0
	v_mul_f32_e32 v22, v21, v20
	v_fma_f32 v23, -v19, v22, v21
	v_fmac_f32_e32 v22, v23, v20
	v_fma_f32 v19, -v19, v22, v21
	v_div_fmas_f32 v19, v19, v20, v22
	v_div_fixup_f32 v18, v19, v18, 1.0
	v_pk_mul_f32 v[10:11], v[18:19], v[10:11] op_sel_hi:[0,1]
	v_pk_mul_f32 v[18:19], v[18:19], v[12:13] op_sel_hi:[0,1]
	v_pk_mul_f32 v[12:13], v[2:3], v[10:11]
	v_pk_mul_f32 v[10:11], v[4:5], v[18:19]
	s_and_b64 vcc, exec, s[4:5]
	s_cbranch_vccnz .LBB0_477
	v_ashrrev_i32_e32 v18, 6, v17
	v_cvt_f32_i32_e32 v18, v18
	v_and_b32_e32 v17, 63, v17
	v_cvt_f32_ubyte0_e32 v17, v17
	v_mul_f32_e32 v17, v16, v17
	v_mul_f32_e32 v18, v16, v18
	v_mul_f32_e32 v18, 0.15915494, v18
	v_mul_f32_e32 v17, 0.15915494, v17
	v_sin_f32_e32 v19, v18
	v_cos_f32_e32 v21, v18
	v_sin_f32_e32 v18, v17
	v_cos_f32_e32 v20, v17
	v_pk_mul_f32 v[22:23], v[18:19], v[10:11]
	s_nop 0
	v_pk_fma_f32 v[22:23], v[20:21], v[12:13], v[22:23] neg_lo:[0,0,1] neg_hi:[0,0,1]
	v_pk_mul_f32 v[12:13], v[18:19], v[12:13]
	s_nop 0
	v_pk_fma_f32 v[10:11], v[20:21], v[10:11], v[12:13]
	v_mov_b64_e32 v[12:13], v[22:23]
	s_branch .LBB0_477

; __device__ __forceinline__ float bf2f(unsigned v) { return __uint_as_float(v << 16); }
; __device__ __forceinline__ unsigned f2bf(float f) { return pk2(f, 0.f) & 0xffffu; }
; template <int K> __device__ __forceinline__ float swz_xor(float v) { return __uint_as_float((unsigned)__builtin_amdgcn_ds_swizzle((int)__float_as_uint(v), (K << 10) | 0x1f)); }
; __device__ __forceinline__ void prep_qk(bf16_t* PB, int tok0, int col, const float* gain, bool rope, float outscale, int lane) {
;     ...
;     for (int pass = 0; pass < 16; ++pass) {
;         const int tok = tok0 + pass * 4 + tq;
;         bf16_t* p = PB + (size_t)tok * INW + col + i;
;         float x0 = bf2f(p[0]), x1 = bf2f(p[16]), x2 = bf2f(p[32]), x3 = bf2f(p[48]);
;         float ss = (x0 * x0 + x1 * x1) + (x2 * x2 + x3 * x3);
;         ss += swz_xor<1>(ss); ss += swz_xor<2>(ss); ss += swz_xor<4>(ss); ss += swz_xor<8>(ss);
;         const float r = 1.0f / sqrtf(ss * (1.f / 64.f) + EPSN);
;         x0 = x0 * r * g0; x1 = x1 * r * g1; x2 = x2 * r * g2; x3 = x3 * r * g3;
;         if (rope) {
;             const float ar = (float)(tok >> 6) * inv, ac = (float)(tok & 63) * inv;
;             const float sr = __sinf(ar), cr = __cosf(ar), sc = __sinf(ac), cc = __cosf(ac);
;             const float a0 = x0, b0 = x1; x0 = a0 * cr - b0 * sr; x1 = b0 * cr + a0 * sr;
;             const float a1 = x2, b1 = x3; x2 = a1 * cc - b1 * sc; x3 = b1 * cc + a1 * sc;
;         }
;         p[0] = (bf16_t)f2bf(x0 * outscale); p[16] = (bf16_t)f2bf(x1 * outscale); p[32] = (bf16_t)f2bf(x2 * outscale); p[48] = (bf16_t)f2bf(x3 * outscale);
;     }
.LBB0_490:
	v_add_u32_e32 v16, s2, v0
	v_mad_i64_i32 v[8:9], s[4:5], v16, s21, v[6:7]
	global_load_ushort v10, v[8:9], off offset:64
	global_load_ushort v11, v[8:9], off
	global_load_ushort v12, v[8:9], off offset:96
	global_load_ushort v13, v[8:9], off offset:32
	s_waitcnt vmcnt(0)
	v_lshlrev_b32_e32 v10, 16, v10
	s_waitcnt vmcnt(1)
	v_lshlrev_b32_e32 v12, 16, v12
	s_waitcnt vmcnt(0)
	v_lshlrev_b32_e32 v13, 16, v13
	v_lshlrev_b32_e32 v11, 16, v11
	v_pk_mul_f32 v[18:19], v[12:13], v[12:13]
	s_nop 0
	v_pk_fma_f32 v[18:19], v[10:11], v[10:11], v[18:19]
	s_nop 0
	v_add_f32_e32 v17, v19, v18
	s_nop 1
	v_mov_b32_dpp v18, v17 quad_perm:[1,0,3,2] row_mask:0xf bank_mask:0xf
	s_waitcnt lgkmcnt(0)
	v_add_f32_e32 v17, v17, v18
	s_nop 1
	v_mov_b32_dpp v18, v17 quad_perm:[2,3,0,1] row_mask:0xf bank_mask:0xf
	s_waitcnt lgkmcnt(0)
	v_add_f32_e32 v17, v17, v18
	s_nop 1
	v_mov_b32_dpp v18, v17 row_half_mirror row_mask:0xf bank_mask:0xf
	s_waitcnt lgkmcnt(0)
	v_add_f32_e32 v17, v17, v18
	s_nop 1
	v_mov_b32_dpp v18, v17 row_ror:8 row_mask:0xf bank_mask:0xf
	s_waitcnt lgkmcnt(0)
	v_add_f32_e32 v17, v17, v18
	v_fmamk_f32 v17, v17, 0x3c800000, v193
	v_cmp_gt_f32_e32 vcc, s41, v17
	v_mul_f32_e32 v18, 0x4f800000, v17
	s_nop 0
	v_cndmask_b32_e32 v17, v17, v18, vcc
	v_sqrt_f32_e32 v18, v17
	s_nop 0
	v_add_u32_e32 v19, -1, v18
	v_fma_f32 v20, -v19, v18, v17
	v_cmp_ge_f32_e64 s[4:5], 0, v20
	v_add_u32_e32 v20, 1, v18
	s_nop 0
	v_cndmask_b32_e64 v19, v18, v19, s[4:5]
	v_fma_f32 v18, -v20, v18, v17
	v_cmp_lt_f32_e64 s[4:5], 0, v18
	s_nop 1
	v_cndmask_b32_e64 v18, v19, v20, s[4:5]
	v_mul_f32_e32 v19, 0x37800000, v18
	v_cndmask_b32_e32 v18, v18, v19, vcc
	v_cmp_class_f32_e32 vcc, v17, v202
	s_nop 1
	v_cndmask_b32_e32 v17, v18, v17, vcc
	v_div_scale_f32 v18, s[4:5], v17, v17, 1.0
	v_rcp_f32_e32 v19, v18
	s_nop 0
	v_fma_f32 v20, -v18, v19, 1.0
	v_fmac_f32_e32 v19, v20, v19
	v_div_scale_f32 v20, vcc, 1.0, v17, 1.0
	v_mul_f32_e32 v21, v20, v19
	v_fma_f32 v22, -v18, v21, v20
	v_fmac_f32_e32 v21, v22, v19
	v_fma_f32 v18, -v18, v21, v20
	v_div_fmas_f32 v18, v18, v19, v21
	v_div_fixup_f32 v18, v18, v17, 1.0
	v_pk_mul_f32 v[10:11], v[18:19], v[10:11] op_sel_hi:[0,1]
	v_pk_mul_f32 v[18:19], v[18:19], v[12:13] op_sel_hi:[0,1]
	v_cndmask_b32_e64 v17, 0, 1, s[44:45]
	v_pk_mul_f32 v[12:13], v[2:3], v[10:11]
	v_pk_mul_f32 v[10:11], v[4:5], v[18:19]
	v_cmp_ne_u32_e64 s[4:5], 1, v17
	s_andn2_b64 vcc, exec, s[44:45]
	s_cbranch_vccnz .LBB0_492
	v_ashrrev_i32_e32 v17, 6, v16
	v_cvt_f32_i32_e32 v17, v17
	v_and_b32_e32 v18, 63, v16
	v_cvt_f32_ubyte0_e32 v18, v18
	v_mul_f32_e32 v18, v15, v18
	v_mul_f32_e32 v17, v15, v17
	v_mul_f32_e32 v17, 0.15915494, v17
	v_sin_f32_e32 v19, v17
	v_cos_f32_e32 v21, v17
	v_mul_f32_e32 v17, 0.15915494, v18
	v_sin_f32_e32 v18, v17
	v_cos_f32_e32 v20, v17
	v_pk_mul_f32 v[22:23], v[18:19], v[10:11]
	s_nop 0
	v_pk_fma_f32 v[22:23], v[20:21], v[12:13], v[22:23] neg_lo:[0,0,1] neg_hi:[0,0,1]
	v_pk_mul_f32 v[12:13], v[18:19], v[12:13]
	s_nop 0
	v_pk_fma_f32 v[10:11], v[20:21], v[10:11], v[12:13]
	v_mov_b64_e32 v[12:13], v[22:23]
.LBB0_492:
	v_mul_f32_e32 v11, 0x3e38aa3b, v11
	v_cvt_pk_bf16_f32 v11, v11, s0
	v_mul_f32_e32 v13, 0x3e38aa3b, v13
	global_store_short v[8:9], v11, off offset:32
	v_mul_f32_e32 v11, 0x3e38aa3b, v12
	v_mul_f32_e32 v10, 0x3e38aa3b, v10
	v_cvt_pk_bf16_f32 v13, v13, s0
	v_cvt_pk_bf16_f32 v11, v11, s0
	v_cvt_pk_bf16_f32 v10, v10, s0
	v_add_u32_e32 v17, 4, v16
	global_store_short v[8:9], v13, off
	global_store_short v[8:9], v11, off offset:64
	global_store_short v[8:9], v10, off offset:96
	v_mad_i64_i32 v[8:9], s[6:7], v17, s21, v[6:7]
	global_load_ushort v10, v[8:9], off offset:64
	global_load_ushort v11, v[8:9], off
	global_load_ushort v12, v[8:9], off offset:96
	global_load_ushort v13, v[8:9], off offset:32
	s_waitcnt vmcnt(3)
	v_lshlrev_b32_e32 v10, 16, v10
	s_waitcnt vmcnt(1)
	v_lshlrev_b32_e32 v12, 16, v12
	s_waitcnt vmcnt(0)
	v_lshlrev_b32_e32 v13, 16, v13
	v_lshlrev_b32_e32 v11, 16, v11
	v_pk_mul_f32 v[18:19], v[12:13], v[12:13]
	s_nop 0
	v_pk_fma_f32 v[18:19], v[10:11], v[10:11], v[18:19]
	s_nop 0
	v_add_f32_e32 v18, v19, v18
	s_nop 1
	v_mov_b32_dpp v19, v18 quad_perm:[1,0,3,2] row_mask:0xf bank_mask:0xf
	s_waitcnt lgkmcnt(0)
	v_add_f32_e32 v18, v18, v19
	s_nop 1
	v_mov_b32_dpp v19, v18 quad_perm:[2,3,0,1] row_mask:0xf bank_mask:0xf
	s_waitcnt lgkmcnt(0)
	v_add_f32_e32 v18, v18, v19
	s_nop 1
	v_mov_b32_dpp v19, v18 row_half_mirror row_mask:0xf bank_mask:0xf
	s_waitcnt lgkmcnt(0)
	v_add_f32_e32 v18, v18, v19
	s_nop 1
	v_mov_b32_dpp v19, v18 row_ror:8 row_mask:0xf bank_mask:0xf
	s_waitcnt lgkmcnt(0)
	v_add_f32_e32 v18, v18, v19
	v_fmamk_f32 v18, v18, 0x3c800000, v193
	v_cmp_gt_f32_e32 vcc, s41, v18
	v_mul_f32_e32 v19, 0x4f800000, v18
	s_nop 0
	v_cndmask_b32_e32 v18, v18, v19, vcc
	v_sqrt_f32_e32 v19, v18
	s_nop 0
	v_add_u32_e32 v20, -1, v19
	v_fma_f32 v21, -v20, v19, v18
	v_cmp_ge_f32_e64 s[6:7], 0, v21
	v_add_u32_e32 v21, 1, v19
	s_nop 0
	v_cndmask_b32_e64 v20, v19, v20, s[6:7]
	v_fma_f32 v19, -v21, v19, v18
	v_cmp_lt_f32_e64 s[6:7], 0, v19
	s_nop 1
	v_cndmask_b32_e64 v19, v20, v21, s[6:7]
	v_mul_f32_e32 v20, 0x37800000, v19
	v_cndmask_b32_e32 v19, v19, v20, vcc
	v_cmp_class_f32_e32 vcc, v18, v202
	s_nop 1
	v_cndmask_b32_e32 v18, v19, v18, vcc
	v_div_scale_f32 v19, s[6:7], v18, v18, 1.0
	v_rcp_f32_e32 v20, v19
	s_nop 0
	v_fma_f32 v21, -v19, v20, 1.0
	v_fmac_f32_e32 v20, v21, v20
	v_div_scale_f32 v21, vcc, 1.0, v18, 1.0
	v_mul_f32_e32 v22, v21, v20
	v_fma_f32 v23, -v19, v22, v21
	v_fmac_f32_e32 v22, v23, v20
	v_fma_f32 v19, -v19, v22, v21
	v_div_fmas_f32 v19, v19, v20, v22
	v_div_fixup_f32 v18, v19, v18, 1.0
	v_pk_mul_f32 v[10:11], v[18:19], v[10:11] op_sel_hi:[0,1]
	v_pk_mul_f32 v[18:19], v[18:19], v[12:13] op_sel_hi:[0,1]
	v_pk_mul_f32 v[12:13], v[2:3], v[10:11]
	v_pk_mul_f32 v[10:11], v[4:5], v[18:19]
	s_and_b64 vcc, exec, s[4:5]
	s_cbranch_vccnz .LBB0_494
	v_ashrrev_i32_e32 v18, 6, v17
	v_cvt_f32_i32_e32 v18, v18
	v_and_b32_e32 v17, 63, v17
	v_cvt_f32_ubyte0_e32 v17, v17
	v_mul_f32_e32 v17, v15, v17
	v_mul_f32_e32 v18, v15, v18
	v_mul_f32_e32 v18, 0.15915494, v18
	v_mul_f32_e32 v17, 0.15915494, v17
	v_sin_f32_e32 v19, v18
	v_cos_f32_e32 v21, v18
	v_sin_f32_e32 v18, v17
	v_cos_f32_e32 v20, v17
	v_pk_mul_f32 v[22:23], v[18:19], v[10:11]
	s_nop 0
	v_pk_fma_f32 v[22:23], v[20:21], v[12:13], v[22:23] neg_lo:[0,0,1] neg_hi:[0,0,1]
	v_pk_mul_f32 v[12:13], v[18:19], v[12:13]
	s_nop 0
	v_pk_fma_f32 v[10:11], v[20:21], v[10:11], v[12:13]
	v_mov_b64_e32 v[12:13], v[22:23]
; __device__ __forceinline__ float bf2f(unsigned v) { return __uint_as_float(v << 16); }
; __device__ __forceinline__ unsigned f2bf(float f) { return pk2(f, 0.f) & 0xffffu; }
; template <int K> __device__ __forceinline__ float swz_xor(float v) { return __uint_as_float((unsigned)__builtin_amdgcn_ds_swizzle((int)__float_as_uint(v), (K << 10) | 0x1f)); }
; __device__ __forceinline__ void prep_qk(bf16_t* PB, int tok0, int col, const float* gain, bool rope, float outscale, int lane) {
;     ...
;     for (int pass = 0; pass < 16; ++pass) {
;         const int tok = tok0 + pass * 4 + tq;
;         bf16_t* p = PB + (size_t)tok * INW + col + i;
;         float x0 = bf2f(p[0]), x1 = bf2f(p[16]), x2 = bf2f(p[32]), x3 = bf2f(p[48]);
;         float ss = (x0 * x0 + x1 * x1) + (x2 * x2 + x3 * x3);
;         ss += swz_xor<1>(ss); ss += swz_xor<2>(ss); ss += swz_xor<4>(ss); ss += swz_xor<8>(ss);
;         const float r = 1.0f / sqrtf(ss * (1.f / 64.f) + EPSN);
;         x0 = x0 * r * g0; x1 = x1 * r * g1; x2 = x2 * r * g2; x3 = x3 * r * g3;
;         if (rope) {
;             const float ar = (float)(tok >> 6) * inv, ac = (float)(tok & 63) * inv;
;             const float sr = __sinf(ar), cr = __cosf(ar), sc = __sinf(ac), cc = __cosf(ac);
;             const float a0 = x0, b0 = x1; x0 = a0 * cr - b0 * sr; x1 = b0 * cr + a0 * sr;
;             const float a1 = x2, b1 = x3; x2 = a1 * cc - b1 * sc; x3 = b1 * cc + a1 * sc;
;         }
;         p[0] = (bf16_t)f2bf(x0 * outscale); p[16] = (bf16_t)f2bf(x1 * outscale); p[32] = (bf16_t)f2bf(x2 * outscale); p[48] = (bf16_t)f2bf(x3 * outscale);
;     }
.LBB0_494:
	v_mul_f32_e32 v11, 0x3e38aa3b, v11
	v_cvt_pk_bf16_f32 v11, v11, s0
	v_mul_f32_e32 v13, 0x3e38aa3b, v13
	global_store_short v[8:9], v11, off offset:32
	v_mul_f32_e32 v11, 0x3e38aa3b, v12
	v_mul_f32_e32 v10, 0x3e38aa3b, v10
	v_cvt_pk_bf16_f32 v13, v13, s0
	v_cvt_pk_bf16_f32 v11, v11, s0
	v_cvt_pk_bf16_f32 v10, v10, s0
	v_add_u32_e32 v17, 8, v16
	global_store_short v[8:9], v13, off
	global_store_short v[8:9], v11, off offset:64
	global_store_short v[8:9], v10, off offset:96
	v_mad_i64_i32 v[8:9], s[6:7], v17, s21, v[6:7]
	global_load_ushort v10, v[8:9], off offset:64
	global_load_ushort v11, v[8:9], off
	global_load_ushort v12, v[8:9], off offset:96
	global_load_ushort v13, v[8:9], off offset:32
	s_waitcnt vmcnt(3)
	v_lshlrev_b32_e32 v10, 16, v10
	s_waitcnt vmcnt(1)
	v_lshlrev_b32_e32 v12, 16, v12
	s_waitcnt vmcnt(0)
	v_lshlrev_b32_e32 v13, 16, v13
	v_lshlrev_b32_e32 v11, 16, v11
	v_pk_mul_f32 v[18:19], v[12:13], v[12:13]
	s_nop 0
	v_pk_fma_f32 v[18:19], v[10:11], v[10:11], v[18:19]
	s_nop 0
	v_add_f32_e32 v18, v19, v18
	s_nop 1
	v_mov_b32_dpp v19, v18 quad_perm:[1,0,3,2] row_mask:0xf bank_mask:0xf
	s_waitcnt lgkmcnt(0)
	v_add_f32_e32 v18, v18, v19
	s_nop 1
	v_mov_b32_dpp v19, v18 quad_perm:[2,3,0,1] row_mask:0xf bank_mask:0xf
	s_waitcnt lgkmcnt(0)
	v_add_f32_e32 v18, v18, v19
	s_nop 1
	v_mov_b32_dpp v19, v18 row_half_mirror row_mask:0xf bank_mask:0xf
	s_waitcnt lgkmcnt(0)
	v_add_f32_e32 v18, v18, v19
	s_nop 1
	v_mov_b32_dpp v19, v18 row_ror:8 row_mask:0xf bank_mask:0xf
	s_waitcnt lgkmcnt(0)
	v_add_f32_e32 v18, v18, v19
	v_fmamk_f32 v18, v18, 0x3c800000, v193
	v_cmp_gt_f32_e32 vcc, s41, v18
	v_mul_f32_e32 v19, 0x4f800000, v18
	s_nop 0
	v_cndmask_b32_e32 v18, v18, v19, vcc
	v_sqrt_f32_e32 v19, v18
	s_nop 0
	v_add_u32_e32 v20, -1, v19
	v_fma_f32 v21, -v20, v19, v18
	v_cmp_ge_f32_e64 s[6:7], 0, v21
	v_add_u32_e32 v21, 1, v19
	s_nop 0
	v_cndmask_b32_e64 v20, v19, v20, s[6:7]
	v_fma_f32 v19, -v21, v19, v18
	v_cmp_lt_f32_e64 s[6:7], 0, v19
	s_nop 1
	v_cndmask_b32_e64 v19, v20, v21, s[6:7]
	v_mul_f32_e32 v20, 0x37800000, v19
	v_cndmask_b32_e32 v19, v19, v20, vcc
	v_cmp_class_f32_e32 vcc, v18, v202
	s_nop 1
	v_cndmask_b32_e32 v18, v19, v18, vcc
	v_div_scale_f32 v19, s[6:7], v18, v18, 1.0
	v_rcp_f32_e32 v20, v19
	s_nop 0
	v_fma_f32 v21, -v19, v20, 1.0
	v_fmac_f32_e32 v20, v21, v20
	v_div_scale_f32 v21, vcc, 1.0, v18, 1.0
	v_mul_f32_e32 v22, v21, v20
	v_fma_f32 v23, -v19, v22, v21
	v_fmac_f32_e32 v22, v23, v20
	v_fma_f32 v19, -v19, v22, v21
	v_div_fmas_f32 v19, v19, v20, v22
	v_div_fixup_f32 v18, v19, v18, 1.0
	v_pk_mul_f32 v[10:11], v[18:19], v[10:11] op_sel_hi:[0,1]
	v_pk_mul_f32 v[18:19], v[18:19], v[12:13] op_sel_hi:[0,1]
	v_pk_mul_f32 v[12:13], v[2:3], v[10:11]
	v_pk_mul_f32 v[10:11], v[4:5], v[18:19]
	s_and_b64 vcc, exec, s[4:5]
	s_cbranch_vccnz .LBB0_496
	v_ashrrev_i32_e32 v18, 6, v17
	v_cvt_f32_i32_e32 v18, v18
	v_and_b32_e32 v17, 63, v17
	v_cvt_f32_ubyte0_e32 v17, v17
	v_mul_f32_e32 v17, v15, v17
	v_mul_f32_e32 v18, v15, v18
	v_mul_f32_e32 v18, 0.15915494, v18
	v_mul_f32_e32 v17, 0.15915494, v17
	v_sin_f32_e32 v19, v18
	v_cos_f32_e32 v21, v18
	v_sin_f32_e32 v18, v17
	v_cos_f32_e32 v20, v17
	v_pk_mul_f32 v[22:23], v[18:19], v[10:11]
	s_nop 0
	v_pk_fma_f32 v[22:23], v[20:21], v[12:13], v[22:23] neg_lo:[0,0,1] neg_hi:[0,0,1]
	v_pk_mul_f32 v[12:13], v[18:19], v[12:13]
	s_nop 0
	v_pk_fma_f32 v[10:11], v[20:21], v[10:11], v[12:13]
	v_mov_b64_e32 v[12:13], v[22:23]
.LBB0_496:
	v_mul_f32_e32 v11, 0x3e38aa3b, v11
	v_cvt_pk_bf16_f32 v11, v11, s0
	v_mul_f32_e32 v13, 0x3e38aa3b, v13
	global_store_short v[8:9], v11, off offset:32
	v_mul_f32_e32 v11, 0x3e38aa3b, v12
	v_mul_f32_e32 v10, 0x3e38aa3b, v10
	v_cvt_pk_bf16_f32 v13, v13, s0
	v_cvt_pk_bf16_f32 v11, v11, s0
	v_cvt_pk_bf16_f32 v10, v10, s0
	v_add_u32_e32 v16, 12, v16
	global_store_short v[8:9], v13, off
	global_store_short v[8:9], v11, off offset:64
	global_store_short v[8:9], v10, off offset:96
	v_mad_i64_i32 v[8:9], s[6:7], v16, s21, v[6:7]
	global_load_ushort v10, v[8:9], off offset:64
	global_load_ushort v11, v[8:9], off
	global_load_ushort v12, v[8:9], off offset:96
	global_load_ushort v13, v[8:9], off offset:32
	s_waitcnt vmcnt(3)
	v_lshlrev_b32_e32 v10, 16, v10
	s_waitcnt vmcnt(1)
	v_lshlrev_b32_e32 v12, 16, v12
	s_waitcnt vmcnt(0)
	v_lshlrev_b32_e32 v13, 16, v13
	v_lshlrev_b32_e32 v11, 16, v11
	v_pk_mul_f32 v[18:19], v[12:13], v[12:13]
	s_nop 0
	v_pk_fma_f32 v[18:19], v[10:11], v[10:11], v[18:19]
	s_nop 0
	v_add_f32_e32 v17, v19, v18
	s_nop 1
	v_mov_b32_dpp v18, v17 quad_perm:[1,0,3,2] row_mask:0xf bank_mask:0xf
	s_waitcnt lgkmcnt(0)
	v_add_f32_e32 v17, v17, v18
	s_nop 1
	v_mov_b32_dpp v18, v17 quad_perm:[2,3,0,1] row_mask:0xf bank_mask:0xf
	s_waitcnt lgkmcnt(0)
	v_add_f32_e32 v17, v17, v18
	s_nop 1
	v_mov_b32_dpp v18, v17 row_half_mirror row_mask:0xf bank_mask:0xf
	s_waitcnt lgkmcnt(0)
	v_add_f32_e32 v17, v17, v18
	s_nop 1
	v_mov_b32_dpp v18, v17 row_ror:8 row_mask:0xf bank_mask:0xf
	s_waitcnt lgkmcnt(0)
	v_add_f32_e32 v17, v17, v18
	v_fmamk_f32 v17, v17, 0x3c800000, v193
	v_cmp_gt_f32_e32 vcc, s41, v17
	v_mul_f32_e32 v18, 0x4f800000, v17
	s_nop 0
	v_cndmask_b32_e32 v17, v17, v18, vcc
	v_sqrt_f32_e32 v18, v17
	s_nop 0
	v_add_u32_e32 v19, -1, v18
	v_fma_f32 v20, -v19, v18, v17
	v_cmp_ge_f32_e64 s[6:7], 0, v20
	v_add_u32_e32 v20, 1, v18
	s_nop 0
	v_cndmask_b32_e64 v19, v18, v19, s[6:7]
	v_fma_f32 v18, -v20, v18, v17
	v_cmp_lt_f32_e64 s[6:7], 0, v18
	s_nop 1
	v_cndmask_b32_e64 v18, v19, v20, s[6:7]
	v_mul_f32_e32 v19, 0x37800000, v18
	v_cndmask_b32_e32 v18, v18, v19, vcc
	v_cmp_class_f32_e32 vcc, v17, v202
	s_nop 1
	v_cndmask_b32_e32 v17, v18, v17, vcc
	v_div_scale_f32 v18, s[6:7], v17, v17, 1.0
	v_rcp_f32_e32 v19, v18
	s_nop 0
	v_fma_f32 v20, -v18, v19, 1.0
	v_fmac_f32_e32 v19, v20, v19
	v_div_scale_f32 v20, vcc, 1.0, v17, 1.0
	v_mul_f32_e32 v21, v20, v19
	v_fma_f32 v22, -v18, v21, v20
	v_fmac_f32_e32 v21, v22, v19
	v_fma_f32 v18, -v18, v21, v20
	v_div_fmas_f32 v18, v18, v19, v21
	v_div_fixup_f32 v18, v18, v17, 1.0
	v_pk_mul_f32 v[10:11], v[18:19], v[10:11] op_sel_hi:[0,1]
	v_pk_mul_f32 v[18:19], v[18:19], v[12:13] op_sel_hi:[0,1]
	v_pk_mul_f32 v[12:13], v[2:3], v[10:11]
	v_pk_mul_f32 v[10:11], v[4:5], v[18:19]
	s_and_b64 vcc, exec, s[4:5]
	s_cbranch_vccnz .LBB0_489
	v_ashrrev_i32_e32 v17, 6, v16
	v_cvt_f32_i32_e32 v17, v17
	v_and_b32_e32 v16, 63, v16
	v_cvt_f32_ubyte0_e32 v16, v16
	v_mul_f32_e32 v16, v15, v16
	v_mul_f32_e32 v17, v15, v17
	v_mul_f32_e32 v18, 0.15915494, v17
	v_sin_f32_e32 v17, v18
	v_cos_f32_e32 v19, v18
	v_mul_f32_e32 v18, 0.15915494, v16
	v_sin_f32_e32 v16, v18
	v_cos_f32_e32 v18, v18
	v_pk_mul_f32 v[20:21], v[16:17], v[10:11]
	s_nop 0
	v_pk_fma_f32 v[20:21], v[18:19], v[12:13], v[20:21] neg_lo:[0,0,1] neg_hi:[0,0,1]
	v_pk_mul_f32 v[12:13], v[16:17], v[12:13]
	s_nop 0
	v_pk_fma_f32 v[10:11], v[18:19], v[10:11], v[12:13]
	v_mov_b64_e32 v[12:13], v[20:21]
	s_branch .LBB0_489

; __device__ __forceinline__ void norm_phase(const Ctx& F, float* X, const float* gw, const float* modl, int ish, int isc, bf16_t* XN, const float* part, int nsplit) {
;     for (int row = SEQ + F.gw; row < NTOK; row += F.ngw) {
;         const float* mv = modl + NMODV;
;         f32x4* xr = (f32x4*)(X + (size_t)row * D) + F.lane;
;         f32x4 v[4];
; #pragma unroll
;         for (int j = 0; j < 4; ++j) v[j] = xr[64 * j];
;         const f32x4* pr = (const f32x4*)(part + (size_t)(row - SEQ) * D) + F.lane;
;         int s = 0;
;         for (; s + 4 <= nsplit; s += 4) {
;             f32x4 t[4][4];
; #pragma unroll
;             for (int u = 0; u < 4; ++u)
; #pragma unroll
;                 for (int j = 0; j < 4; ++j) t[u][j] = pr[(size_t)(s + u) * (256 * D / 4) + 64 * j];
; #pragma unroll
;             for (int u = 0; u < 4; ++u)
; #pragma unroll
;                 for (int j = 0; j < 4; ++j) v[j] += t[u][j];
;         }
;         for (; s < nsplit; ++s)
; #pragma unroll
;             for (int j = 0; j < 4; ++j) v[j] += pr[(size_t)s * (256 * D / 4) + 64 * j];
.LBB0_591:
	v_lshl_add_u64 v[12:13], s[14:15], 0, v[46:47]
	v_add_co_u32_e32 v48, vcc, 0xcb48000, v12
	v_lshl_add_u64 v[10:11], s[14:15], 0, v[42:43]
	s_nop 0
	v_addc_co_u32_e32 v49, vcc, 0, v13, vcc
	v_add_co_u32_e32 v50, vcc, 0x2355a000, v10
	global_load_dwordx4 v[2:5], v[48:49], off offset:1024
	s_nop 0
	v_addc_co_u32_e32 v51, vcc, 0, v11, vcc
	global_load_dwordx4 v[6:9], v[50:51], off offset:1024
	v_add_co_u32_e32 v54, vcc, 0x2365a000, v10
	s_mov_b32 s2, 0x2355b000
	s_nop 0
	v_addc_co_u32_e32 v55, vcc, 0, v11, vcc
	v_add_co_u32_e32 v56, vcc, 0x2375a000, v10
	s_add_i32 s42, s42, s58
	s_nop 0
	v_addc_co_u32_e32 v57, vcc, 0, v11, vcc
	v_add_co_u32_e32 v58, vcc, 0x2385a000, v10
	v_lshl_add_u64 v[42:43], v[42:43], 0, s[0:1]
	s_nop 0
	v_addc_co_u32_e32 v59, vcc, 0, v11, vcc
	v_add_co_u32_e32 v60, vcc, 0x2395a000, v10
	v_lshl_add_u64 v[46:47], v[46:47], 0, s[0:1]
	s_nop 0
	v_addc_co_u32_e32 v61, vcc, 0, v11, vcc
	v_add_co_u32_e32 v62, vcc, 0x23a5a000, v10
	s_cmpk_gt_i32 s42, 0x40ff
	s_nop 0
	v_addc_co_u32_e32 v63, vcc, 0, v11, vcc
	v_add_co_u32_e32 v64, vcc, 0x23b5a000, v10
	s_waitcnt vmcnt(0)
	v_pk_add_f32 v[8:9], v[4:5], v[8:9]
	v_pk_add_f32 v[6:7], v[2:3], v[6:7]
	global_load_dwordx4 v[2:5], v[54:55], off offset:1024
	v_addc_co_u32_e32 v65, vcc, 0, v11, vcc
	v_add_co_u32_e32 v66, vcc, 0x23c5a000, v10
	s_waitcnt vmcnt(0)
	v_pk_add_f32 v[8:9], v[8:9], v[4:5]
	v_pk_add_f32 v[6:7], v[6:7], v[2:3]
	global_load_dwordx4 v[2:5], v[56:57], off offset:1024
	v_addc_co_u32_e32 v67, vcc, 0, v11, vcc
	v_add_co_u32_e32 v70, vcc, 0x23d5a000, v10
	s_waitcnt vmcnt(0)
	v_pk_add_f32 v[8:9], v[8:9], v[4:5]
	v_pk_add_f32 v[6:7], v[6:7], v[2:3]
	global_load_dwordx4 v[2:5], v[58:59], off offset:1024
	v_addc_co_u32_e32 v71, vcc, 0, v11, vcc
	v_add_co_u32_e32 v72, vcc, 0x23e5a000, v10
	s_waitcnt vmcnt(0)
	v_pk_add_f32 v[8:9], v[8:9], v[4:5]
	v_pk_add_f32 v[6:7], v[6:7], v[2:3]
	global_load_dwordx4 v[2:5], v[60:61], off offset:1024
	v_addc_co_u32_e32 v73, vcc, 0, v11, vcc
	v_add_co_u32_e32 v74, vcc, 0x23f5a000, v10
	s_waitcnt vmcnt(0)
	v_pk_add_f32 v[8:9], v[8:9], v[4:5]
	v_pk_add_f32 v[6:7], v[6:7], v[2:3]
	global_load_dwordx4 v[2:5], v[62:63], off offset:1024
	v_addc_co_u32_e32 v75, vcc, 0, v11, vcc
	s_waitcnt vmcnt(0)
	v_pk_add_f32 v[8:9], v[8:9], v[4:5]
	v_pk_add_f32 v[6:7], v[6:7], v[2:3]
	global_load_dwordx4 v[2:5], v[64:65], off offset:1024
	s_waitcnt vmcnt(0)
	v_pk_add_f32 v[8:9], v[8:9], v[4:5]
	v_pk_add_f32 v[6:7], v[6:7], v[2:3]
	global_load_dwordx4 v[2:5], v[66:67], off offset:1024
	s_waitcnt vmcnt(0)
	v_pk_add_f32 v[8:9], v[8:9], v[4:5]
	v_pk_add_f32 v[6:7], v[6:7], v[2:3]
	global_load_dwordx4 v[2:5], v[70:71], off offset:1024
	s_waitcnt vmcnt(0)
	v_pk_add_f32 v[8:9], v[8:9], v[4:5]
	v_pk_add_f32 v[6:7], v[6:7], v[2:3]
	global_load_dwordx4 v[2:5], v[72:73], off offset:1024
	s_waitcnt vmcnt(0)
	v_pk_add_f32 v[8:9], v[8:9], v[4:5]
	v_pk_add_f32 v[6:7], v[6:7], v[2:3]
	global_load_dwordx4 v[2:5], v[74:75], off offset:1024
	s_waitcnt vmcnt(0)
	v_pk_add_f32 v[16:17], v[8:9], v[4:5]
	v_pk_add_f32 v[14:15], v[6:7], v[2:3]
	global_load_dwordx4 v[2:5], v[48:49], off offset:2048
	global_load_dwordx4 v[6:9], v[50:51], off offset:2048
	v_mul_f32_e32 v19, v15, v15
	v_mul_f32_e32 v21, v17, v17
	v_fmac_f32_e32 v19, v14, v14
	v_fmac_f32_e32 v21, v16, v16
	v_add_f32_e32 v19, v19, v21
	s_waitcnt vmcnt(0)
	v_pk_add_f32 v[8:9], v[4:5], v[8:9]
	v_pk_add_f32 v[6:7], v[2:3], v[6:7]
	global_load_dwordx4 v[2:5], v[54:55], off offset:2048
	s_waitcnt vmcnt(0)
	v_pk_add_f32 v[8:9], v[8:9], v[4:5]
	v_pk_add_f32 v[6:7], v[6:7], v[2:3]
	global_load_dwordx4 v[2:5], v[56:57], off offset:2048
	s_waitcnt vmcnt(0)
	v_pk_add_f32 v[8:9], v[8:9], v[4:5]
	v_pk_add_f32 v[6:7], v[6:7], v[2:3]
	global_load_dwordx4 v[2:5], v[58:59], off offset:2048
	s_waitcnt vmcnt(0)
	v_pk_add_f32 v[8:9], v[8:9], v[4:5]
	v_pk_add_f32 v[6:7], v[6:7], v[2:3]
	global_load_dwordx4 v[2:5], v[60:61], off offset:2048
	s_waitcnt vmcnt(0)
	v_pk_add_f32 v[8:9], v[8:9], v[4:5]
	v_pk_add_f32 v[6:7], v[6:7], v[2:3]
	global_load_dwordx4 v[2:5], v[62:63], off offset:2048
	s_waitcnt vmcnt(0)
	v_pk_add_f32 v[8:9], v[8:9], v[4:5]
	v_pk_add_f32 v[6:7], v[6:7], v[2:3]
	global_load_dwordx4 v[2:5], v[64:65], off offset:2048
	s_waitcnt vmcnt(0)
	v_pk_add_f32 v[8:9], v[8:9], v[4:5]
	v_pk_add_f32 v[6:7], v[6:7], v[2:3]
	global_load_dwordx4 v[2:5], v[66:67], off offset:2048
	s_waitcnt vmcnt(0)
	v_pk_add_f32 v[8:9], v[8:9], v[4:5]
	v_pk_add_f32 v[6:7], v[6:7], v[2:3]
	global_load_dwordx4 v[2:5], v[70:71], off offset:2048
	s_waitcnt vmcnt(0)
	v_pk_add_f32 v[8:9], v[8:9], v[4:5]
	v_pk_add_f32 v[6:7], v[6:7], v[2:3]
	global_load_dwordx4 v[2:5], v[72:73], off offset:2048
	s_waitcnt vmcnt(0)
	v_pk_add_f32 v[8:9], v[8:9], v[4:5]
	v_pk_add_f32 v[6:7], v[6:7], v[2:3]
	global_load_dwordx4 v[2:5], v[74:75], off offset:2048
	s_waitcnt vmcnt(0)
	v_pk_add_f32 v[8:9], v[8:9], v[4:5]
	v_pk_add_f32 v[6:7], v[6:7], v[2:3]
	global_load_dwordx4 v[2:5], v[48:49], off offset:3072
	s_nop 0
	global_load_dwordx4 v[50:53], v[50:51], off offset:3072
	v_mul_f32_e32 v21, v7, v7
	v_mul_f32_e32 v23, v9, v9
	v_fmac_f32_e32 v21, v6, v6
	v_fmac_f32_e32 v23, v8, v8
	v_add_f32_e32 v21, v21, v23
	v_add_f32_e32 v19, v19, v21
	s_waitcnt vmcnt(0)
	v_pk_add_f32 v[52:53], v[4:5], v[52:53]
	v_pk_add_f32 v[50:51], v[2:3], v[50:51]
	global_load_dwordx4 v[2:5], v[54:55], off offset:3072
	s_waitcnt vmcnt(0)
	v_pk_add_f32 v[52:53], v[52:53], v[4:5]
	v_pk_add_f32 v[50:51], v[50:51], v[2:3]
	global_load_dwordx4 v[2:5], v[56:57], off offset:3072
	s_waitcnt vmcnt(0)
	v_pk_add_f32 v[52:53], v[52:53], v[4:5]
	v_pk_add_f32 v[50:51], v[50:51], v[2:3]
	global_load_dwordx4 v[2:5], v[58:59], off offset:3072
	s_waitcnt vmcnt(0)
; __device__ __forceinline__ void norm_phase(const Ctx& F, float* X, const float* gw, const float* modl, int ish, int isc, bf16_t* XN, const float* part, int nsplit) {
;     for (int row = SEQ + F.gw; row < NTOK; row += F.ngw) {
;         const float* mv = modl + NMODV;
;         f32x4* xr = (f32x4*)(X + (size_t)row * D) + F.lane;
;         f32x4 v[4];
; #pragma unroll
;         for (int j = 0; j < 4; ++j) v[j] = xr[64 * j];
;         const f32x4* pr = (const f32x4*)(part + (size_t)(row - SEQ) * D) + F.lane;
;         int s = 0;
;         for (; s + 4 <= nsplit; s += 4) {
;             f32x4 t[4][4];
; #pragma unroll
;             for (int u = 0; u < 4; ++u)
; #pragma unroll
;                 for (int j = 0; j < 4; ++j) t[u][j] = pr[(size_t)(s + u) * (256 * D / 4) + 64 * j];
; #pragma unroll
;             for (int u = 0; u < 4; ++u)
; #pragma unroll
;                 for (int j = 0; j < 4; ++j) v[j] += t[u][j];
;         }
;         for (; s < nsplit; ++s)
; #pragma unroll
;             for (int j = 0; j < 4; ++j) v[j] += pr[(size_t)s * (256 * D / 4) + 64 * j];
;         if (nsplit > 0) {
; #pragma unroll
;             for (int j = 0; j < 4; ++j) xr[64 * j] = v[j];
;         }
;         float ss = 0.f;
; #pragma unroll
;         for (int j = 0; j < 4; ++j) ss += (v[j].x * v[j].x + v[j].y * v[j].y) + (v[j].z * v[j].z + v[j].w * v[j].w);
	v_pk_add_f32 v[52:53], v[52:53], v[4:5]
	v_pk_add_f32 v[50:51], v[50:51], v[2:3]
	global_load_dwordx4 v[2:5], v[60:61], off offset:3072
	s_waitcnt vmcnt(0)
	v_pk_add_f32 v[52:53], v[52:53], v[4:5]
	v_pk_add_f32 v[50:51], v[50:51], v[2:3]
	global_load_dwordx4 v[2:5], v[62:63], off offset:3072
	s_waitcnt vmcnt(0)
	v_pk_add_f32 v[52:53], v[52:53], v[4:5]
	v_pk_add_f32 v[50:51], v[50:51], v[2:3]
	global_load_dwordx4 v[2:5], v[64:65], off offset:3072
	s_waitcnt vmcnt(0)
	v_pk_add_f32 v[52:53], v[52:53], v[4:5]
	v_pk_add_f32 v[50:51], v[50:51], v[2:3]
	global_load_dwordx4 v[2:5], v[66:67], off offset:3072
	s_waitcnt vmcnt(0)
	v_pk_add_f32 v[52:53], v[52:53], v[4:5]
	v_pk_add_f32 v[50:51], v[50:51], v[2:3]
	global_load_dwordx4 v[2:5], v[70:71], off offset:3072
	s_waitcnt vmcnt(0)
	v_pk_add_f32 v[52:53], v[52:53], v[4:5]
	v_pk_add_f32 v[50:51], v[50:51], v[2:3]
	global_load_dwordx4 v[2:5], v[72:73], off offset:3072
	s_waitcnt vmcnt(0)
	v_pk_add_f32 v[52:53], v[52:53], v[4:5]
	v_pk_add_f32 v[50:51], v[50:51], v[2:3]
	global_load_dwordx4 v[2:5], v[74:75], off offset:3072
	s_waitcnt vmcnt(0)
	v_pk_add_f32 v[2:3], v[50:51], v[2:3]
	v_add_co_u32_e32 v50, vcc, s89, v12
	v_pk_add_f32 v[4:5], v[52:53], v[4:5]
	s_nop 0
	v_addc_co_u32_e32 v51, vcc, 0, v13, vcc
	v_add_co_u32_e32 v12, vcc, s2, v10
	global_load_dwordx4 v[52:55], v[50:51], off
	s_nop 0
	v_addc_co_u32_e32 v13, vcc, 0, v11, vcc
	global_load_dwordx4 v[56:59], v[12:13], off
	s_mov_b32 s2, 0x2365b000
	v_mul_f32_e32 v21, v3, v3
	v_mul_f32_e32 v23, v5, v5
	v_fmac_f32_e32 v21, v2, v2
	v_fmac_f32_e32 v23, v4, v4
	v_add_f32_e32 v21, v21, v23
	v_add_f32_e32 v19, v21, v19
	s_waitcnt vmcnt(0)
	v_pk_add_f32 v[56:57], v[52:53], v[56:57]
	v_add_co_u32_e32 v52, vcc, s2, v10
	v_pk_add_f32 v[12:13], v[54:55], v[58:59]
	s_nop 0
	v_addc_co_u32_e32 v53, vcc, 0, v11, vcc
	global_load_dwordx4 v[52:55], v[52:53], off
	s_mov_b32 s2, 0x2375b000
	s_waitcnt vmcnt(0)
	v_pk_add_f32 v[56:57], v[56:57], v[52:53]
	v_add_co_u32_e32 v52, vcc, s2, v10
	v_pk_add_f32 v[12:13], v[12:13], v[54:55]
	s_nop 0
	v_addc_co_u32_e32 v53, vcc, 0, v11, vcc
	global_load_dwordx4 v[52:55], v[52:53], off
	s_mov_b32 s2, 0x2385b000
	s_waitcnt vmcnt(0)
	v_pk_add_f32 v[56:57], v[56:57], v[52:53]
	v_add_co_u32_e32 v52, vcc, s2, v10
	v_pk_add_f32 v[12:13], v[12:13], v[54:55]
	s_nop 0
	v_addc_co_u32_e32 v53, vcc, 0, v11, vcc
	global_load_dwordx4 v[52:55], v[52:53], off
	s_mov_b32 s2, 0x23d5b000
	s_waitcnt vmcnt(0)
	v_pk_add_f32 v[56:57], v[56:57], v[52:53]
	v_add_co_u32_e32 v52, vcc, s5, v10
	v_pk_add_f32 v[12:13], v[12:13], v[54:55]
	s_nop 0
	v_addc_co_u32_e32 v53, vcc, 0, v11, vcc
	global_load_dwordx4 v[52:55], v[52:53], off
	s_waitcnt vmcnt(0)
	v_pk_add_f32 v[56:57], v[56:57], v[52:53]
	v_add_co_u32_e32 v52, vcc, s20, v10
	v_pk_add_f32 v[12:13], v[12:13], v[54:55]
	s_nop 0
	v_addc_co_u32_e32 v53, vcc, 0, v11, vcc
	global_load_dwordx4 v[52:55], v[52:53], off
	s_waitcnt vmcnt(0)
	v_pk_add_f32 v[56:57], v[56:57], v[52:53]
	v_add_co_u32_e32 v52, vcc, s57, v10
	v_pk_add_f32 v[12:13], v[12:13], v[54:55]
	s_nop 0
	v_addc_co_u32_e32 v53, vcc, 0, v11, vcc
	global_load_dwordx4 v[52:55], v[52:53], off
	s_waitcnt vmcnt(0)
	v_pk_add_f32 v[56:57], v[56:57], v[52:53]
	v_add_co_u32_e32 v52, vcc, s91, v10
	v_pk_add_f32 v[12:13], v[12:13], v[54:55]
	s_nop 0
	v_addc_co_u32_e32 v53, vcc, 0, v11, vcc
	global_load_dwordx4 v[52:55], v[52:53], off
	s_waitcnt vmcnt(0)
	v_pk_add_f32 v[56:57], v[56:57], v[52:53]
	v_add_co_u32_e32 v52, vcc, s2, v10
	v_pk_add_f32 v[12:13], v[12:13], v[54:55]
	s_nop 0
	v_addc_co_u32_e32 v53, vcc, 0, v11, vcc
	global_load_dwordx4 v[52:55], v[52:53], off
	s_mov_b32 s2, 0x23e5b000
	s_waitcnt vmcnt(0)
	v_pk_add_f32 v[56:57], v[56:57], v[52:53]
	v_add_co_u32_e32 v52, vcc, s2, v10
	v_pk_add_f32 v[12:13], v[12:13], v[54:55]
	s_nop 0
	v_addc_co_u32_e32 v53, vcc, 0, v11, vcc
	global_load_dwordx4 v[52:55], v[52:53], off
	s_mov_b32 s2, 0x23f5b000
	v_add_co_u32_e32 v10, vcc, s2, v10
	s_waitcnt vmcnt(0)
	v_pk_add_f32 v[54:55], v[12:13], v[54:55]
	v_addc_co_u32_e32 v11, vcc, 0, v11, vcc
	global_load_dwordx4 v[10:13], v[10:11], off
	v_pk_add_f32 v[52:53], v[56:57], v[52:53]
	s_waitcnt vmcnt(0)
; __device__ __forceinline__ unsigned pk2(float lo, float hi) { const f32x2_t v = {lo, hi}; const bf16x2_t b = __builtin_convertvector(v, bf16x2_t); return __builtin_bit_cast(unsigned, b); }
; __device__ __forceinline__ void norm_phase(const Ctx& F, float* X, const float* gw, const float* modl, int ish, int isc, bf16_t* XN, const float* part, int nsplit) {
;     ...
;         if (nsplit > 0) {
; #pragma unroll
;             for (int j = 0; j < 4; ++j) xr[64 * j] = v[j];
;         }
;         float ss = 0.f;
; #pragma unroll
;         for (int j = 0; j < 4; ++j) ss += (v[j].x * v[j].x + v[j].y * v[j].y) + (v[j].z * v[j].z + v[j].w * v[j].w);
;         const float rs = __builtin_amdgcn_rsqf(wave_sum(ss) * (1.f / D) + EPSN);
; #pragma unroll
;         for (int j = 0; j < 4; ++j) {
;             const int col = 4 * F.lane + 256 * j;
;             const f32x4 g4 = *(const f32x4*)(gw + col), sh = *(const f32x4*)(mv + ish * 1024 + col), sc = *(const f32x4*)(mv + isc * 1024 + col);
;             const f32x4 o = (v[j] * rs) * (g4 * (sc + 1.0f)) + sh;
;             u32x2 w; w.x = pk2(o.x, o.y); w.y = pk2(o.z, o.w);
;             *(u32x2*)(XN + (size_t)row * D + col) = w;
;         }
	v_pk_add_f32 v[12:13], v[54:55], v[12:13]
	v_pk_add_f32 v[10:11], v[52:53], v[10:11]
	global_store_dwordx4 v[48:49], v[14:17], off offset:1024
	global_store_dwordx4 v[48:49], v[6:9], off offset:2048
	global_store_dwordx4 v[48:49], v[2:5], off offset:3072
	global_store_dwordx4 v[50:51], v[10:13], off
	global_load_dwordx4 v[50:53], v[24:25], off
	s_nop 0
	global_load_dwordx4 v[54:57], v[26:27], off
	global_load_dwordx4 v[58:61], v[28:29], off
	v_mul_f32_e32 v21, v11, v11
	v_mul_f32_e32 v23, v13, v13
	v_fmac_f32_e32 v21, v10, v10
	v_fmac_f32_e32 v23, v12, v12
	v_add_f32_e32 v21, v21, v23
	v_add_f32_e32 v19, v21, v19
	s_nop 1
	v_mov_b32_dpp v21, v19 quad_perm:[1,0,3,2] row_mask:0xf bank_mask:0xf
	s_waitcnt lgkmcnt(0)
	v_add_f32_e32 v19, v19, v21
	s_nop 1
	v_mov_b32_dpp v21, v19 quad_perm:[2,3,0,1] row_mask:0xf bank_mask:0xf
	s_waitcnt lgkmcnt(0)
	v_add_f32_e32 v19, v19, v21
	s_nop 1
	v_mov_b32_dpp v21, v19 row_half_mirror row_mask:0xf bank_mask:0xf
	s_waitcnt lgkmcnt(0)
	v_add_f32_e32 v19, v19, v21
	s_nop 1
	v_mov_b32_dpp v21, v19 row_ror:8 row_mask:0xf bank_mask:0xf
	s_waitcnt lgkmcnt(0)
	v_add_f32_e32 v19, v19, v21
	v_mov_b32_e32 v21, v19
	s_nop 1
	v_permlane16_swap_b32_e32 v19, v21
	s_waitcnt lgkmcnt(0)
	v_add_f32_e32 v19, v19, v21
	v_mov_b32_e32 v21, v19
	s_nop 1
	v_permlane32_swap_b32_e32 v19, v21
	v_add_f32_e32 v19, v19, v21
	v_fmamk_f32 v19, v19, 0x3a800000, v193
	v_rsq_f32_e32 v48, v19
	s_waitcnt vmcnt(0)
	v_pk_add_f32 v[60:61], v[60:61], 1.0 op_sel_hi:[1,0]
	v_pk_add_f32 v[58:59], v[58:59], 1.0 op_sel_hi:[1,0]
	v_pk_mul_f32 v[14:15], v[14:15], v[48:49] op_sel_hi:[1,0]
	v_pk_mul_f32 v[16:17], v[16:17], v[48:49] op_sel_hi:[1,0]
	v_pk_mul_f32 v[52:53], v[52:53], v[60:61]
	v_pk_mul_f32 v[50:51], v[50:51], v[58:59]
	v_pk_fma_f32 v[16:17], v[52:53], v[16:17], v[56:57]
	v_pk_fma_f32 v[14:15], v[50:51], v[14:15], v[54:55]
	v_pk_mul_f32 v[6:7], v[6:7], v[48:49] op_sel_hi:[1,0]
	v_cvt_pk_bf16_f32 v14, v14, v15
	v_cvt_pk_bf16_f32 v15, v16, v17
	v_lshl_add_u64 v[16:17], s[14:15], 0, v[44:45]
	v_add_co_u32_e32 v16, vcc, s74, v16
	v_pk_mul_f32 v[8:9], v[8:9], v[48:49] op_sel_hi:[1,0]
	s_nop 0
	v_addc_co_u32_e32 v17, vcc, 0, v17, vcc
	global_store_dwordx2 v[16:17], v[14:15], off offset:1024
	global_load_dwordx4 v[50:53], v[24:25], off offset:1024
	global_load_dwordx4 v[54:57], v[30:31], off
	global_load_dwordx4 v[58:61], v[32:33], off
	v_pk_mul_f32 v[2:3], v[2:3], v[48:49] op_sel_hi:[1,0]
	v_pk_mul_f32 v[4:5], v[4:5], v[48:49] op_sel_hi:[1,0]
	v_pk_mul_f32 v[10:11], v[10:11], v[48:49] op_sel_hi:[1,0]
	v_pk_mul_f32 v[12:13], v[12:13], v[48:49] op_sel_hi:[1,0]
	v_lshl_add_u64 v[44:45], v[44:45], 0, s[54:55]
	s_waitcnt vmcnt(0)
	v_pk_add_f32 v[14:15], v[60:61], 1.0 op_sel_hi:[1,0]
	v_pk_add_f32 v[58:59], v[58:59], 1.0 op_sel_hi:[1,0]
	v_pk_mul_f32 v[14:15], v[52:53], v[14:15]
	v_pk_mul_f32 v[50:51], v[50:51], v[58:59]
	v_pk_fma_f32 v[8:9], v[8:9], v[14:15], v[56:57]
	v_pk_fma_f32 v[6:7], v[6:7], v[50:51], v[54:55]
	s_nop 0
	v_cvt_pk_bf16_f32 v6, v6, v7
	v_cvt_pk_bf16_f32 v7, v8, v9
	global_store_dwordx2 v[16:17], v[6:7], off offset:1536
	global_load_dwordx4 v[6:9], v[24:25], off offset:2048
	s_nop 0
	global_load_dwordx4 v[50:53], v[34:35], off
	global_load_dwordx4 v[54:57], v[36:37], off
	s_waitcnt vmcnt(0)
	v_pk_add_f32 v[14:15], v[56:57], 1.0 op_sel_hi:[1,0]
	v_pk_add_f32 v[54:55], v[54:55], 1.0 op_sel_hi:[1,0]
	v_pk_mul_f32 v[8:9], v[8:9], v[14:15]
	v_pk_mul_f32 v[6:7], v[6:7], v[54:55]
	v_pk_fma_f32 v[4:5], v[4:5], v[8:9], v[52:53]
	v_pk_fma_f32 v[2:3], v[2:3], v[6:7], v[50:51]
	s_nop 0
	v_cvt_pk_bf16_f32 v2, v2, v3
	v_cvt_pk_bf16_f32 v3, v4, v5
	global_store_dwordx2 v[16:17], v[2:3], off offset:2048
	global_load_dwordx4 v[2:5], v[24:25], off offset:3072
	s_nop 0
	global_load_dwordx4 v[6:9], v[38:39], off
	global_load_dwordx4 v[50:53], v[40:41], off
	s_waitcnt vmcnt(0)
	v_pk_add_f32 v[14:15], v[52:53], 1.0 op_sel_hi:[1,0]
	v_pk_add_f32 v[48:49], v[50:51], 1.0 op_sel_hi:[1,0]
	v_pk_mul_f32 v[4:5], v[4:5], v[14:15]
	v_pk_mul_f32 v[2:3], v[2:3], v[48:49]
	v_pk_fma_f32 v[4:5], v[12:13], v[4:5], v[8:9]
	v_pk_fma_f32 v[2:3], v[10:11], v[2:3], v[6:7]
	s_nop 0
	v_cvt_pk_bf16_f32 v2, v2, v3
	v_cvt_pk_bf16_f32 v3, v4, v5
	global_store_dwordx2 v[16:17], v[2:3], off offset:2560
	s_cbranch_scc0 .LBB0_591

; __device__ __forceinline__ void norm_phase(const Ctx& F, float* X, const float* gw, const float* modl, int ish, int isc, bf16_t* XN, const float* part, int nsplit) {
;     ...
;     for (int row0 = 4 * F.gw; row0 < SEQ; row0 += 4 * F.ngw) {
;         const float* mv = modl;
;         f32x4 v[4][4];
; #pragma unroll
;         for (int r = 0; r < 4; ++r) { const f32x4* xr = (const f32x4*)(X + (size_t)(row0 + r) * D) + F.lane;
; #pragma unroll
;             for (int j = 0; j < 4; ++j) v[r][j] = xr[64 * j]; }
;         float rs[4];
; #pragma unroll
;         for (int r = 0; r < 4; ++r) { float ss = 0.f;
; #pragma unroll
;             for (int j = 0; j < 4; ++j) ss += (v[r][j].x * v[r][j].x + v[r][j].y * v[r][j].y) + (v[r][j].z * v[r][j].z + v[r][j].w * v[r][j].w);
;             rs[r] = __builtin_amdgcn_rsqf(wave_sum(ss) * (1.f / D) + EPSN); }
.LBB0_594:
	v_lshl_add_u64 v[76:77], s[14:15], 0, v[68:69]
	v_add_co_u32_e64 v72, s[4:5], s74, v76
	v_lshl_add_u64 v[14:15], s[14:15], 0, v[70:71]
	s_nop 0
	v_addc_co_u32_e64 v73, s[4:5], 0, v77, s[4:5]
	v_add_co_u32_e64 v74, s[4:5], s56, v76
	v_add_co_u32_e32 v2, vcc, 0xcb48000, v14
	s_nop 0
	v_addc_co_u32_e64 v75, s[4:5], 0, v77, s[4:5]
	s_mov_b64 s[4:5], vcc
	v_add_co_u32_e32 v6, vcc, 0xcb49000, v14
	v_addc_co_u32_e64 v3, s[4:5], 0, v15, s[4:5]
	s_mov_b64 s[4:5], vcc
	global_load_dwordx4 v[78:81], v[50:51], off
	global_load_dwordx4 v[34:37], v[52:53], off
	global_load_dwordx4 v[82:85], v[54:55], off
	v_add_co_u32_e32 v10, vcc, 0xcb4a000, v14
	v_addc_co_u32_e64 v7, s[4:5], 0, v15, s[4:5]
	global_load_dwordx4 v[86:89], v[2:3], off offset:1024
	global_load_dwordx4 v[38:41], v[2:3], off offset:2048
	global_load_dwordx4 v[18:21], v[2:3], off offset:3072
	s_mov_b64 s[4:5], vcc
	global_load_dwordx4 v[2:5], v[6:7], off
	global_load_dwordx4 v[90:93], v[6:7], off offset:1024
	global_load_dwordx4 v[42:45], v[6:7], off offset:2048
	global_load_dwordx4 v[22:25], v[6:7], off offset:3072
	v_add_co_u32_e32 v16, vcc, 0xcb4b000, v14
	v_addc_co_u32_e64 v11, s[4:5], 0, v15, s[4:5]
	s_mov_b64 s[4:5], vcc
	global_load_dwordx4 v[6:9], v[10:11], off
	global_load_dwordx4 v[94:97], v[10:11], off offset:1024
	global_load_dwordx4 v[98:101], v[10:11], off offset:2048
	global_load_dwordx4 v[30:33], v[10:11], off offset:3072
	v_add_co_u32_e32 v14, vcc, 0xcb4c000, v14
	v_addc_co_u32_e64 v17, s[4:5], 0, v15, s[4:5]
	global_load_dwordx4 v[10:13], v[16:17], off
	global_load_dwordx4 v[102:105], v[16:17], off offset:1024
	global_load_dwordx4 v[46:49], v[16:17], off offset:2048
	global_load_dwordx4 v[26:29], v[16:17], off offset:3072
	v_addc_co_u32_e32 v15, vcc, 0, v15, vcc
	global_load_dwordx4 v[14:17], v[14:15], off
	s_add_i32 s42, s42, s88
	v_lshl_add_u64 v[68:69], v[68:69], 0, s[6:7]
	v_lshl_add_u64 v[70:71], v[70:71], 0, s[64:65]
	s_cmpk_gt_i32 s42, 0x3fff
	s_waitcnt vmcnt(0)
	v_pk_add_f32 v[84:85], v[84:85], 1.0 op_sel_hi:[1,0]
	v_pk_add_f32 v[82:83], v[82:83], 1.0 op_sel_hi:[1,0]
	v_pk_mul_f32 v[84:85], v[80:81], v[84:85]
	v_pk_mul_f32 v[106:107], v[78:79], v[82:83]
	v_mul_f32_e32 v0, v87, v87
	v_mul_f32_e32 v78, v89, v89
	v_mul_f32_e32 v79, v39, v39
	v_mul_f32_e32 v80, v41, v41
	v_mul_f32_e32 v81, v19, v19
	v_mul_f32_e32 v82, v21, v21
	v_fmac_f32_e32 v0, v86, v86
	v_fmac_f32_e32 v78, v88, v88
	v_fmac_f32_e32 v79, v38, v38
	v_fmac_f32_e32 v80, v40, v40
	v_fmac_f32_e32 v81, v18, v18
	v_fmac_f32_e32 v82, v20, v20
	v_mul_f32_e32 v83, v3, v3
	v_mul_f32_e32 v108, v5, v5
	v_mul_f32_e32 v109, v91, v91
	v_mul_f32_e32 v110, v93, v93
	v_mul_f32_e32 v111, v43, v43
	v_mul_f32_e32 v112, v45, v45
	v_mul_f32_e32 v113, v23, v23
	v_mul_f32_e32 v114, v25, v25
	v_add_f32_e32 v0, v0, v78
	v_add_f32_e32 v78, v79, v80
	v_add_f32_e32 v79, v81, v82
	v_fmac_f32_e32 v83, v2, v2
	v_fmac_f32_e32 v108, v4, v4
	v_fmac_f32_e32 v109, v90, v90
	v_fmac_f32_e32 v110, v92, v92
	v_fmac_f32_e32 v111, v42, v42
	v_fmac_f32_e32 v112, v44, v44
	v_fmac_f32_e32 v113, v22, v22
	v_fmac_f32_e32 v114, v24, v24
	v_mul_f32_e32 v80, v7, v7
	v_mul_f32_e32 v81, v9, v9
	v_mul_f32_e32 v82, v95, v95
	v_mul_f32_e32 v115, v97, v97
	v_mul_f32_e32 v116, v99, v99
	v_mul_f32_e32 v117, v101, v101
	v_mul_f32_e32 v118, v31, v31
	v_mul_f32_e32 v119, v33, v33
	v_add_f32_e32 v0, v0, v78
	v_add_f32_e32 v78, v83, v108
	v_add_f32_e32 v83, v109, v110
	v_add_f32_e32 v108, v111, v112
	v_add_f32_e32 v109, v113, v114
	v_fmac_f32_e32 v80, v6, v6
	v_fmac_f32_e32 v81, v8, v8
	v_fmac_f32_e32 v82, v94, v94
	v_fmac_f32_e32 v115, v96, v96
	v_fmac_f32_e32 v116, v98, v98
	v_fmac_f32_e32 v117, v100, v100
	v_mul_f32_e32 v112, v103, v103
	v_mul_f32_e32 v113, v105, v105
	v_mul_f32_e32 v114, v47, v47
	v_mul_f32_e32 v120, v49, v49
	v_fmac_f32_e32 v118, v30, v30
	v_fmac_f32_e32 v119, v32, v32
	v_mul_f32_e32 v110, v11, v11
	v_mul_f32_e32 v111, v13, v13
	v_mul_f32_e32 v121, v27, v27
	v_mul_f32_e32 v122, v29, v29
	v_add_f32_e32 v0, v0, v79
	v_add_f32_e32 v79, v83, v108
	v_add_f32_e32 v80, v80, v81
	v_add_f32_e32 v81, v82, v115
	v_add_f32_e32 v82, v116, v117
	v_fmac_f32_e32 v112, v102, v102
	v_fmac_f32_e32 v113, v104, v104
	v_fmac_f32_e32 v114, v46, v46
	v_fmac_f32_e32 v120, v48, v48
	v_add_f32_e32 v83, v118, v119
	v_fmac_f32_e32 v110, v10, v10
	v_fmac_f32_e32 v111, v12, v12
	v_fmac_f32_e32 v121, v26, v26
	v_fmac_f32_e32 v122, v28, v28
	v_mul_f32_e32 v108, v15, v15
	v_mul_f32_e32 v115, v17, v17
	v_add_f32_e32 v0, v0, v78
	v_add_f32_e32 v78, v79, v109
	v_add_f32_e32 v79, v81, v82
	v_add_f32_e32 v82, v112, v113
	v_add_f32_e32 v109, v114, v120
	v_add_f32_e32 v81, v110, v111
	v_add_f32_e32 v110, v121, v122
	v_fmac_f32_e32 v108, v14, v14
	v_fmac_f32_e32 v115, v16, v16
	s_nop 1
	v_mov_b32_dpp v111, v0 quad_perm:[1,0,3,2] row_mask:0xf bank_mask:0xf
	v_add_f32_e32 v78, v78, v80
	v_add_f32_e32 v79, v79, v83
	v_add_f32_e32 v80, v82, v109
	v_add_f32_e32 v82, v108, v115
	s_nop 1
	v_mov_b32_dpp v83, v78 quad_perm:[1,0,3,2] row_mask:0xf bank_mask:0xf
	v_add_f32_e32 v79, v79, v81
	v_add_f32_e32 v80, v80, v110
	s_nop 1
	v_mov_b32_dpp v81, v79 quad_perm:[1,0,3,2] row_mask:0xf bank_mask:0xf
	v_add_f32_e32 v80, v80, v82
	s_nop 1
	v_mov_b32_dpp v82, v80 quad_perm:[1,0,3,2] row_mask:0xf bank_mask:0xf
	s_waitcnt lgkmcnt(3)
	v_add_f32_e32 v0, v0, v111
	s_nop 1
	v_mov_b32_dpp v108, v0 quad_perm:[2,3,0,1] row_mask:0xf bank_mask:0xf
	s_waitcnt lgkmcnt(3)
	v_add_f32_e32 v78, v78, v83
	s_nop 1
	v_mov_b32_dpp v83, v78 quad_perm:[2,3,0,1] row_mask:0xf bank_mask:0xf
	s_waitcnt lgkmcnt(3)
	v_add_f32_e32 v79, v79, v81
	s_nop 1
	v_mov_b32_dpp v81, v79 quad_perm:[2,3,0,1] row_mask:0xf bank_mask:0xf
	s_waitcnt lgkmcnt(3)
; __device__ __forceinline__ unsigned pk2(float lo, float hi) { const f32x2_t v = {lo, hi}; const bf16x2_t b = __builtin_convertvector(v, bf16x2_t); return __builtin_bit_cast(unsigned, b); }
; __device__ __forceinline__ void norm_phase(const Ctx& F, float* X, const float* gw, const float* modl, int ish, int isc, bf16_t* XN, const float* part, int nsplit) {
;     ...
;         for (int r = 0; r < 4; ++r) { float ss = 0.f;
; #pragma unroll
;             for (int j = 0; j < 4; ++j) ss += (v[r][j].x * v[r][j].x + v[r][j].y * v[r][j].y) + (v[r][j].z * v[r][j].z + v[r][j].w * v[r][j].w);
;             rs[r] = __builtin_amdgcn_rsqf(wave_sum(ss) * (1.f / D) + EPSN); }
; #pragma unroll
;         for (int j = 0; j < 4; ++j) {
;             const int col = 4 * F.lane + 256 * j;
;             const f32x4 g4 = *(const f32x4*)(gw + col), sh = *(const f32x4*)(mv + ish * 1024 + col), sc = *(const f32x4*)(mv + isc * 1024 + col);
;             const f32x4 gs = g4 * (sc + 1.0f);
; #pragma unroll
;             for (int r = 0; r < 4; ++r) {
;                 const f32x4 o = (v[r][j] * rs[r]) * gs + sh;
;                 u32x2 w; w.x = pk2(o.x, o.y); w.y = pk2(o.z, o.w);
;                 *(u32x2*)(XN + (size_t)(row0 + r) * D + col) = w;
	v_add_f32_e32 v80, v80, v82
	s_nop 1
	v_mov_b32_dpp v82, v80 quad_perm:[2,3,0,1] row_mask:0xf bank_mask:0xf
	s_waitcnt lgkmcnt(3)
	v_add_f32_e32 v0, v0, v108
	s_nop 1
	v_mov_b32_dpp v108, v0 row_half_mirror row_mask:0xf bank_mask:0xf
	s_waitcnt lgkmcnt(3)
	v_add_f32_e32 v78, v78, v83
	s_nop 1
	v_mov_b32_dpp v83, v78 row_half_mirror row_mask:0xf bank_mask:0xf
	s_waitcnt lgkmcnt(3)
	v_add_f32_e32 v79, v79, v81
	s_nop 1
	v_mov_b32_dpp v81, v79 row_half_mirror row_mask:0xf bank_mask:0xf
	s_waitcnt lgkmcnt(3)
	v_add_f32_e32 v80, v80, v82
	s_nop 1
	v_mov_b32_dpp v82, v80 row_half_mirror row_mask:0xf bank_mask:0xf
	s_waitcnt lgkmcnt(3)
	v_add_f32_e32 v0, v0, v108
	s_nop 1
	v_mov_b32_dpp v108, v0 row_ror:8 row_mask:0xf bank_mask:0xf
	s_waitcnt lgkmcnt(3)
	v_add_f32_e32 v78, v78, v83
	s_nop 1
	v_mov_b32_dpp v83, v78 row_ror:8 row_mask:0xf bank_mask:0xf
	s_waitcnt lgkmcnt(3)
	v_add_f32_e32 v79, v79, v81
	s_nop 1
	v_mov_b32_dpp v81, v79 row_ror:8 row_mask:0xf bank_mask:0xf
	s_waitcnt lgkmcnt(3)
	v_add_f32_e32 v80, v80, v82
	s_nop 1
	v_mov_b32_dpp v82, v80 row_ror:8 row_mask:0xf bank_mask:0xf
	s_waitcnt lgkmcnt(3)
	v_add_f32_e32 v0, v0, v108
	v_mov_b32_e32 v108, v0
	s_nop 1
	v_permlane16_swap_b32_e32 v0, v108
	s_waitcnt lgkmcnt(3)
	v_add_f32_e32 v78, v78, v83
	v_mov_b32_e32 v83, v78
	s_nop 1
	v_permlane16_swap_b32_e32 v78, v83
	s_waitcnt lgkmcnt(3)
	v_add_f32_e32 v79, v79, v81
	v_mov_b32_e32 v81, v79
	s_nop 1
	v_permlane16_swap_b32_e32 v79, v81
	s_waitcnt lgkmcnt(3)
	v_add_f32_e32 v80, v80, v82
	v_mov_b32_e32 v82, v80
	s_nop 1
	v_permlane16_swap_b32_e32 v80, v82
	s_waitcnt lgkmcnt(3)
	v_add_f32_e32 v0, v0, v108
	v_mov_b32_e32 v108, v0
	s_waitcnt lgkmcnt(2)
	v_add_f32_e32 v78, v78, v83
	v_permlane32_swap_b32_e32 v0, v108
	v_mov_b32_e32 v83, v78
	s_waitcnt lgkmcnt(1)
	v_add_f32_e32 v79, v79, v81
	v_add_f32_e32 v0, v0, v108
	v_permlane32_swap_b32_e32 v78, v83
	v_mov_b32_e32 v81, v79
	s_waitcnt lgkmcnt(0)
	v_add_f32_e32 v80, v80, v82
	v_fmamk_f32 v0, v0, 0x3a800000, v193
	v_add_f32_e32 v78, v78, v83
	v_permlane32_swap_b32_e32 v79, v81
	v_mov_b32_e32 v82, v80
	v_rsq_f32_e32 v0, v0
	v_fmamk_f32 v78, v78, 0x3a800000, v193
	v_add_f32_e32 v79, v79, v81
	v_permlane32_swap_b32_e32 v80, v82
	v_rsq_f32_e32 v78, v78
	v_fmamk_f32 v79, v79, 0x3a800000, v193
	v_add_f32_e32 v81, v80, v82
	v_rsq_f32_e32 v80, v79
	v_fmamk_f32 v79, v81, 0x3a800000, v193
	v_rsq_f32_e32 v82, v79
	v_pk_mul_f32 v[86:87], v[86:87], v[0:1] op_sel_hi:[1,0]
	v_pk_mul_f32 v[88:89], v[88:89], v[0:1] op_sel_hi:[1,0]
	v_pk_fma_f32 v[86:87], v[86:87], v[106:107], v[34:35]
	v_pk_fma_f32 v[88:89], v[88:89], v[84:85], v[36:37]
	v_pk_mul_f32 v[90:91], v[90:91], v[78:79] op_sel_hi:[1,0]
	v_pk_mul_f32 v[92:93], v[92:93], v[78:79] op_sel_hi:[1,0]
	v_cvt_pk_bf16_f32 v86, v86, v87
	v_cvt_pk_bf16_f32 v87, v88, v89
	v_pk_fma_f32 v[88:89], v[92:93], v[84:85], v[36:37]
	v_pk_fma_f32 v[90:91], v[90:91], v[106:107], v[34:35]
	v_pk_mul_f32 v[92:93], v[94:95], v[80:81] op_sel_hi:[1,0]
	v_pk_mul_f32 v[94:95], v[96:97], v[80:81] op_sel_hi:[1,0]
	global_store_dwordx2 v[72:73], v[86:87], off offset:1024
	v_cvt_pk_bf16_f32 v86, v90, v91
	v_cvt_pk_bf16_f32 v87, v88, v89
	v_pk_fma_f32 v[88:89], v[94:95], v[84:85], v[36:37]
	v_pk_fma_f32 v[90:91], v[92:93], v[106:107], v[34:35]
	v_pk_mul_f32 v[92:93], v[102:103], v[82:83] op_sel_hi:[1,0]
	v_pk_mul_f32 v[94:95], v[104:105], v[82:83] op_sel_hi:[1,0]
	v_pk_fma_f32 v[34:35], v[106:107], v[92:93], v[34:35]
	v_pk_fma_f32 v[36:37], v[84:85], v[94:95], v[36:37]
	global_store_dwordx2 v[72:73], v[86:87], off offset:3072
	v_cvt_pk_bf16_f32 v86, v90, v91
	v_cvt_pk_bf16_f32 v87, v88, v89
	v_cvt_pk_bf16_f32 v34, v34, v35
	v_cvt_pk_bf16_f32 v35, v36, v37
	global_store_dwordx2 v[74:75], v[86:87], off offset:1024
	global_store_dwordx2 v[74:75], v[34:35], off offset:3072
	global_load_dwordx4 v[34:37], v[58:59], off
	s_nop 0
	global_load_dwordx4 v[84:87], v[50:51], off offset:1024
	global_load_dwordx4 v[88:91], v[56:57], off
	v_pk_mul_f32 v[38:39], v[38:39], v[0:1] op_sel_hi:[1,0]
	v_pk_mul_f32 v[40:41], v[40:41], v[0:1] op_sel_hi:[1,0]
	v_pk_mul_f32 v[42:43], v[42:43], v[78:79] op_sel_hi:[1,0]
	v_pk_mul_f32 v[44:45], v[44:45], v[78:79] op_sel_hi:[1,0]
	v_pk_mul_f32 v[92:93], v[98:99], v[80:81] op_sel_hi:[1,0]
	v_pk_mul_f32 v[94:95], v[100:101], v[80:81] op_sel_hi:[1,0]
	v_pk_mul_f32 v[46:47], v[46:47], v[82:83] op_sel_hi:[1,0]
	v_pk_mul_f32 v[48:49], v[48:49], v[82:83] op_sel_hi:[1,0]
	v_pk_mul_f32 v[18:19], v[18:19], v[0:1] op_sel_hi:[1,0]
	v_pk_mul_f32 v[20:21], v[20:21], v[0:1] op_sel_hi:[1,0]
	v_pk_mul_f32 v[22:23], v[22:23], v[78:79] op_sel_hi:[1,0]
	v_pk_mul_f32 v[24:25], v[24:25], v[78:79] op_sel_hi:[1,0]
	v_pk_mul_f32 v[30:31], v[30:31], v[80:81] op_sel_hi:[1,0]
	v_pk_mul_f32 v[32:33], v[32:33], v[80:81] op_sel_hi:[1,0]
	v_pk_mul_f32 v[26:27], v[26:27], v[82:83] op_sel_hi:[1,0]
	v_pk_mul_f32 v[28:29], v[28:29], v[82:83] op_sel_hi:[1,0]
	v_pk_mul_f32 v[2:3], v[2:3], v[0:1] op_sel_hi:[1,0]
	v_pk_mul_f32 v[4:5], v[4:5], v[0:1] op_sel_hi:[1,0]
	v_pk_mul_f32 v[6:7], v[6:7], v[78:79] op_sel_hi:[1,0]
	v_pk_mul_f32 v[8:9], v[8:9], v[78:79] op_sel_hi:[1,0]
	v_pk_mul_f32 v[10:11], v[10:11], v[80:81] op_sel_hi:[1,0]
	v_pk_mul_f32 v[12:13], v[12:13], v[80:81] op_sel_hi:[1,0]
	v_pk_mul_f32 v[14:15], v[14:15], v[82:83] op_sel_hi:[1,0]
	v_pk_mul_f32 v[16:17], v[16:17], v[82:83] op_sel_hi:[1,0]
	s_waitcnt vmcnt(2)
; __device__ __forceinline__ unsigned pk2(float lo, float hi) { const f32x2_t v = {lo, hi}; const bf16x2_t b = __builtin_convertvector(v, bf16x2_t); return __builtin_bit_cast(unsigned, b); }
; __device__ __forceinline__ void norm_phase(const Ctx& F, float* X, const float* gw, const float* modl, int ish, int isc, bf16_t* XN, const float* part, int nsplit) {
;     ...
; #pragma unroll
;         for (int j = 0; j < 4; ++j) {
;             const int col = 4 * F.lane + 256 * j;
;             const f32x4 g4 = *(const f32x4*)(gw + col), sh = *(const f32x4*)(mv + ish * 1024 + col), sc = *(const f32x4*)(mv + isc * 1024 + col);
;             const f32x4 gs = g4 * (sc + 1.0f);
; #pragma unroll
;             for (int r = 0; r < 4; ++r) {
;                 const f32x4 o = (v[r][j] * rs[r]) * gs + sh;
;                 u32x2 w; w.x = pk2(o.x, o.y); w.y = pk2(o.z, o.w);
;                 *(u32x2*)(XN + (size_t)(row0 + r) * D + col) = w;
;             }
;         }
	v_pk_add_f32 v[36:37], v[36:37], 1.0 op_sel_hi:[1,0]
	v_pk_add_f32 v[34:35], v[34:35], 1.0 op_sel_hi:[1,0]
	s_waitcnt vmcnt(1)
	v_pk_mul_f32 v[36:37], v[86:87], v[36:37]
	v_pk_mul_f32 v[34:35], v[84:85], v[34:35]
	s_waitcnt vmcnt(0)
	v_pk_fma_f32 v[40:41], v[40:41], v[36:37], v[90:91]
	v_pk_fma_f32 v[38:39], v[38:39], v[34:35], v[88:89]
	v_pk_fma_f32 v[44:45], v[44:45], v[36:37], v[90:91]
	v_pk_fma_f32 v[42:43], v[42:43], v[34:35], v[88:89]
	v_pk_fma_f32 v[84:85], v[94:95], v[36:37], v[90:91]
	v_pk_fma_f32 v[86:87], v[92:93], v[34:35], v[88:89]
	v_pk_fma_f32 v[36:37], v[48:49], v[36:37], v[90:91]
	v_pk_fma_f32 v[34:35], v[46:47], v[34:35], v[88:89]
	v_cvt_pk_bf16_f32 v38, v38, v39
	v_cvt_pk_bf16_f32 v39, v40, v41
	v_cvt_pk_bf16_f32 v40, v42, v43
	v_cvt_pk_bf16_f32 v41, v44, v45
	v_cvt_pk_bf16_f32 v42, v86, v87
	v_cvt_pk_bf16_f32 v43, v84, v85
	v_cvt_pk_bf16_f32 v34, v34, v35
	v_cvt_pk_bf16_f32 v35, v36, v37
	global_store_dwordx2 v[72:73], v[38:39], off offset:1536
	global_store_dwordx2 v[72:73], v[40:41], off offset:3584
	global_store_dwordx2 v[74:75], v[42:43], off offset:1536
	global_store_dwordx2 v[74:75], v[34:35], off offset:3584
	global_load_dwordx4 v[34:37], v[62:63], off
	s_nop 0
	global_load_dwordx4 v[38:41], v[50:51], off offset:2048
	global_load_dwordx4 v[42:45], v[60:61], off
	v_add_co_u32_e32 v46, vcc, s29, v76
	s_waitcnt vmcnt(2)
	v_pk_add_f32 v[36:37], v[36:37], 1.0 op_sel_hi:[1,0]
	v_pk_add_f32 v[34:35], v[34:35], 1.0 op_sel_hi:[1,0]
	s_waitcnt vmcnt(1)
	v_pk_mul_f32 v[36:37], v[40:41], v[36:37]
	v_pk_mul_f32 v[34:35], v[38:39], v[34:35]
	s_waitcnt vmcnt(0)
	v_pk_fma_f32 v[20:21], v[20:21], v[36:37], v[44:45]
	v_pk_fma_f32 v[18:19], v[18:19], v[34:35], v[42:43]
	v_pk_fma_f32 v[24:25], v[24:25], v[36:37], v[44:45]
	v_pk_fma_f32 v[22:23], v[22:23], v[34:35], v[42:43]
	v_pk_fma_f32 v[32:33], v[32:33], v[36:37], v[44:45]
	v_pk_fma_f32 v[30:31], v[30:31], v[34:35], v[42:43]
	v_pk_fma_f32 v[28:29], v[28:29], v[36:37], v[44:45]
	v_pk_fma_f32 v[26:27], v[26:27], v[34:35], v[42:43]
	v_cvt_pk_bf16_f32 v18, v18, v19
	v_cvt_pk_bf16_f32 v19, v20, v21
	v_addc_co_u32_e32 v47, vcc, 0, v77, vcc
	v_cvt_pk_bf16_f32 v20, v22, v23
	v_cvt_pk_bf16_f32 v21, v24, v25
	v_cvt_pk_bf16_f32 v22, v30, v31
	v_cvt_pk_bf16_f32 v23, v32, v33
	v_cvt_pk_bf16_f32 v24, v26, v27
	v_cvt_pk_bf16_f32 v25, v28, v29
	global_store_dwordx2 v[72:73], v[18:19], off offset:2048
	global_store_dwordx2 v[46:47], v[20:21], off offset:-4096
	global_store_dwordx2 v[74:75], v[22:23], off offset:2048
	global_store_dwordx2 v[46:47], v[24:25], off
	global_load_dwordx4 v[18:21], v[66:67], off
	s_nop 0
	global_load_dwordx4 v[22:25], v[50:51], off offset:3072
	global_load_dwordx4 v[26:29], v[64:65], off
	s_waitcnt vmcnt(2)
	v_pk_add_f32 v[20:21], v[20:21], 1.0 op_sel_hi:[1,0]
	v_pk_add_f32 v[18:19], v[18:19], 1.0 op_sel_hi:[1,0]
	s_waitcnt vmcnt(1)
	v_pk_mul_f32 v[20:21], v[24:25], v[20:21]
	v_pk_mul_f32 v[18:19], v[22:23], v[18:19]
	s_waitcnt vmcnt(0)
	v_pk_fma_f32 v[4:5], v[4:5], v[20:21], v[28:29]
	v_pk_fma_f32 v[2:3], v[2:3], v[18:19], v[26:27]
	v_pk_fma_f32 v[8:9], v[8:9], v[20:21], v[28:29]
	v_pk_fma_f32 v[6:7], v[6:7], v[18:19], v[26:27]
	v_pk_fma_f32 v[12:13], v[12:13], v[20:21], v[28:29]
	v_pk_fma_f32 v[10:11], v[10:11], v[18:19], v[26:27]
	v_pk_fma_f32 v[16:17], v[16:17], v[20:21], v[28:29]
	v_pk_fma_f32 v[14:15], v[14:15], v[18:19], v[26:27]
	v_cvt_pk_bf16_f32 v2, v2, v3
	v_cvt_pk_bf16_f32 v3, v4, v5
	v_cvt_pk_bf16_f32 v4, v6, v7
	v_cvt_pk_bf16_f32 v5, v8, v9
	v_cvt_pk_bf16_f32 v6, v10, v11
	v_cvt_pk_bf16_f32 v7, v12, v13
	v_cvt_pk_bf16_f32 v8, v14, v15
	v_cvt_pk_bf16_f32 v9, v16, v17
	global_store_dwordx2 v[72:73], v[2:3], off offset:2560
	global_store_dwordx2 v[74:75], v[4:5], off offset:512
	global_store_dwordx2 v[74:75], v[6:7], off offset:2560
	global_store_dwordx2 v[46:47], v[8:9], off offset:512
	s_cbranch_scc0 .LBB0_594

; __device__ __forceinline__ unsigned pk2(float lo, float hi) { const f32x2_t v = {lo, hi}; const bf16x2_t b = __builtin_convertvector(v, bf16x2_t); return __builtin_bit_cast(unsigned, b); }
; template <int K> __device__ __forceinline__ float swz_xor(float v) { return __uint_as_float((unsigned)__builtin_amdgcn_ds_swizzle((int)__float_as_uint(v), (K << 10) | 0x1f)); }
; __device__ __forceinline__ float xor32_sum(float v) { const auto rr = __builtin_amdgcn_permlane32_swap(__float_as_uint(v), __float_as_uint(v), false, false); return __uint_as_float(rr[0]) + __uint_as_float(rr[1]); }
; __device__ __forceinline__ float wave_sum(float v) {
;     v += swz_xor<1>(v); v += swz_xor<2>(v); v += swz_xor<4>(v); v += swz_xor<8>(v); v += swz_xor<16>(v);
;     return xor32_sum(v);
; __device__ __forceinline__ void norm_phase(const Ctx& F, float* X, const float* gw, const float* modl, int ish, int isc, bf16_t* XN, const float* part, int nsplit) {
;     ...
;         float ss = 0.f;
; #pragma unroll
;         for (int j = 0; j < 4; ++j) ss += (v[j].x * v[j].x + v[j].y * v[j].y) + (v[j].z * v[j].z + v[j].w * v[j].w);
;         const float rs = __builtin_amdgcn_rsqf(wave_sum(ss) * (1.f / D) + EPSN);
; #pragma unroll
;         for (int j = 0; j < 4; ++j) {
;             const int col = 4 * F.lane + 256 * j;
;             const f32x4 g4 = *(const f32x4*)(gw + col), sh = *(const f32x4*)(mv + ish * 1024 + col), sc = *(const f32x4*)(mv + isc * 1024 + col);
;             const f32x4 o = (v[j] * rs) * (g4 * (sc + 1.0f)) + sh;
;             u32x2 w; w.x = pk2(o.x, o.y); w.y = pk2(o.z, o.w);
;             *(u32x2*)(XN + (size_t)row * D + col) = w;
;         }
.LBB0_710:
	global_load_dwordx4 v[50:53], v[32:33], off
	s_nop 0
	global_load_dwordx4 v[54:57], v[28:29], off
	global_load_dwordx4 v[58:61], v[30:31], off
	s_waitcnt vmcnt(0)
	v_mul_f32_e32 v19, v15, v15
	v_mul_f32_e32 v21, v17, v17
	v_mul_f32_e32 v23, v10, v10
	v_mul_f32_e32 v63, v12, v12
	v_mul_f32_e32 v64, v6, v6
	v_mul_f32_e32 v65, v8, v8
	v_fmac_f32_e32 v19, v14, v14
	v_fmac_f32_e32 v21, v16, v16
	v_fmac_f32_e32 v23, v11, v11
	v_fmac_f32_e32 v63, v13, v13
	v_mul_f32_e32 v66, v2, v2
	v_mul_f32_e32 v67, v4, v4
	v_fmac_f32_e32 v64, v7, v7
	v_fmac_f32_e32 v65, v9, v9
	v_add_f32_e32 v19, v19, v21
	v_add_f32_e32 v21, v63, v23
	v_fmac_f32_e32 v66, v3, v3
	v_fmac_f32_e32 v67, v5, v5
	v_add_f32_e32 v23, v65, v64
	v_add_f32_e32 v19, v19, v21
	v_add_f32_e32 v63, v67, v66
	v_add_f32_e32 v19, v23, v19
	v_add_f32_e32 v19, v63, v19
	s_nop 1
	v_mov_b32_dpp v21, v19 quad_perm:[1,0,3,2] row_mask:0xf bank_mask:0xf
	v_lshl_add_u64 v[66:67], s[44:45], 1, v[46:47]
	s_add_i32 s6, s6, s58
	s_add_i32 s42, s42, s58
	s_cmpk_gt_i32 s6, 0x40ff
	s_waitcnt lgkmcnt(0)
	v_add_f32_e32 v19, v19, v21
	s_nop 1
	v_mov_b32_dpp v21, v19 quad_perm:[2,3,0,1] row_mask:0xf bank_mask:0xf
	s_waitcnt lgkmcnt(0)
	v_add_f32_e32 v19, v19, v21
	s_nop 1
	v_mov_b32_dpp v21, v19 row_half_mirror row_mask:0xf bank_mask:0xf
	s_waitcnt lgkmcnt(0)
	v_add_f32_e32 v19, v19, v21
	s_nop 1
	v_mov_b32_dpp v21, v19 row_ror:8 row_mask:0xf bank_mask:0xf
	s_waitcnt lgkmcnt(0)
	v_add_f32_e32 v19, v19, v21
	v_mov_b32_e32 v21, v19
	s_nop 1
	v_permlane16_swap_b32_e32 v19, v21
	s_waitcnt lgkmcnt(0)
	v_add_f32_e32 v19, v19, v21
	v_mov_b32_e32 v21, v19
	s_nop 1
	v_permlane32_swap_b32_e32 v19, v21
	v_add_f32_e32 v19, v19, v21
	v_fmamk_f32 v19, v19, 0x3a800000, v193
	v_rsq_f32_e32 v64, v19
	v_pk_add_f32 v[52:53], v[52:53], 1.0 op_sel_hi:[1,0]
	v_pk_add_f32 v[50:51], v[50:51], 1.0 op_sel_hi:[1,0]
	v_pk_mul_f32 v[14:15], v[14:15], v[64:65] op_sel_hi:[1,0]
	v_pk_mul_f32 v[16:17], v[16:17], v[64:65] op_sel_hi:[1,0]
	v_pk_mul_f32 v[52:53], v[56:57], v[52:53]
	v_pk_mul_f32 v[50:51], v[54:55], v[50:51]
	v_pk_fma_f32 v[16:17], v[52:53], v[16:17], v[60:61]
	v_pk_fma_f32 v[14:15], v[50:51], v[14:15], v[58:59]
	v_pk_mul_f32 v[10:11], v[10:11], v[64:65] op_sel_hi:[1,0]
	v_cvt_pk_bf16_f32 v14, v14, v15
	v_cvt_pk_bf16_f32 v15, v16, v17
	global_store_dwordx2 v[66:67], v[14:15], off
	global_load_dwordx4 v[14:17], v[36:37], off
	s_nop 0
	global_load_dwordx4 v[50:53], v[28:29], off offset:1024
	global_load_dwordx4 v[54:57], v[34:35], off
	v_pk_mul_f32 v[12:13], v[12:13], v[64:65] op_sel_hi:[1,0]
	v_pk_mul_f32 v[6:7], v[6:7], v[64:65] op_sel_hi:[1,0]
	v_pk_mul_f32 v[8:9], v[8:9], v[64:65] op_sel_hi:[1,0]
	v_pk_mul_f32 v[2:3], v[2:3], v[64:65] op_sel_hi:[1,0]
	v_pk_mul_f32 v[4:5], v[4:5], v[64:65] op_sel_hi:[1,0]
	s_waitcnt vmcnt(2)
	v_pk_add_f32 v[16:17], v[16:17], 1.0 op_sel_hi:[1,0]
	v_pk_add_f32 v[14:15], v[14:15], 1.0 op_sel_hi:[1,0]
	s_waitcnt vmcnt(1)
	v_pk_mul_f32 v[16:17], v[52:53], v[16:17]
	v_pk_mul_f32 v[14:15], v[50:51], v[14:15]
	s_waitcnt vmcnt(0)
	v_pk_fma_f32 v[12:13], v[12:13], v[16:17], v[56:57]
	v_pk_fma_f32 v[10:11], v[10:11], v[14:15], v[54:55]
	s_nop 0
	v_cvt_pk_bf16_f32 v10, v10, v11
	v_cvt_pk_bf16_f32 v11, v12, v13
	global_store_dwordx2 v[66:67], v[10:11], off offset:512
	global_load_dwordx4 v[10:13], v[40:41], off
	s_nop 0
	global_load_dwordx4 v[14:17], v[28:29], off offset:2048
	global_load_dwordx4 v[50:53], v[38:39], off
	s_waitcnt vmcnt(2)
	v_pk_add_f32 v[12:13], v[12:13], 1.0 op_sel_hi:[1,0]
	v_pk_add_f32 v[10:11], v[10:11], 1.0 op_sel_hi:[1,0]
	s_waitcnt vmcnt(1)
	v_pk_mul_f32 v[12:13], v[16:17], v[12:13]
	v_pk_mul_f32 v[10:11], v[14:15], v[10:11]
	s_waitcnt vmcnt(0)
	v_pk_fma_f32 v[8:9], v[8:9], v[12:13], v[52:53]
	v_pk_fma_f32 v[6:7], v[6:7], v[10:11], v[50:51]
	s_nop 0
	v_cvt_pk_bf16_f32 v6, v6, v7
	v_cvt_pk_bf16_f32 v7, v8, v9
	global_store_dwordx2 v[66:67], v[6:7], off offset:1024
	global_load_dwordx4 v[6:9], v[44:45], off
	s_nop 0
	global_load_dwordx4 v[10:13], v[28:29], off offset:3072
	global_load_dwordx4 v[14:17], v[42:43], off
	s_waitcnt vmcnt(2)
	v_pk_add_f32 v[8:9], v[8:9], 1.0 op_sel_hi:[1,0]
	v_pk_add_f32 v[6:7], v[6:7], 1.0 op_sel_hi:[1,0]
	s_waitcnt vmcnt(1)
	v_pk_mul_f32 v[8:9], v[12:13], v[8:9]
	v_pk_mul_f32 v[6:7], v[10:11], v[6:7]
	s_waitcnt vmcnt(0)
	v_pk_fma_f32 v[4:5], v[4:5], v[8:9], v[16:17]
	v_pk_fma_f32 v[2:3], v[2:3], v[6:7], v[14:15]
	s_nop 0
	v_cvt_pk_bf16_f32 v2, v2, v3
	v_cvt_pk_bf16_f32 v3, v4, v5
	global_store_dwordx2 v[66:67], v[2:3], off offset:1536
	s_cbranch_scc1 .LBB0_719

; template <int K> __device__ __forceinline__ float swz_xor(float v) { return __uint_as_float((unsigned)__builtin_amdgcn_ds_swizzle((int)__float_as_uint(v), (K << 10) | 0x1f)); }
; __device__ __forceinline__ float xor32_sum(float v) { const auto rr = __builtin_amdgcn_permlane32_swap(__float_as_uint(v), __float_as_uint(v), false, false); return __uint_as_float(rr[0]) + __uint_as_float(rr[1]); }
; __device__ __forceinline__ float wave_sum(float v) {
;     v += swz_xor<1>(v); v += swz_xor<2>(v); v += swz_xor<4>(v); v += swz_xor<8>(v); v += swz_xor<16>(v);
;     return xor32_sum(v);
; __device__ __forceinline__ void norm_phase(const Ctx& F, float* X, const float* gw, const float* modl, int ish, int isc, bf16_t* XN, const float* part, int nsplit) {
;     ...
;     for (int row0 = 4 * F.gw; row0 < SEQ; row0 += 4 * F.ngw) {
;         const float* mv = modl;
;         f32x4 v[4][4];
; #pragma unroll
;         for (int r = 0; r < 4; ++r) { const f32x4* xr = (const f32x4*)(X + (size_t)(row0 + r) * D) + F.lane;
; #pragma unroll
;             for (int j = 0; j < 4; ++j) v[r][j] = xr[64 * j]; }
;         float rs[4];
; #pragma unroll
;         for (int r = 0; r < 4; ++r) { float ss = 0.f;
; #pragma unroll
;             for (int j = 0; j < 4; ++j) ss += (v[r][j].x * v[r][j].x + v[r][j].y * v[r][j].y) + (v[r][j].z * v[r][j].z + v[r][j].w * v[r][j].w);
;             rs[r] = __builtin_amdgcn_rsqf(wave_sum(ss) * (1.f / D) + EPSN); }
.LBB0_721:
	v_lshl_add_u64 v[70:71], s[14:15], 0, v[62:63]
	v_add_co_u32_e64 v66, s[4:5], s74, v70
	v_lshl_add_u64 v[14:15], s[14:15], 0, v[64:65]
	s_nop 0
	v_addc_co_u32_e64 v67, s[4:5], 0, v71, s[4:5]
	v_add_co_u32_e64 v68, s[4:5], s56, v70
	v_add_co_u32_e32 v2, vcc, 0xcb48000, v14
	s_nop 0
	v_addc_co_u32_e64 v69, s[4:5], 0, v71, s[4:5]
	s_mov_b64 s[4:5], vcc
	v_add_co_u32_e32 v6, vcc, 0xcb49000, v14
	v_addc_co_u32_e64 v3, s[4:5], 0, v15, s[4:5]
	s_mov_b64 s[4:5], vcc
	global_load_dwordx4 v[72:75], v[50:51], off
	global_load_dwordx4 v[34:37], v[52:53], off
	global_load_dwordx4 v[76:79], v[54:55], off
	v_add_co_u32_e32 v10, vcc, 0xcb4a000, v14
	v_addc_co_u32_e64 v7, s[4:5], 0, v15, s[4:5]
	global_load_dwordx4 v[80:83], v[2:3], off offset:1024
	global_load_dwordx4 v[38:41], v[2:3], off offset:2048
	global_load_dwordx4 v[18:21], v[2:3], off offset:3072
	s_mov_b64 s[4:5], vcc
	global_load_dwordx4 v[2:5], v[6:7], off
	global_load_dwordx4 v[84:87], v[6:7], off offset:1024
	global_load_dwordx4 v[42:45], v[6:7], off offset:2048
	global_load_dwordx4 v[22:25], v[6:7], off offset:3072
	v_add_co_u32_e32 v16, vcc, 0xcb4b000, v14
	v_addc_co_u32_e64 v11, s[4:5], 0, v15, s[4:5]
	s_mov_b64 s[4:5], vcc
	global_load_dwordx4 v[6:9], v[10:11], off
	global_load_dwordx4 v[88:91], v[10:11], off offset:1024
	global_load_dwordx4 v[92:95], v[10:11], off offset:2048
	global_load_dwordx4 v[30:33], v[10:11], off offset:3072
	v_add_co_u32_e32 v14, vcc, 0xcb4c000, v14
	v_addc_co_u32_e64 v17, s[4:5], 0, v15, s[4:5]
	global_load_dwordx4 v[10:13], v[16:17], off
	global_load_dwordx4 v[96:99], v[16:17], off offset:1024
	global_load_dwordx4 v[46:49], v[16:17], off offset:2048
	global_load_dwordx4 v[26:29], v[16:17], off offset:3072
	v_addc_co_u32_e32 v15, vcc, 0, v15, vcc
	global_load_dwordx4 v[14:17], v[14:15], off
	s_add_i32 s6, s6, s88
	v_lshl_add_u64 v[62:63], v[62:63], 0, s[2:3]
	v_lshl_add_u64 v[64:65], v[64:65], 0, s[64:65]
	s_cmpk_gt_i32 s6, 0x3fff
	s_waitcnt vmcnt(0)
	v_pk_add_f32 v[78:79], v[78:79], 1.0 op_sel_hi:[1,0]
	v_pk_add_f32 v[76:77], v[76:77], 1.0 op_sel_hi:[1,0]
	v_pk_mul_f32 v[78:79], v[74:75], v[78:79]
	v_pk_mul_f32 v[100:101], v[72:73], v[76:77]
	v_mul_f32_e32 v0, v81, v81
	v_mul_f32_e32 v72, v83, v83
	v_mul_f32_e32 v73, v39, v39
	v_mul_f32_e32 v74, v41, v41
	v_mul_f32_e32 v75, v19, v19
	v_mul_f32_e32 v76, v21, v21
	v_fmac_f32_e32 v0, v80, v80
	v_fmac_f32_e32 v72, v82, v82
	v_fmac_f32_e32 v73, v38, v38
	v_fmac_f32_e32 v74, v40, v40
	v_fmac_f32_e32 v75, v18, v18
	v_fmac_f32_e32 v76, v20, v20
	v_mul_f32_e32 v77, v3, v3
	v_mul_f32_e32 v102, v5, v5
	v_mul_f32_e32 v103, v85, v85
	v_mul_f32_e32 v104, v87, v87
	v_mul_f32_e32 v105, v43, v43
	v_mul_f32_e32 v106, v45, v45
	v_mul_f32_e32 v107, v23, v23
	v_mul_f32_e32 v108, v25, v25
	v_add_f32_e32 v0, v0, v72
	v_add_f32_e32 v72, v73, v74
	v_add_f32_e32 v73, v75, v76
	v_fmac_f32_e32 v77, v2, v2
	v_fmac_f32_e32 v102, v4, v4
	v_fmac_f32_e32 v103, v84, v84
	v_fmac_f32_e32 v104, v86, v86
	v_fmac_f32_e32 v105, v42, v42
	v_fmac_f32_e32 v106, v44, v44
	v_fmac_f32_e32 v107, v22, v22
	v_fmac_f32_e32 v108, v24, v24
	v_mul_f32_e32 v74, v7, v7
	v_mul_f32_e32 v75, v9, v9
	v_mul_f32_e32 v76, v89, v89
	v_mul_f32_e32 v109, v91, v91
	v_mul_f32_e32 v110, v93, v93
	v_mul_f32_e32 v111, v95, v95
	v_mul_f32_e32 v112, v31, v31
	v_mul_f32_e32 v113, v33, v33
	v_add_f32_e32 v0, v0, v72
	v_add_f32_e32 v72, v77, v102
	v_add_f32_e32 v77, v103, v104
	v_add_f32_e32 v102, v105, v106
	v_add_f32_e32 v103, v107, v108
	v_fmac_f32_e32 v74, v6, v6
	v_fmac_f32_e32 v75, v8, v8
	v_fmac_f32_e32 v76, v88, v88
	v_fmac_f32_e32 v109, v90, v90
	v_fmac_f32_e32 v110, v92, v92
	v_fmac_f32_e32 v111, v94, v94
	v_mul_f32_e32 v106, v97, v97
	v_mul_f32_e32 v107, v99, v99
	v_mul_f32_e32 v108, v47, v47
	v_mul_f32_e32 v114, v49, v49
	v_fmac_f32_e32 v112, v30, v30
	v_fmac_f32_e32 v113, v32, v32
	v_mul_f32_e32 v104, v11, v11
	v_mul_f32_e32 v105, v13, v13
	v_mul_f32_e32 v115, v27, v27
	v_mul_f32_e32 v116, v29, v29
	v_add_f32_e32 v0, v0, v73
	v_add_f32_e32 v73, v77, v102
	v_add_f32_e32 v74, v74, v75
	v_add_f32_e32 v75, v76, v109
	v_add_f32_e32 v76, v110, v111
	v_fmac_f32_e32 v106, v96, v96
	v_fmac_f32_e32 v107, v98, v98
	v_fmac_f32_e32 v108, v46, v46
	v_fmac_f32_e32 v114, v48, v48
	v_add_f32_e32 v77, v112, v113
	v_fmac_f32_e32 v104, v10, v10
	v_fmac_f32_e32 v105, v12, v12
	v_fmac_f32_e32 v115, v26, v26
	v_fmac_f32_e32 v116, v28, v28
	v_mul_f32_e32 v102, v15, v15
	v_mul_f32_e32 v109, v17, v17
	v_add_f32_e32 v0, v0, v72
	v_add_f32_e32 v72, v73, v103
	v_add_f32_e32 v73, v75, v76
	v_add_f32_e32 v76, v106, v107
	v_add_f32_e32 v103, v108, v114
	v_add_f32_e32 v75, v104, v105
	v_add_f32_e32 v104, v115, v116
	v_fmac_f32_e32 v102, v14, v14
	v_fmac_f32_e32 v109, v16, v16
	s_nop 1
	v_mov_b32_dpp v105, v0 quad_perm:[1,0,3,2] row_mask:0xf bank_mask:0xf
	v_add_f32_e32 v72, v72, v74
	v_add_f32_e32 v73, v73, v77
	v_add_f32_e32 v74, v76, v103
	v_add_f32_e32 v76, v102, v109
	s_nop 1
	v_mov_b32_dpp v77, v72 quad_perm:[1,0,3,2] row_mask:0xf bank_mask:0xf
	v_add_f32_e32 v73, v73, v75
	v_add_f32_e32 v74, v74, v104
	s_nop 1
	v_mov_b32_dpp v75, v73 quad_perm:[1,0,3,2] row_mask:0xf bank_mask:0xf
	v_add_f32_e32 v74, v74, v76
	s_nop 1
	v_mov_b32_dpp v76, v74 quad_perm:[1,0,3,2] row_mask:0xf bank_mask:0xf
	s_waitcnt lgkmcnt(3)
	v_add_f32_e32 v0, v0, v105
	s_nop 1
	v_mov_b32_dpp v102, v0 quad_perm:[2,3,0,1] row_mask:0xf bank_mask:0xf
	s_waitcnt lgkmcnt(3)
	v_add_f32_e32 v72, v72, v77
	s_nop 1
	v_mov_b32_dpp v77, v72 quad_perm:[2,3,0,1] row_mask:0xf bank_mask:0xf
	s_waitcnt lgkmcnt(3)
	v_add_f32_e32 v73, v73, v75
	s_nop 1
	v_mov_b32_dpp v75, v73 quad_perm:[2,3,0,1] row_mask:0xf bank_mask:0xf
	s_waitcnt lgkmcnt(3)
; __device__ __forceinline__ unsigned pk2(float lo, float hi) { const f32x2_t v = {lo, hi}; const bf16x2_t b = __builtin_convertvector(v, bf16x2_t); return __builtin_bit_cast(unsigned, b); }
; template <int K> __device__ __forceinline__ float swz_xor(float v) { return __uint_as_float((unsigned)__builtin_amdgcn_ds_swizzle((int)__float_as_uint(v), (K << 10) | 0x1f)); }
; __device__ __forceinline__ float xor32_sum(float v) { const auto rr = __builtin_amdgcn_permlane32_swap(__float_as_uint(v), __float_as_uint(v), false, false); return __uint_as_float(rr[0]) + __uint_as_float(rr[1]); }
; __device__ __forceinline__ float wave_sum(float v) {
;     v += swz_xor<1>(v); v += swz_xor<2>(v); v += swz_xor<4>(v); v += swz_xor<8>(v); v += swz_xor<16>(v);
;     return xor32_sum(v);
; __device__ __forceinline__ void norm_phase(const Ctx& F, float* X, const float* gw, const float* modl, int ish, int isc, bf16_t* XN, const float* part, int nsplit) {
;     ...
;         for (int r = 0; r < 4; ++r) { float ss = 0.f;
; #pragma unroll
;             for (int j = 0; j < 4; ++j) ss += (v[r][j].x * v[r][j].x + v[r][j].y * v[r][j].y) + (v[r][j].z * v[r][j].z + v[r][j].w * v[r][j].w);
;             rs[r] = __builtin_amdgcn_rsqf(wave_sum(ss) * (1.f / D) + EPSN); }
; #pragma unroll
;         for (int j = 0; j < 4; ++j) {
;             const int col = 4 * F.lane + 256 * j;
;             const f32x4 g4 = *(const f32x4*)(gw + col), sh = *(const f32x4*)(mv + ish * 1024 + col), sc = *(const f32x4*)(mv + isc * 1024 + col);
;             const f32x4 gs = g4 * (sc + 1.0f);
; #pragma unroll
;             for (int r = 0; r < 4; ++r) {
;                 const f32x4 o = (v[r][j] * rs[r]) * gs + sh;
;                 u32x2 w; w.x = pk2(o.x, o.y); w.y = pk2(o.z, o.w);
;                 *(u32x2*)(XN + (size_t)(row0 + r) * D + col) = w;
	v_add_f32_e32 v74, v74, v76
	s_nop 1
	v_mov_b32_dpp v76, v74 quad_perm:[2,3,0,1] row_mask:0xf bank_mask:0xf
	s_waitcnt lgkmcnt(3)
	v_add_f32_e32 v0, v0, v102
	s_nop 1
	v_mov_b32_dpp v102, v0 row_half_mirror row_mask:0xf bank_mask:0xf
	s_waitcnt lgkmcnt(3)
	v_add_f32_e32 v72, v72, v77
	s_nop 1
	v_mov_b32_dpp v77, v72 row_half_mirror row_mask:0xf bank_mask:0xf
	s_waitcnt lgkmcnt(3)
	v_add_f32_e32 v73, v73, v75
	s_nop 1
	v_mov_b32_dpp v75, v73 row_half_mirror row_mask:0xf bank_mask:0xf
	s_waitcnt lgkmcnt(3)
	v_add_f32_e32 v74, v74, v76
	s_nop 1
	v_mov_b32_dpp v76, v74 row_half_mirror row_mask:0xf bank_mask:0xf
	s_waitcnt lgkmcnt(3)
	v_add_f32_e32 v0, v0, v102
	s_nop 1
	v_mov_b32_dpp v102, v0 row_ror:8 row_mask:0xf bank_mask:0xf
	s_waitcnt lgkmcnt(3)
	v_add_f32_e32 v72, v72, v77
	s_nop 1
	v_mov_b32_dpp v77, v72 row_ror:8 row_mask:0xf bank_mask:0xf
	s_waitcnt lgkmcnt(3)
	v_add_f32_e32 v73, v73, v75
	s_nop 1
	v_mov_b32_dpp v75, v73 row_ror:8 row_mask:0xf bank_mask:0xf
	s_waitcnt lgkmcnt(3)
	v_add_f32_e32 v74, v74, v76
	s_nop 1
	v_mov_b32_dpp v76, v74 row_ror:8 row_mask:0xf bank_mask:0xf
	s_waitcnt lgkmcnt(3)
	v_add_f32_e32 v0, v0, v102
	v_mov_b32_e32 v102, v0
	s_nop 1
	v_permlane16_swap_b32_e32 v0, v102
	s_waitcnt lgkmcnt(3)
	v_add_f32_e32 v72, v72, v77
	v_mov_b32_e32 v77, v72
	s_nop 1
	v_permlane16_swap_b32_e32 v72, v77
	s_waitcnt lgkmcnt(3)
	v_add_f32_e32 v73, v73, v75
	v_mov_b32_e32 v75, v73
	s_nop 1
	v_permlane16_swap_b32_e32 v73, v75
	s_waitcnt lgkmcnt(3)
	v_add_f32_e32 v74, v74, v76
	v_mov_b32_e32 v76, v74
	s_nop 1
	v_permlane16_swap_b32_e32 v74, v76
	s_waitcnt lgkmcnt(3)
	v_add_f32_e32 v0, v0, v102
	v_mov_b32_e32 v102, v0
	s_waitcnt lgkmcnt(2)
	v_add_f32_e32 v72, v72, v77
	v_permlane32_swap_b32_e32 v0, v102
	v_mov_b32_e32 v77, v72
	s_waitcnt lgkmcnt(1)
	v_add_f32_e32 v73, v73, v75
	v_add_f32_e32 v0, v0, v102
	v_permlane32_swap_b32_e32 v72, v77
	v_mov_b32_e32 v75, v73
	s_waitcnt lgkmcnt(0)
	v_add_f32_e32 v74, v74, v76
	v_fmamk_f32 v0, v0, 0x3a800000, v193
	v_add_f32_e32 v72, v72, v77
	v_permlane32_swap_b32_e32 v73, v75
	v_mov_b32_e32 v76, v74
	v_rsq_f32_e32 v0, v0
	v_fmamk_f32 v72, v72, 0x3a800000, v193
	v_add_f32_e32 v73, v73, v75
	v_permlane32_swap_b32_e32 v74, v76
	v_rsq_f32_e32 v72, v72
	v_fmamk_f32 v73, v73, 0x3a800000, v193
	v_add_f32_e32 v75, v74, v76
	v_rsq_f32_e32 v74, v73
	v_fmamk_f32 v73, v75, 0x3a800000, v193
	v_rsq_f32_e32 v76, v73
	v_pk_mul_f32 v[80:81], v[80:81], v[0:1] op_sel_hi:[1,0]
	v_pk_mul_f32 v[82:83], v[82:83], v[0:1] op_sel_hi:[1,0]
	v_pk_fma_f32 v[80:81], v[80:81], v[100:101], v[34:35]
	v_pk_fma_f32 v[82:83], v[82:83], v[78:79], v[36:37]
	v_pk_mul_f32 v[84:85], v[84:85], v[72:73] op_sel_hi:[1,0]
	v_pk_mul_f32 v[86:87], v[86:87], v[72:73] op_sel_hi:[1,0]
	v_cvt_pk_bf16_f32 v80, v80, v81
	v_cvt_pk_bf16_f32 v81, v82, v83
	v_pk_fma_f32 v[82:83], v[86:87], v[78:79], v[36:37]
	v_pk_fma_f32 v[84:85], v[84:85], v[100:101], v[34:35]
	v_pk_mul_f32 v[86:87], v[88:89], v[74:75] op_sel_hi:[1,0]
	v_pk_mul_f32 v[88:89], v[90:91], v[74:75] op_sel_hi:[1,0]
	global_store_dwordx2 v[66:67], v[80:81], off offset:1024
	v_cvt_pk_bf16_f32 v80, v84, v85
	v_cvt_pk_bf16_f32 v81, v82, v83
	v_pk_fma_f32 v[82:83], v[88:89], v[78:79], v[36:37]
	v_pk_fma_f32 v[84:85], v[86:87], v[100:101], v[34:35]
	v_pk_mul_f32 v[86:87], v[96:97], v[76:77] op_sel_hi:[1,0]
	v_pk_mul_f32 v[88:89], v[98:99], v[76:77] op_sel_hi:[1,0]
	v_pk_fma_f32 v[34:35], v[100:101], v[86:87], v[34:35]
	v_pk_fma_f32 v[36:37], v[78:79], v[88:89], v[36:37]
	global_store_dwordx2 v[66:67], v[80:81], off offset:3072
	v_cvt_pk_bf16_f32 v80, v84, v85
	v_cvt_pk_bf16_f32 v81, v82, v83
	v_cvt_pk_bf16_f32 v34, v34, v35
	v_cvt_pk_bf16_f32 v35, v36, v37
	global_store_dwordx2 v[68:69], v[80:81], off offset:1024
	global_store_dwordx2 v[68:69], v[34:35], off offset:3072
	global_load_dwordx4 v[34:37], v[56:57], off
	s_nop 0
	global_load_dwordx4 v[78:81], v[50:51], off offset:1024
	global_load_dwordx4 v[82:85], v[52:53], off offset:1024
	v_pk_mul_f32 v[38:39], v[38:39], v[0:1] op_sel_hi:[1,0]
	v_pk_mul_f32 v[40:41], v[40:41], v[0:1] op_sel_hi:[1,0]
	v_pk_mul_f32 v[42:43], v[42:43], v[72:73] op_sel_hi:[1,0]
	v_pk_mul_f32 v[44:45], v[44:45], v[72:73] op_sel_hi:[1,0]
	v_pk_mul_f32 v[86:87], v[92:93], v[74:75] op_sel_hi:[1,0]
	v_pk_mul_f32 v[88:89], v[94:95], v[74:75] op_sel_hi:[1,0]
	v_pk_mul_f32 v[46:47], v[46:47], v[76:77] op_sel_hi:[1,0]
	v_pk_mul_f32 v[48:49], v[48:49], v[76:77] op_sel_hi:[1,0]
	v_pk_mul_f32 v[18:19], v[18:19], v[0:1] op_sel_hi:[1,0]
	v_pk_mul_f32 v[20:21], v[20:21], v[0:1] op_sel_hi:[1,0]
	v_pk_mul_f32 v[22:23], v[22:23], v[72:73] op_sel_hi:[1,0]
	v_pk_mul_f32 v[24:25], v[24:25], v[72:73] op_sel_hi:[1,0]
	v_pk_mul_f32 v[30:31], v[30:31], v[74:75] op_sel_hi:[1,0]
	v_pk_mul_f32 v[32:33], v[32:33], v[74:75] op_sel_hi:[1,0]
	v_pk_mul_f32 v[26:27], v[26:27], v[76:77] op_sel_hi:[1,0]
	v_pk_mul_f32 v[28:29], v[28:29], v[76:77] op_sel_hi:[1,0]
	v_pk_mul_f32 v[2:3], v[2:3], v[0:1] op_sel_hi:[1,0]
	v_pk_mul_f32 v[4:5], v[4:5], v[0:1] op_sel_hi:[1,0]
	v_pk_mul_f32 v[6:7], v[6:7], v[72:73] op_sel_hi:[1,0]
	v_pk_mul_f32 v[8:9], v[8:9], v[72:73] op_sel_hi:[1,0]
	v_pk_mul_f32 v[10:11], v[10:11], v[74:75] op_sel_hi:[1,0]
	v_pk_mul_f32 v[12:13], v[12:13], v[74:75] op_sel_hi:[1,0]
	v_pk_mul_f32 v[14:15], v[14:15], v[76:77] op_sel_hi:[1,0]
	v_pk_mul_f32 v[16:17], v[16:17], v[76:77] op_sel_hi:[1,0]
	s_waitcnt vmcnt(2)
; __device__ __forceinline__ unsigned pk2(float lo, float hi) { const f32x2_t v = {lo, hi}; const bf16x2_t b = __builtin_convertvector(v, bf16x2_t); return __builtin_bit_cast(unsigned, b); }
; __device__ __forceinline__ void norm_phase(const Ctx& F, float* X, const float* gw, const float* modl, int ish, int isc, bf16_t* XN, const float* part, int nsplit) {
;     ...
;         for (int j = 0; j < 4; ++j) {
;             const int col = 4 * F.lane + 256 * j;
;             const f32x4 g4 = *(const f32x4*)(gw + col), sh = *(const f32x4*)(mv + ish * 1024 + col), sc = *(const f32x4*)(mv + isc * 1024 + col);
;             const f32x4 gs = g4 * (sc + 1.0f);
; #pragma unroll
;             for (int r = 0; r < 4; ++r) {
;                 const f32x4 o = (v[r][j] * rs[r]) * gs + sh;
;                 u32x2 w; w.x = pk2(o.x, o.y); w.y = pk2(o.z, o.w);
;                 *(u32x2*)(XN + (size_t)(row0 + r) * D + col) = w;
;             }
;         }
	v_pk_add_f32 v[36:37], v[36:37], 1.0 op_sel_hi:[1,0]
	v_pk_add_f32 v[34:35], v[34:35], 1.0 op_sel_hi:[1,0]
	s_waitcnt vmcnt(1)
	v_pk_mul_f32 v[36:37], v[80:81], v[36:37]
	v_pk_mul_f32 v[34:35], v[78:79], v[34:35]
	s_waitcnt vmcnt(0)
	v_pk_fma_f32 v[40:41], v[40:41], v[36:37], v[84:85]
	v_pk_fma_f32 v[38:39], v[38:39], v[34:35], v[82:83]
	v_pk_fma_f32 v[44:45], v[44:45], v[36:37], v[84:85]
	v_pk_fma_f32 v[42:43], v[42:43], v[34:35], v[82:83]
	v_pk_fma_f32 v[78:79], v[88:89], v[36:37], v[84:85]
	v_pk_fma_f32 v[80:81], v[86:87], v[34:35], v[82:83]
	v_pk_fma_f32 v[36:37], v[48:49], v[36:37], v[84:85]
	v_pk_fma_f32 v[34:35], v[46:47], v[34:35], v[82:83]
	v_cvt_pk_bf16_f32 v38, v38, v39
	v_cvt_pk_bf16_f32 v39, v40, v41
	v_cvt_pk_bf16_f32 v40, v42, v43
	v_cvt_pk_bf16_f32 v41, v44, v45
	v_cvt_pk_bf16_f32 v42, v80, v81
	v_cvt_pk_bf16_f32 v43, v78, v79
	v_cvt_pk_bf16_f32 v34, v34, v35
	v_cvt_pk_bf16_f32 v35, v36, v37
	global_store_dwordx2 v[66:67], v[38:39], off offset:1536
	global_store_dwordx2 v[66:67], v[40:41], off offset:3584
	global_store_dwordx2 v[68:69], v[42:43], off offset:1536
	global_store_dwordx2 v[68:69], v[34:35], off offset:3584
	global_load_dwordx4 v[34:37], v[58:59], off
	s_nop 0
	global_load_dwordx4 v[38:41], v[50:51], off offset:2048
	global_load_dwordx4 v[42:45], v[52:53], off offset:2048
	v_add_co_u32_e32 v46, vcc, s29, v70
	s_waitcnt vmcnt(2)
	v_pk_add_f32 v[36:37], v[36:37], 1.0 op_sel_hi:[1,0]
	v_pk_add_f32 v[34:35], v[34:35], 1.0 op_sel_hi:[1,0]
	s_waitcnt vmcnt(1)
	v_pk_mul_f32 v[36:37], v[40:41], v[36:37]
	v_pk_mul_f32 v[34:35], v[38:39], v[34:35]
	s_waitcnt vmcnt(0)
	v_pk_fma_f32 v[20:21], v[20:21], v[36:37], v[44:45]
	v_pk_fma_f32 v[18:19], v[18:19], v[34:35], v[42:43]
	v_pk_fma_f32 v[24:25], v[24:25], v[36:37], v[44:45]
	v_pk_fma_f32 v[22:23], v[22:23], v[34:35], v[42:43]
	v_pk_fma_f32 v[32:33], v[32:33], v[36:37], v[44:45]
	v_pk_fma_f32 v[30:31], v[30:31], v[34:35], v[42:43]
	v_pk_fma_f32 v[28:29], v[28:29], v[36:37], v[44:45]
	v_pk_fma_f32 v[26:27], v[26:27], v[34:35], v[42:43]
	v_cvt_pk_bf16_f32 v18, v18, v19
	v_cvt_pk_bf16_f32 v19, v20, v21
	v_addc_co_u32_e32 v47, vcc, 0, v71, vcc
	v_cvt_pk_bf16_f32 v20, v22, v23
	v_cvt_pk_bf16_f32 v21, v24, v25
	v_cvt_pk_bf16_f32 v22, v30, v31
	v_cvt_pk_bf16_f32 v23, v32, v33
	v_cvt_pk_bf16_f32 v24, v26, v27
	v_cvt_pk_bf16_f32 v25, v28, v29
	global_store_dwordx2 v[66:67], v[18:19], off offset:2048
	global_store_dwordx2 v[46:47], v[20:21], off offset:-4096
	global_store_dwordx2 v[68:69], v[22:23], off offset:2048
	global_store_dwordx2 v[46:47], v[24:25], off
	global_load_dwordx4 v[18:21], v[60:61], off
	s_nop 0
	global_load_dwordx4 v[22:25], v[50:51], off offset:3072
	global_load_dwordx4 v[26:29], v[52:53], off offset:3072
	s_waitcnt vmcnt(2)
	v_pk_add_f32 v[20:21], v[20:21], 1.0 op_sel_hi:[1,0]
	v_pk_add_f32 v[18:19], v[18:19], 1.0 op_sel_hi:[1,0]
	s_waitcnt vmcnt(1)
	v_pk_mul_f32 v[20:21], v[24:25], v[20:21]
	v_pk_mul_f32 v[18:19], v[22:23], v[18:19]
	s_waitcnt vmcnt(0)
	v_pk_fma_f32 v[4:5], v[4:5], v[20:21], v[28:29]
	v_pk_fma_f32 v[2:3], v[2:3], v[18:19], v[26:27]
	v_pk_fma_f32 v[8:9], v[8:9], v[20:21], v[28:29]
	v_pk_fma_f32 v[6:7], v[6:7], v[18:19], v[26:27]
	v_pk_fma_f32 v[12:13], v[12:13], v[20:21], v[28:29]
	v_pk_fma_f32 v[10:11], v[10:11], v[18:19], v[26:27]
	v_pk_fma_f32 v[16:17], v[16:17], v[20:21], v[28:29]
	v_pk_fma_f32 v[14:15], v[14:15], v[18:19], v[26:27]
	v_cvt_pk_bf16_f32 v2, v2, v3
	v_cvt_pk_bf16_f32 v3, v4, v5
	v_cvt_pk_bf16_f32 v4, v6, v7
	v_cvt_pk_bf16_f32 v5, v8, v9
	v_cvt_pk_bf16_f32 v6, v10, v11
	v_cvt_pk_bf16_f32 v7, v12, v13
	v_cvt_pk_bf16_f32 v8, v14, v15
	v_cvt_pk_bf16_f32 v9, v16, v17
	global_store_dwordx2 v[66:67], v[2:3], off offset:2560
	global_store_dwordx2 v[68:69], v[4:5], off offset:512
	global_store_dwordx2 v[68:69], v[6:7], off offset:2560
	global_store_dwordx2 v[46:47], v[8:9], off offset:512
	s_cbranch_scc0 .LBB0_721
